# out-proj epilogue fused with the final rmsnorm: row sums exchanged between the 4 column-tile owners of a panel (atomics + panel counter), y*rstd*g stored straight from the accumulators; last pass and
# speedup vs baseline: 1.0420x; 1.0248x over previous
; #define PG8_LAS __attribute__((address_space(3)))
; #define PG8_STAGE(bufoff, gbase, voff) do { _Pragma("unroll") for (int _i = 0; _i < 2; ++_i) \
;         __builtin_amdgcn_global_load_lds((const unsigned*)((const char*)(gbase) + (voff)[_i]), (PG8_LAS unsigned*)(lds + (bufoff) + ldsw + _i * 8192), 16, 0, 0); } while (0)
; #define PG8_WAIT_V(n) asm volatile("s_waitcnt vmcnt(" #n ")" ::: "memory")
; #define PG8_BAR __builtin_amdgcn_s_barrier()
; template <class Epi, class Sched, bool ALIGN_EPI = false, bool SP2 = false>
; __device__ __forceinline__ void gemm_phase(PG8_LAS unsigned char* lds, const Gemm g, const Sched& S, const Epi& E) {
;     ...
;     const char* cA = (const char*)g.A + (size_t)cur.pm * tstep; const char* cB = (const char*)g.Bt + (size_t)cur.pn * tstep;
;     S.a_ready(cur);
;     if constexpr (SP2) {
;         PG8_STAGE(PG8_SB(0, 0), cB, voffB); PG8_STAGE(PG8_SB(0, 1), cB + hstep, voffB); PG8_STAGE(PG8_SA(0, 0), cA, voffA); PG8_STAGE(PG8_SA(0, 1), cA + hstep, voffA);
;         if (wr == 1) PG8_BAR;
;         PG8_WAIT_V(2); PG8_BAR;
;         PG8_STAGE(PG8_SB(1, 0), cB + kstep, voffB); PG8_STAGE(PG8_SA(1, 0), cA + kstep, voffA); PG8_STAGE(PG8_SB(1, 1), cB + hstep + kstep, voffB);
;         PG8_WAIT_V(6); PG8_BAR;
; __global__ void __launch_bounds__(512, 2) hymba_mega(Params p) {
;     ...
;         pg8::StaticOrder S; S.init(NR, DM, (int)gridDim.x, (int)blockIdx.x);
;         const pg8::Gemm g{p.mix, p.wtout, NR, DM, DM};
;         const EpiOut8 E{&p};
;         pg8::gemm_phase<EpiOut8, pg8::StaticOrder, true, true>((PG8_LAS unsigned char*)smem, g, S, E);
.LBB0_604:
	s_and_b32 s94, s2, 7
	s_lshl_b32 s94, s94, 3
	s_bfe_u32 s0, s2, 0x30003
	s_add_i32 s94, s94, s0
	s_lshr_b32 s42, s2, 6
	s_andn2_b64 vcc, exec, s[36:37]
	s_cbranch_vccnz .LBB0_704
	v_writelane_b32 v246, s90, 3
	s_lshr_b32 s6, s8, 6
	s_ashr_i32 s95, s94, 31
	v_writelane_b32 v246, s91, 4
	v_writelane_b32 v246, s88, 5
	s_ashr_i32 s43, s42, 31
	s_lshr_b32 s7, s8, 8
	v_writelane_b32 v246, s89, 6
	v_writelane_b32 v246, s86, 7
	s_lshl_b32 s3, s6, 10
	s_lshl_b64 s[4:5], s[94:95], 19
	v_writelane_b32 v246, s87, 8
	v_writelane_b32 v246, s24, 9
	s_lshl_b64 s[0:1], s[42:43], 19
	s_add_u32 s98, s64, s0
	v_writelane_b32 v246, s25, 10
	v_writelane_b32 v246, s22, 11
	s_addc_u32 s99, s65, s1
	s_add_i32 s0, s3, 0x100
	v_writelane_b32 v246, s23, 12
	v_writelane_b32 v246, s20, 13
	s_add_i32 m0, s0, 0x10000
	v_mov_b32_e32 v133, 0
	v_writelane_b32 v246, s21, 14
	v_writelane_b32 v246, s18, 15
	global_load_lds_dwordx4 v142, s[98:99]
	s_nop 0
	v_writelane_b32 v246, s19, 16
	v_writelane_b32 v246, s16, 17
	s_add_i32 m0, s0, 0x12000
	v_mov_b32_e32 v143, v133
	v_writelane_b32 v246, s17, 18
	v_writelane_b32 v246, s14, 19
	global_load_lds_dwordx4 v146, s[98:99]
	s_nop 0
	v_writelane_b32 v246, s15, 20
	v_writelane_b32 v246, s12, 21
	v_mov_b32_e32 v147, v133
	v_mov_b32_e32 v141, v133
	v_writelane_b32 v246, s13, 22
	v_writelane_b32 v246, s10, 23
	v_mov_b32_e32 v145, v133
	v_lshl_add_u64 v[6:7], s[98:99], 0, v[142:143]
	v_writelane_b32 v246, s11, 24
	s_add_u32 s10, s98, 0x40000
	s_addc_u32 s11, s99, 0
	s_add_i32 m0, s0, 0x14000
	v_lshl_add_u64 v[2:3], s[98:99], 0, v[146:147]
	global_load_lds_dwordx4 v142, s[10:11]
	s_add_i32 m0, s0, 0x16000
	s_add_u32 s96, s70, s4
	s_addc_u32 s97, s71, s5
	s_add_i32 s1, s0, 0x2000
	global_load_lds_dwordx4 v146, s[10:11]
	s_mov_b32 m0, s0
	s_add_u32 s10, s96, 0x40000
	global_load_lds_dwordx4 v140, s[96:97]
	s_mov_b32 m0, s1
	s_addc_u32 s11, s97, 0
	s_add_i32 s4, s0, 0x4000
	global_load_lds_dwordx4 v144, s[96:97]
	s_mov_b32 m0, s4
	s_add_i32 s5, s0, 0x6000
	global_load_lds_dwordx4 v140, s[10:11]
	s_mov_b32 m0, s5
	s_cmp_eq_u32 s7, 1
	global_load_lds_dwordx4 v144, s[10:11]
	v_lshl_add_u64 v[0:1], s[96:97], 0, v[140:141]
	s_cselect_b64 s[72:73], -1, 0
	s_cmp_lg_u32 s7, 1
	v_lshl_add_u64 v[4:5], s[96:97], 0, v[144:145]
	s_cbranch_scc1 .LBB0_607
	s_barrier

;     __host__ __device__ bool next(int i, Unit& u) const {
;         const long L = (long)i * G + c; if (L >= nwg) return false;
;         int wgid = (int)L; { const int q = nwg / NXCD, r = nwg % NXCD, xcd = wgid % NXCD, off = wgid / NXCD; wgid = (xcd < r ? xcd * (q + 1) : r * (q + 1) + (xcd - r) * q) + off; }
;         const int nig = WGM * nN, gid = wgid / nig, fm = gid * WGM, gsz = (nM - fm) < WGM ? (nM - fm) : WGM;
;         u.pm = fm + ((wgid % nig) % gsz); u.pn = (wgid % nig) / gsz; return true;
; template <class Epi, class Sched, bool ALIGN_EPI = false, bool SP2 = false>
; __device__ __forceinline__ void gemm_phase(PG8_LAS unsigned char* lds, const Gemm g, const Sched& S, const Epi& E) {
;     ...
;     f32x4 acc[2][2][4][2];
; #pragma unroll
;     for (int a = 0; a < 2; ++a)
; #pragma unroll
;         for (int b = 0; b < 2; ++b)
; #pragma unroll
;             for (int m = 0; m < 4; ++m)
; #pragma unroll
;                 for (int n = 0; n < 2; ++n) acc[a][b][m][n] = (f32x4){0.f, 0.f, 0.f, 0.f};
.LBB0_616:
	s_and_b32 s19, s2, 7
	s_mul_i32 s19, s19, 6
	s_lshr_b32 s86, s2, 3
	s_add_i32 s19, s19, s86
	s_bfe_u32 s86, s19, 0x20002
	s_lshr_b32 s88, s19, 4
	s_add_i32 s88, s88, 64
	s_ashr_i32 s89, s88, 31
	s_lshl_b64 s[20:21], s[88:89], 19
	s_add_u32 s90, s70, s20
	s_addc_u32 s91, s71, s21
	s_and_b64 s[20:21], s[38:39], exec
	s_cselect_b32 s19, s91, s97
	s_cselect_b32 s43, s90, s96
	s_ashr_i32 s87, s86, 31
	s_lshl_b64 s[20:21], s[86:87], 19
	s_add_u32 s92, s64, s20
	s_addc_u32 s93, s65, s21
	s_and_b64 s[20:21], s[38:39], exec
	s_cselect_b32 s87, s93, s99
	s_cselect_b32 s89, s92, s98
	s_add_u32 s96, s96, 0x40080
	s_addc_u32 s97, s97, 0
	s_add_u32 s95, s98, 0x100
	v_mov_b32_e32 v0, 0
	s_addc_u32 s20, s99, 0
	s_mov_b32 s21, -2
	s_waitcnt lgkmcnt(0)
	v_mov_b32_e32 v1, v0
	v_mov_b32_e32 v2, v0
	v_mov_b32_e32 v3, v0
	v_mov_b32_e32 v4, v0
	v_mov_b32_e32 v5, v0
	v_mov_b32_e32 v6, v0
	v_mov_b32_e32 v7, v0
	v_mov_b32_e32 v16, v0
	v_mov_b32_e32 v17, v0
	v_mov_b32_e32 v18, v0
	v_mov_b32_e32 v19, v0
	v_mov_b32_e32 v20, v0
	v_mov_b32_e32 v21, v0
	v_mov_b32_e32 v22, v0
	v_mov_b32_e32 v23, v0
	v_mov_b32_e32 v32, v0
	v_mov_b32_e32 v33, v0
	v_mov_b32_e32 v34, v0
	v_mov_b32_e32 v35, v0
	v_mov_b32_e32 v36, v0
	v_mov_b32_e32 v37, v0
	v_mov_b32_e32 v38, v0
	v_mov_b32_e32 v39, v0
	v_mov_b32_e32 v48, v0
	v_mov_b32_e32 v49, v0
	v_mov_b32_e32 v50, v0
	v_mov_b32_e32 v51, v0
	v_mov_b32_e32 v52, v0
	v_mov_b32_e32 v53, v0
	v_mov_b32_e32 v54, v0
	v_mov_b32_e32 v55, v0
	v_mov_b32_e32 v8, v0
	v_mov_b32_e32 v9, v0
	v_mov_b32_e32 v10, v0
	v_mov_b32_e32 v11, v0
	v_mov_b32_e32 v12, v0
	v_mov_b32_e32 v13, v0
	v_mov_b32_e32 v14, v0
	v_mov_b32_e32 v15, v0
	v_mov_b32_e32 v24, v0
	v_mov_b32_e32 v25, v0
	v_mov_b32_e32 v26, v0
	v_mov_b32_e32 v27, v0
	v_mov_b32_e32 v28, v0
	v_mov_b32_e32 v29, v0
	v_mov_b32_e32 v30, v0
	v_mov_b32_e32 v31, v0
	v_mov_b32_e32 v40, v0
	v_mov_b32_e32 v41, v0
	v_mov_b32_e32 v42, v0
	v_mov_b32_e32 v43, v0
	v_mov_b32_e32 v44, v0
	v_mov_b32_e32 v45, v0
	v_mov_b32_e32 v46, v0
	v_mov_b32_e32 v47, v0
	v_mov_b32_e32 v56, v0
	v_mov_b32_e32 v57, v0
	v_mov_b32_e32 v58, v0
	v_mov_b32_e32 v59, v0
	v_mov_b32_e32 v60, v0
	v_mov_b32_e32 v61, v0
	v_mov_b32_e32 v62, v0
	v_mov_b32_e32 v63, v0
	s_waitcnt vmcnt(0)
	v_mov_b32_e32 v64, v0
	v_mov_b32_e32 v65, v0
	v_mov_b32_e32 v66, v0
	v_mov_b32_e32 v67, v0
	v_mov_b32_e32 v68, v0
	v_mov_b32_e32 v69, v0
	v_mov_b32_e32 v70, v0
	v_mov_b32_e32 v71, v0
	v_mov_b32_e32 v80, v0
	v_mov_b32_e32 v81, v0
	v_mov_b32_e32 v82, v0
	v_mov_b32_e32 v83, v0
	v_mov_b32_e32 v84, v0
	v_mov_b32_e32 v85, v0
	v_mov_b32_e32 v86, v0
	v_mov_b32_e32 v87, v0
	v_mov_b32_e32 v96, v0
	v_mov_b32_e32 v97, v0
	v_mov_b32_e32 v98, v0
	v_mov_b32_e32 v99, v0
	v_mov_b32_e32 v100, v0
	v_mov_b32_e32 v101, v0
	v_mov_b32_e32 v102, v0
	v_mov_b32_e32 v103, v0
	v_mov_b32_e32 v112, v0
	v_mov_b32_e32 v113, v0
	v_mov_b32_e32 v114, v0
	v_mov_b32_e32 v115, v0
	v_mov_b32_e32 v116, v0
	v_mov_b32_e32 v117, v0
	v_mov_b32_e32 v118, v0
	v_mov_b32_e32 v119, v0
	v_mov_b32_e32 v72, v0
	v_mov_b32_e32 v73, v0
	v_mov_b32_e32 v74, v0
	v_mov_b32_e32 v75, v0
	v_mov_b32_e32 v76, v0
	v_mov_b32_e32 v77, v0
	v_mov_b32_e32 v78, v0
	v_mov_b32_e32 v79, v0
	v_mov_b32_e32 v88, v0
	v_mov_b32_e32 v89, v0
	v_mov_b32_e32 v90, v0
	v_mov_b32_e32 v91, v0
	v_mov_b32_e32 v92, v0
	v_mov_b32_e32 v93, v0
	v_mov_b32_e32 v94, v0
	v_mov_b32_e32 v95, v0
	v_mov_b32_e32 v104, v0
	v_mov_b32_e32 v105, v0
	v_mov_b32_e32 v106, v0
	v_mov_b32_e32 v107, v0
	v_mov_b32_e32 v108, v0
	v_mov_b32_e32 v109, v0
	v_mov_b32_e32 v110, v0
	v_mov_b32_e32 v111, v0
	v_mov_b32_e32 v120, v0
	v_mov_b32_e32 v121, v0
	v_mov_b32_e32 v122, v0
	v_mov_b32_e32 v123, v0
	v_mov_b32_e32 v124, v0
	v_mov_b32_e32 v125, v0
	v_mov_b32_e32 v126, v0
	v_mov_b32_e32 v127, v0

;     DI void operator()(const f32x4 (&acc)[2][2][4][2], const pg8::Unit& u, int wr, int wc, int fr, int fq) const {
;     ...
;                 const int R = u.pm * 256 + ai * 128 + wr * 64 + m * 16 + fr;
;                 const float* xs = nullptr; float* yd = nullptr;
;                 if (R < ROWS_P) { const int b = R / LPAD, t = R - b * LPAD; if (t >= NMETA && t < LP) { const size_t idx = ((size_t)b * SEQ + t - NMETA) * DM; xs = p.x_prompt + idx; yd = p.out + O_YP + idx; } }
;                 else { const size_t idx = (size_t)(R - ROWS_P) * DM; xs = p.x_sample + idx; yd = p.out + O_YS + idx; }
;                 float ss = 0.f;
;                 if (xs) {
; #pragma unroll
;                     for (int bj = 0; bj < 2; ++bj) {
;                         const int n = colt + bj * 128 + wc * 32 + 8 * fq;
;                         const f32x4 x0 = *(const f32x4*)(xs + n), x1 = *(const f32x4*)(xs + n + 4);
.LBB0_620:
	s_cmp_eq_u32 s100, 15
	s_cbranch_scc0 .Lp3q_epi
	v_lshl_add_u32 v150, s94, 8, v158
	v_lshl_or_b32 v155, s42, 8, v159
	v_and_b32_e32 v151, 15, v158
	v_lshlrev_b32_e32 v155, 2, v155
	v_lshl_or_b32 v151, v151, 12, v155
	v_lshlrev_b32_e32 v152, 2, v150
	v_mov_b32_e32 v150, v155
	v_xor_b32_e32 v153, 16, v174
	v_xor_b32_e32 v154, 32, v174
	v_lshlrev_b32_e32 v153, 2, v153
	v_lshlrev_b32_e32 v154, 2, v154
	s_and_b64 s[20:21], s[72:73], exec
	s_cselect_b32 s20, 64, 0
	s_lshl_b32 s21, s94, 8
	s_add_i32 s21, s21, s20
	s_cmp_ge_u32 s94, 65
	s_cselect_b32 s96, s78, s76
	s_cselect_b32 s97, s79, s77
	s_cselect_b32 s98, s82, s54
	s_cselect_b32 s99, s83, s55
	s_mov_b32 s19, 0
	s_add_i32 s87, s21, 0
	s_mul_hi_u32 s89, s87, 0x7e07e07f
	s_lshr_b32 s89, s89, 11
	s_mul_i32 vcc_lo, s89, 0x1040
	s_sub_i32 vcc_lo, s87, vcc_lo
	s_add_i32 vcc_lo, vcc_lo, -16
	s_lshl_b32 s89, s89, 12
	s_add_i32 s89, s89, vcc_lo
	s_cmp_lt_u32 vcc_lo, 0x1000
	s_cselect_b32 vcc_hi, 1, 0
	s_sub_i32 vcc_lo, s87, 0x4100
	s_cmp_ge_u32 s94, 65
	s_cselect_b32 s89, vcc_lo, s89
	s_cselect_b32 vcc_hi, 1, vcc_hi
	s_cmp_lg_u32 vcc_hi, 0
	s_cselect_b32 s89, s89, 0
	s_lshl_b32 s20, s89, 12
	s_lshl_b32 vcc_hi, vcc_hi, 0
	s_or_b32 s19, s19, vcc_hi
	s_add_u32 s22, s96, s20
	s_addc_u32 s23, s97, 0
	global_load_dwordx4 v[176:179], v151, s[22:23]
	global_load_dwordx4 v[180:183], v151, s[22:23] offset:16
	global_load_dwordx4 v[184:187], v151, s[22:23] offset:512
	global_load_dwordx4 v[188:191], v151, s[22:23] offset:528
	s_add_i32 s87, s21, 16
	s_mul_hi_u32 s89, s87, 0x7e07e07f
	s_lshr_b32 s89, s89, 11
	s_mul_i32 vcc_lo, s89, 0x1040
	s_sub_i32 vcc_lo, s87, vcc_lo
	s_add_i32 vcc_lo, vcc_lo, -16
	s_lshl_b32 s89, s89, 12
	s_add_i32 s89, s89, vcc_lo
	s_cmp_lt_u32 vcc_lo, 0x1000
	s_cselect_b32 vcc_hi, 1, 0
	s_sub_i32 vcc_lo, s87, 0x4100
	s_cmp_ge_u32 s94, 65
	s_cselect_b32 s89, vcc_lo, s89
	s_cselect_b32 vcc_hi, 1, vcc_hi
	s_cmp_lg_u32 vcc_hi, 0
	s_cselect_b32 s89, s89, 0
	s_lshl_b32 s42, s89, 12
	s_lshl_b32 vcc_hi, vcc_hi, 1
	s_or_b32 s19, s19, vcc_hi
	s_add_u32 s22, s96, s42
	s_addc_u32 s23, s97, 0
	global_load_dwordx4 v[192:195], v151, s[22:23]
	global_load_dwordx4 v[196:199], v151, s[22:23] offset:16
	global_load_dwordx4 v[200:203], v151, s[22:23] offset:512
	global_load_dwordx4 v[204:207], v151, s[22:23] offset:528
	s_add_i32 s87, s21, 32
	s_mul_hi_u32 s89, s87, 0x7e07e07f
	s_lshr_b32 s89, s89, 11
	s_mul_i32 vcc_lo, s89, 0x1040
	s_sub_i32 vcc_lo, s87, vcc_lo
	s_add_i32 vcc_lo, vcc_lo, -16
	s_lshl_b32 s89, s89, 12
	s_add_i32 s89, s89, vcc_lo
	s_cmp_lt_u32 vcc_lo, 0x1000
	s_cselect_b32 vcc_hi, 1, 0
	s_sub_i32 vcc_lo, s87, 0x4100
	s_cmp_ge_u32 s94, 65
	s_cselect_b32 s89, vcc_lo, s89
	s_cselect_b32 vcc_hi, 1, vcc_hi
	s_cmp_lg_u32 vcc_hi, 0
	s_cselect_b32 s89, s89, 0
	s_lshl_b32 s43, s89, 12
	s_lshl_b32 vcc_hi, vcc_hi, 2
	s_or_b32 s19, s19, vcc_hi
	s_add_u32 s22, s96, s43
	s_addc_u32 s23, s97, 0
	global_load_dwordx4 v[208:211], v151, s[22:23]
	global_load_dwordx4 v[212:215], v151, s[22:23] offset:16
	global_load_dwordx4 v[216:219], v151, s[22:23] offset:512
	global_load_dwordx4 v[220:223], v151, s[22:23] offset:528
	s_add_i32 s87, s21, 48
	s_mul_hi_u32 s89, s87, 0x7e07e07f
	s_lshr_b32 s89, s89, 11
	s_mul_i32 vcc_lo, s89, 0x1040
	s_sub_i32 vcc_lo, s87, vcc_lo
	s_add_i32 vcc_lo, vcc_lo, -16
	s_lshl_b32 s89, s89, 12
	s_add_i32 s89, s89, vcc_lo
	s_cmp_lt_u32 vcc_lo, 0x1000
	s_cselect_b32 vcc_hi, 1, 0
	s_sub_i32 vcc_lo, s87, 0x4100
	s_cmp_ge_u32 s94, 65
	s_cselect_b32 s89, vcc_lo, s89
	s_cselect_b32 vcc_hi, 1, vcc_hi
	s_cmp_lg_u32 vcc_hi, 0
	s_cselect_b32 s89, s89, 0
	s_lshl_b32 s95, s89, 12
	s_lshl_b32 vcc_hi, vcc_hi, 3
	s_or_b32 s19, s19, vcc_hi
	s_add_u32 s22, s96, s95
	s_addc_u32 s23, s97, 0
	global_load_dwordx4 v[224:227], v151, s[22:23]
	global_load_dwordx4 v[228:231], v151, s[22:23] offset:16
	global_load_dwordx4 v[232:235], v151, s[22:23] offset:512
	global_load_dwordx4 v[236:239], v151, s[22:23] offset:528
	s_waitcnt vmcnt(0)
;     DI void operator()(const f32x4 (&acc)[2][2][4][2], const pg8::Unit& u, int wr, int wc, int fr, int fq) const {
;     ...
;                         const f32x4 h0 = x0 + acc[ai][bj][m][0], h1 = x1 + acc[ai][bj][m][1];
;                         *(f32x4*)(yd + n) = h0; *(f32x4*)(yd + n + 4) = h1;
;                         ss += h0[0] * h0[0] + h0[1] * h0[1] + h0[2] * h0[2] + h0[3] * h0[3] + h1[0] * h1[0] + h1[1] * h1[1] + h1[2] * h1[2] + h1[3] * h1[3];
;                     }
;                 }
;                 ss += __shfl_xor(ss, 16); ss += __shfl_xor(ss, 32);
;                 if (xs && fq == 0) atomicAdd(p.rowss + R, ss);
	v_pk_add_f32 v[124:125], v[124:125], v[176:177]
	v_pk_add_f32 v[126:127], v[126:127], v[178:179]
	v_pk_add_f32 v[120:121], v[120:121], v[180:181]
	v_pk_add_f32 v[122:123], v[122:123], v[182:183]
	v_pk_add_f32 v[116:117], v[116:117], v[184:185]
	v_pk_add_f32 v[118:119], v[118:119], v[186:187]
	v_pk_add_f32 v[112:113], v[112:113], v[188:189]
	v_pk_add_f32 v[114:115], v[114:115], v[190:191]
	v_pk_mul_f32 v[172:173], v[124:125], v[124:125]
	v_pk_fma_f32 v[172:173], v[126:127], v[126:127], v[172:173]
	v_pk_fma_f32 v[172:173], v[120:121], v[120:121], v[172:173]
	v_pk_fma_f32 v[172:173], v[122:123], v[122:123], v[172:173]
	v_pk_fma_f32 v[172:173], v[116:117], v[116:117], v[172:173]
	v_pk_fma_f32 v[172:173], v[118:119], v[118:119], v[172:173]
	v_pk_fma_f32 v[172:173], v[112:113], v[112:113], v[172:173]
	v_pk_fma_f32 v[172:173], v[114:115], v[114:115], v[172:173]
	s_nop 0
	v_add_f32_e32 v168, v172, v173
	v_pk_add_f32 v[108:109], v[108:109], v[192:193]
	v_pk_add_f32 v[110:111], v[110:111], v[194:195]
	v_pk_add_f32 v[104:105], v[104:105], v[196:197]
	v_pk_add_f32 v[106:107], v[106:107], v[198:199]
	v_pk_add_f32 v[100:101], v[100:101], v[200:201]
	v_pk_add_f32 v[102:103], v[102:103], v[202:203]
	v_pk_add_f32 v[96:97], v[96:97], v[204:205]
	v_pk_add_f32 v[98:99], v[98:99], v[206:207]
	v_pk_mul_f32 v[172:173], v[108:109], v[108:109]
	v_pk_fma_f32 v[172:173], v[110:111], v[110:111], v[172:173]
	v_pk_fma_f32 v[172:173], v[104:105], v[104:105], v[172:173]
	v_pk_fma_f32 v[172:173], v[106:107], v[106:107], v[172:173]
	v_pk_fma_f32 v[172:173], v[100:101], v[100:101], v[172:173]
	v_pk_fma_f32 v[172:173], v[102:103], v[102:103], v[172:173]
	v_pk_fma_f32 v[172:173], v[96:97], v[96:97], v[172:173]
	v_pk_fma_f32 v[172:173], v[98:99], v[98:99], v[172:173]
	s_nop 0
	v_add_f32_e32 v169, v172, v173
	v_pk_add_f32 v[92:93], v[92:93], v[208:209]
	v_pk_add_f32 v[94:95], v[94:95], v[210:211]
	v_pk_add_f32 v[88:89], v[88:89], v[212:213]
	v_pk_add_f32 v[90:91], v[90:91], v[214:215]
	v_pk_add_f32 v[84:85], v[84:85], v[216:217]
	v_pk_add_f32 v[86:87], v[86:87], v[218:219]
	v_pk_add_f32 v[80:81], v[80:81], v[220:221]
	v_pk_add_f32 v[82:83], v[82:83], v[222:223]
	v_pk_mul_f32 v[172:173], v[92:93], v[92:93]
	v_pk_fma_f32 v[172:173], v[94:95], v[94:95], v[172:173]
	v_pk_fma_f32 v[172:173], v[88:89], v[88:89], v[172:173]
	v_pk_fma_f32 v[172:173], v[90:91], v[90:91], v[172:173]
	v_pk_fma_f32 v[172:173], v[84:85], v[84:85], v[172:173]
	v_pk_fma_f32 v[172:173], v[86:87], v[86:87], v[172:173]
	v_pk_fma_f32 v[172:173], v[80:81], v[80:81], v[172:173]
	v_pk_fma_f32 v[172:173], v[82:83], v[82:83], v[172:173]
	s_nop 0
	v_add_f32_e32 v170, v172, v173
	v_pk_add_f32 v[76:77], v[76:77], v[224:225]
	v_pk_add_f32 v[78:79], v[78:79], v[226:227]
	v_pk_add_f32 v[72:73], v[72:73], v[228:229]
	v_pk_add_f32 v[74:75], v[74:75], v[230:231]
	v_pk_add_f32 v[68:69], v[68:69], v[232:233]
	v_pk_add_f32 v[70:71], v[70:71], v[234:235]
	v_pk_add_f32 v[64:65], v[64:65], v[236:237]
	v_pk_add_f32 v[66:67], v[66:67], v[238:239]
	v_pk_mul_f32 v[172:173], v[76:77], v[76:77]
	v_pk_fma_f32 v[172:173], v[78:79], v[78:79], v[172:173]
	v_pk_fma_f32 v[172:173], v[72:73], v[72:73], v[172:173]
	v_pk_fma_f32 v[172:173], v[74:75], v[74:75], v[172:173]
	v_pk_fma_f32 v[172:173], v[68:69], v[68:69], v[172:173]
	v_pk_fma_f32 v[172:173], v[70:71], v[70:71], v[172:173]
	v_pk_fma_f32 v[172:173], v[64:65], v[64:65], v[172:173]
	v_pk_fma_f32 v[172:173], v[66:67], v[66:67], v[172:173]
	s_nop 0
	v_add_f32_e32 v171, v172, v173
	ds_bpermute_b32 v155, v153, v168
	ds_bpermute_b32 v156, v153, v169
	ds_bpermute_b32 v157, v153, v170
	ds_bpermute_b32 v132, v153, v171
	s_waitcnt lgkmcnt(0)
	v_add_f32_e32 v168, v168, v155
	v_add_f32_e32 v169, v169, v156
	v_add_f32_e32 v170, v170, v157
	v_add_f32_e32 v171, v171, v132
	ds_bpermute_b32 v155, v154, v168
	ds_bpermute_b32 v156, v154, v169
	ds_bpermute_b32 v157, v154, v170
	ds_bpermute_b32 v132, v154, v171
	s_waitcnt lgkmcnt(0)
	v_add_f32_e32 v168, v168, v155
	v_add_f32_e32 v169, v169, v156
	v_add_f32_e32 v170, v170, v157
	v_add_f32_e32 v171, v171, v132
	s_mov_b64 exec, s[36:37]
	s_bitcmp1_b32 s19, 0
	s_cbranch_scc0 .Lf3f_at_b0_0
	global_atomic_add_f32 v152, v168, s[60:61]

;     DI void operator()(const f32x4 (&acc)[2][2][4][2], const pg8::Unit& u, int wr, int wc, int fr, int fq) const {
;     ...
;                 const int R = u.pm * 256 + ai * 128 + wr * 64 + m * 16 + fr;
;                 const float* xs = nullptr; float* yd = nullptr;
;                 if (R < ROWS_P) { const int b = R / LPAD, t = R - b * LPAD; if (t >= NMETA && t < LP) { const size_t idx = ((size_t)b * SEQ + t - NMETA) * DM; xs = p.x_prompt + idx; yd = p.out + O_YP + idx; } }
;                 else { const size_t idx = (size_t)(R - ROWS_P) * DM; xs = p.x_sample + idx; yd = p.out + O_YS + idx; }
;                 float ss = 0.f;
;                 if (xs) {
; #pragma unroll
;                     for (int bj = 0; bj < 2; ++bj) {
;                         const int n = colt + bj * 128 + wc * 32 + 8 * fq;
;                         const f32x4 x0 = *(const f32x4*)(xs + n), x1 = *(const f32x4*)(xs + n + 4);
.Lf3f_at_b0_3:
	s_mov_b64 exec, -1
	s_add_i32 s87, s21, 128
	s_mul_hi_u32 s89, s87, 0x7e07e07f
	s_lshr_b32 s89, s89, 11
	s_mul_i32 vcc_lo, s89, 0x1040
	s_sub_i32 vcc_lo, s87, vcc_lo
	s_add_i32 vcc_lo, vcc_lo, -16
	s_lshl_b32 s89, s89, 12
	s_add_i32 s89, s89, vcc_lo
	s_cmp_lt_u32 vcc_lo, 0x1000
	s_cselect_b32 vcc_hi, 1, 0
	s_sub_i32 vcc_lo, s87, 0x4100
	s_cmp_ge_u32 s94, 65
	s_cselect_b32 s89, vcc_lo, s89
	s_cselect_b32 vcc_hi, 1, vcc_hi
	s_cmp_lg_u32 vcc_hi, 0
	s_cselect_b32 s89, s89, 0
	s_lshl_b32 s20, s89, 12
	s_lshl_b32 vcc_hi, vcc_hi, 4
	s_or_b32 s19, s19, vcc_hi
	s_add_u32 s22, s96, s20
	s_addc_u32 s23, s97, 0
	global_load_dwordx4 v[176:179], v151, s[22:23]
	global_load_dwordx4 v[180:183], v151, s[22:23] offset:16
	global_load_dwordx4 v[184:187], v151, s[22:23] offset:512
	global_load_dwordx4 v[188:191], v151, s[22:23] offset:528
	s_add_i32 s87, s21, 144
	s_mul_hi_u32 s89, s87, 0x7e07e07f
	s_lshr_b32 s89, s89, 11
	s_mul_i32 vcc_lo, s89, 0x1040
	s_sub_i32 vcc_lo, s87, vcc_lo
	s_add_i32 vcc_lo, vcc_lo, -16
	s_lshl_b32 s89, s89, 12
	s_add_i32 s89, s89, vcc_lo
	s_cmp_lt_u32 vcc_lo, 0x1000
	s_cselect_b32 vcc_hi, 1, 0
	s_sub_i32 vcc_lo, s87, 0x4100
	s_cmp_ge_u32 s94, 65
	s_cselect_b32 s89, vcc_lo, s89
	s_cselect_b32 vcc_hi, 1, vcc_hi
	s_cmp_lg_u32 vcc_hi, 0
	s_cselect_b32 s89, s89, 0
	s_lshl_b32 s42, s89, 12
	s_lshl_b32 vcc_hi, vcc_hi, 5
	s_or_b32 s19, s19, vcc_hi
	s_add_u32 s22, s96, s42
	s_addc_u32 s23, s97, 0
	global_load_dwordx4 v[192:195], v151, s[22:23]
	global_load_dwordx4 v[196:199], v151, s[22:23] offset:16
	global_load_dwordx4 v[200:203], v151, s[22:23] offset:512
	global_load_dwordx4 v[204:207], v151, s[22:23] offset:528
	s_add_i32 s87, s21, 160
	s_mul_hi_u32 s89, s87, 0x7e07e07f
	s_lshr_b32 s89, s89, 11
	s_mul_i32 vcc_lo, s89, 0x1040
	s_sub_i32 vcc_lo, s87, vcc_lo
	s_add_i32 vcc_lo, vcc_lo, -16
	s_lshl_b32 s89, s89, 12
	s_add_i32 s89, s89, vcc_lo
	s_cmp_lt_u32 vcc_lo, 0x1000
	s_cselect_b32 vcc_hi, 1, 0
	s_sub_i32 vcc_lo, s87, 0x4100
	s_cmp_ge_u32 s94, 65
	s_cselect_b32 s89, vcc_lo, s89
	s_cselect_b32 vcc_hi, 1, vcc_hi
	s_cmp_lg_u32 vcc_hi, 0
	s_cselect_b32 s89, s89, 0
	s_lshl_b32 s43, s89, 12
	s_lshl_b32 vcc_hi, vcc_hi, 6
	s_or_b32 s19, s19, vcc_hi
	s_add_u32 s22, s96, s43
	s_addc_u32 s23, s97, 0
	global_load_dwordx4 v[208:211], v151, s[22:23]
	global_load_dwordx4 v[212:215], v151, s[22:23] offset:16
	global_load_dwordx4 v[216:219], v151, s[22:23] offset:512
	global_load_dwordx4 v[220:223], v151, s[22:23] offset:528
	s_add_i32 s87, s21, 176
	s_mul_hi_u32 s89, s87, 0x7e07e07f
	s_lshr_b32 s89, s89, 11
	s_mul_i32 vcc_lo, s89, 0x1040
	s_sub_i32 vcc_lo, s87, vcc_lo
	s_add_i32 vcc_lo, vcc_lo, -16
	s_lshl_b32 s89, s89, 12
	s_add_i32 s89, s89, vcc_lo
	s_cmp_lt_u32 vcc_lo, 0x1000
	s_cselect_b32 vcc_hi, 1, 0
	s_sub_i32 vcc_lo, s87, 0x4100
	s_cmp_ge_u32 s94, 65
	s_cselect_b32 s89, vcc_lo, s89
	s_cselect_b32 vcc_hi, 1, vcc_hi
	s_cmp_lg_u32 vcc_hi, 0
	s_cselect_b32 s89, s89, 0
	s_lshl_b32 s95, s89, 12
	s_lshl_b32 vcc_hi, vcc_hi, 7
	s_or_b32 s19, s19, vcc_hi
	s_add_u32 s22, s96, s95
	s_addc_u32 s23, s97, 0
	global_load_dwordx4 v[224:227], v151, s[22:23]
	global_load_dwordx4 v[228:231], v151, s[22:23] offset:16
	global_load_dwordx4 v[232:235], v151, s[22:23] offset:512
	global_load_dwordx4 v[236:239], v151, s[22:23] offset:528
	s_waitcnt vmcnt(0)
;     DI void operator()(const f32x4 (&acc)[2][2][4][2], const pg8::Unit& u, int wr, int wc, int fr, int fq) const {
;     ...
;                         const f32x4 h0 = x0 + acc[ai][bj][m][0], h1 = x1 + acc[ai][bj][m][1];
;                         *(f32x4*)(yd + n) = h0; *(f32x4*)(yd + n + 4) = h1;
;                         ss += h0[0] * h0[0] + h0[1] * h0[1] + h0[2] * h0[2] + h0[3] * h0[3] + h1[0] * h1[0] + h1[1] * h1[1] + h1[2] * h1[2] + h1[3] * h1[3];
;                     }
;                 }
;                 ss += __shfl_xor(ss, 16); ss += __shfl_xor(ss, 32);
;                 if (xs && fq == 0) atomicAdd(p.rowss + R, ss);
	v_pk_add_f32 v[60:61], v[60:61], v[176:177]
	v_pk_add_f32 v[62:63], v[62:63], v[178:179]
	v_pk_add_f32 v[56:57], v[56:57], v[180:181]
	v_pk_add_f32 v[58:59], v[58:59], v[182:183]
	v_pk_add_f32 v[52:53], v[52:53], v[184:185]
	v_pk_add_f32 v[54:55], v[54:55], v[186:187]
	v_pk_add_f32 v[48:49], v[48:49], v[188:189]
	v_pk_add_f32 v[50:51], v[50:51], v[190:191]
	v_pk_mul_f32 v[172:173], v[60:61], v[60:61]
	v_pk_fma_f32 v[172:173], v[62:63], v[62:63], v[172:173]
	v_pk_fma_f32 v[172:173], v[56:57], v[56:57], v[172:173]
	v_pk_fma_f32 v[172:173], v[58:59], v[58:59], v[172:173]
	v_pk_fma_f32 v[172:173], v[52:53], v[52:53], v[172:173]
	v_pk_fma_f32 v[172:173], v[54:55], v[54:55], v[172:173]
	v_pk_fma_f32 v[172:173], v[48:49], v[48:49], v[172:173]
	v_pk_fma_f32 v[172:173], v[50:51], v[50:51], v[172:173]
	s_nop 0
	v_add_f32_e32 v168, v172, v173
	v_pk_add_f32 v[44:45], v[44:45], v[192:193]
	v_pk_add_f32 v[46:47], v[46:47], v[194:195]
	v_pk_add_f32 v[40:41], v[40:41], v[196:197]
	v_pk_add_f32 v[42:43], v[42:43], v[198:199]
	v_pk_add_f32 v[36:37], v[36:37], v[200:201]
	v_pk_add_f32 v[38:39], v[38:39], v[202:203]
	v_pk_add_f32 v[32:33], v[32:33], v[204:205]
	v_pk_add_f32 v[34:35], v[34:35], v[206:207]
	v_pk_mul_f32 v[172:173], v[44:45], v[44:45]
	v_pk_fma_f32 v[172:173], v[46:47], v[46:47], v[172:173]
	v_pk_fma_f32 v[172:173], v[40:41], v[40:41], v[172:173]
	v_pk_fma_f32 v[172:173], v[42:43], v[42:43], v[172:173]
	v_pk_fma_f32 v[172:173], v[36:37], v[36:37], v[172:173]
	v_pk_fma_f32 v[172:173], v[38:39], v[38:39], v[172:173]
	v_pk_fma_f32 v[172:173], v[32:33], v[32:33], v[172:173]
	v_pk_fma_f32 v[172:173], v[34:35], v[34:35], v[172:173]
	s_nop 0
	v_add_f32_e32 v169, v172, v173
	v_pk_add_f32 v[28:29], v[28:29], v[208:209]
	v_pk_add_f32 v[30:31], v[30:31], v[210:211]
	v_pk_add_f32 v[24:25], v[24:25], v[212:213]
	v_pk_add_f32 v[26:27], v[26:27], v[214:215]
	v_pk_add_f32 v[20:21], v[20:21], v[216:217]
	v_pk_add_f32 v[22:23], v[22:23], v[218:219]
	v_pk_add_f32 v[16:17], v[16:17], v[220:221]
	v_pk_add_f32 v[18:19], v[18:19], v[222:223]
	v_pk_mul_f32 v[172:173], v[28:29], v[28:29]
	v_pk_fma_f32 v[172:173], v[30:31], v[30:31], v[172:173]
	v_pk_fma_f32 v[172:173], v[24:25], v[24:25], v[172:173]
	v_pk_fma_f32 v[172:173], v[26:27], v[26:27], v[172:173]
	v_pk_fma_f32 v[172:173], v[20:21], v[20:21], v[172:173]
	v_pk_fma_f32 v[172:173], v[22:23], v[22:23], v[172:173]
	v_pk_fma_f32 v[172:173], v[16:17], v[16:17], v[172:173]
	v_pk_fma_f32 v[172:173], v[18:19], v[18:19], v[172:173]
	s_nop 0
	v_add_f32_e32 v170, v172, v173
	v_pk_add_f32 v[12:13], v[12:13], v[224:225]
	v_pk_add_f32 v[14:15], v[14:15], v[226:227]
	v_pk_add_f32 v[8:9], v[8:9], v[228:229]
	v_pk_add_f32 v[10:11], v[10:11], v[230:231]
	v_pk_add_f32 v[4:5], v[4:5], v[232:233]
	v_pk_add_f32 v[6:7], v[6:7], v[234:235]
	v_pk_add_f32 v[0:1], v[0:1], v[236:237]
	v_pk_add_f32 v[2:3], v[2:3], v[238:239]
	v_pk_mul_f32 v[172:173], v[12:13], v[12:13]
	v_pk_fma_f32 v[172:173], v[14:15], v[14:15], v[172:173]
	v_pk_fma_f32 v[172:173], v[8:9], v[8:9], v[172:173]
	v_pk_fma_f32 v[172:173], v[10:11], v[10:11], v[172:173]
	v_pk_fma_f32 v[172:173], v[4:5], v[4:5], v[172:173]
	v_pk_fma_f32 v[172:173], v[6:7], v[6:7], v[172:173]
	v_pk_fma_f32 v[172:173], v[0:1], v[0:1], v[172:173]
	v_pk_fma_f32 v[172:173], v[2:3], v[2:3], v[172:173]
	s_nop 0
	v_add_f32_e32 v171, v172, v173
	ds_bpermute_b32 v155, v153, v168
	ds_bpermute_b32 v156, v153, v169
	ds_bpermute_b32 v157, v153, v170
	ds_bpermute_b32 v132, v153, v171
	s_waitcnt lgkmcnt(0)
	v_add_f32_e32 v168, v168, v155
	v_add_f32_e32 v169, v169, v156
	v_add_f32_e32 v170, v170, v157
	v_add_f32_e32 v171, v171, v132
	ds_bpermute_b32 v155, v154, v168
	ds_bpermute_b32 v156, v154, v169
	ds_bpermute_b32 v157, v154, v170
	ds_bpermute_b32 v132, v154, v171
	s_waitcnt lgkmcnt(0)
	v_add_f32_e32 v168, v168, v155
	v_add_f32_e32 v169, v169, v156
	v_add_f32_e32 v170, v170, v157
	v_add_f32_e32 v171, v171, v132
	s_mov_b64 exec, s[36:37]
	s_bitcmp1_b32 s19, 4
	s_cbranch_scc0 .Lf3f_at_b1_0
	global_atomic_add_f32 v152, v168, s[60:61] offset:512

;     DI void operator()(const f32x4 (&acc)[2][2][4][2], const pg8::Unit& u, int wr, int wc, int fr, int fq) const {
;     ...
;                 ss += __shfl_xor(ss, 16); ss += __shfl_xor(ss, 32);
;                 if (xs && fq == 0) atomicAdd(p.rowss + R, ss);
; __global__ void __launch_bounds__(512, 2) hymba_mega(Params p) {
;     ...
;                 rn = p.rowss[Rn < NR ? Rn : 0];
; #pragma unroll
;                 for (int i = 0; i < 4; ++i) vn[i] = *(const f32x4*)(dn + i * 256 + lane * 4);
;             }
;             if (!yd) continue;
;             const float rstd = 1.0f / sqrtf(rs * (1.0f / 1024.0f) + EPS);
.Lf3f_at_b1_3:
	s_mov_b64 exec, -1
	v_mov_b32_e32 v209, 0
	v_mov_b32_e32 v210, 1
	s_lshl_b32 s22, s94, 2
	s_add_i32 s22, s22, 96
	v_mov_b32_e32 v211, s22
	s_waitcnt vmcnt(0)
	s_barrier
	global_load_dwordx4 v[176:179], v150, s[52:53]
	global_load_dwordx4 v[180:183], v150, s[52:53] offset:16
	global_load_dwordx4 v[184:187], v150, s[52:53] offset:512
	global_load_dwordx4 v[188:191], v150, s[52:53] offset:528
	v_and_b32_e32 v208, 15, v174
	v_lshlrev_b32_e32 v208, 2, v208
	v_mov_b32_e32 v218, 0x358637bd
	v_mov_b32_e32 v219, 0x260
	s_movk_i32 s23, 4
	s_and_saveexec_b64 vcc, s[40:41]
	s_cbranch_execz .Lf3f_go_f
	global_atomic_add v211, v210, s[56:57]
.Lf3f_poll_f:
	global_atomic_add v212, v211, v209, s[56:57] sc0
	s_waitcnt vmcnt(0)
	v_readfirstlane_b32 s22, v212
	s_cmp_ge_u32 s22, s23
	s_cbranch_scc1 .Lf3f_go_f
	s_sleep 16
	s_branch .Lf3f_poll_f
.Lf3f_go_f:
	s_or_b64 exec, exec, vcc
	s_barrier
	s_mov_b64 exec, s[36:37]
	global_atomic_add_f32 v192, v152, v209, s[60:61] sc0
	global_atomic_add_f32 v194, v152, v209, s[60:61] offset:64 sc0
	global_atomic_add_f32 v196, v152, v209, s[60:61] offset:128 sc0
	global_atomic_add_f32 v198, v152, v209, s[60:61] offset:192 sc0
	global_atomic_add_f32 v200, v152, v209, s[60:61] offset:512 sc0
	global_atomic_add_f32 v202, v152, v209, s[60:61] offset:576 sc0
	global_atomic_add_f32 v204, v152, v209, s[60:61] offset:640 sc0
	global_atomic_add_f32 v206, v152, v209, s[60:61] offset:704 sc0
	s_mov_b64 exec, -1
	s_waitcnt vmcnt(0)
	ds_bpermute_b32 v192, v208, v192
	ds_bpermute_b32 v194, v208, v194
	ds_bpermute_b32 v196, v208, v196
	ds_bpermute_b32 v198, v208, v198
	ds_bpermute_b32 v200, v208, v200
	ds_bpermute_b32 v202, v208, v202
	ds_bpermute_b32 v204, v208, v204
	ds_bpermute_b32 v206, v208, v206
	s_waitcnt lgkmcnt(0)
	v_fmamk_f32 v213, v192, 0x3a800000, v218
	v_mul_f32_e32 v214, 0x4f800000, v213
	v_cmp_gt_f32_e32 vcc, 0xf800000, v213
	s_nop 1
	v_cndmask_b32_e32 v213, v213, v214, vcc
	v_sqrt_f32_e32 v214, v213
	s_nop 0
	v_add_u32_e32 v215, -1, v214
	v_fma_f32 v217, -v215, v214, v213
	v_add_u32_e32 v216, 1, v214
	v_cmp_ge_f32_e64 s[22:23], 0, v217
	s_nop 1
	v_cndmask_b32_e64 v215, v214, v215, s[22:23]
	v_fma_f32 v214, -v216, v214, v213
	v_cmp_lt_f32_e64 s[22:23], 0, v214
	s_nop 1
	v_cndmask_b32_e64 v214, v215, v216, s[22:23]
	v_mul_f32_e32 v215, 0x37800000, v214
	v_cndmask_b32_e32 v214, v214, v215, vcc
	v_cmp_class_f32_e32 vcc, v213, v219
	s_nop 1
	v_cndmask_b32_e32 v213, v214, v213, vcc
	v_div_scale_f32 v214, s[22:23], v213, v213, 1.0
	v_rcp_f32_e32 v215, v214
	s_nop 0
	v_fma_f32 v216, -v214, v215, 1.0
	v_fmac_f32_e32 v215, v216, v215
	v_div_scale_f32 v216, vcc, 1.0, v213, 1.0
	v_mul_f32_e32 v217, v216, v215
	v_fma_f32 v192, -v214, v217, v216
	v_fmac_f32_e32 v217, v192, v215
	v_fma_f32 v214, -v214, v217, v216
	s_nop 0
	v_div_fmas_f32 v214, v214, v215, v217
	v_div_fixup_f32 v192, v214, v213, 1.0
	v_fmamk_f32 v213, v194, 0x3a800000, v218
	v_mul_f32_e32 v214, 0x4f800000, v213
	v_cmp_gt_f32_e32 vcc, 0xf800000, v213
	s_nop 1
	v_cndmask_b32_e32 v213, v213, v214, vcc
	v_sqrt_f32_e32 v214, v213
	s_nop 0
	v_add_u32_e32 v215, -1, v214
	v_fma_f32 v217, -v215, v214, v213
	v_add_u32_e32 v216, 1, v214
	v_cmp_ge_f32_e64 s[22:23], 0, v217
	s_nop 1
	v_cndmask_b32_e64 v215, v214, v215, s[22:23]
	v_fma_f32 v214, -v216, v214, v213
	v_cmp_lt_f32_e64 s[22:23], 0, v214
	s_nop 1
	v_cndmask_b32_e64 v214, v215, v216, s[22:23]
	v_mul_f32_e32 v215, 0x37800000, v214
	v_cndmask_b32_e32 v214, v214, v215, vcc
	v_cmp_class_f32_e32 vcc, v213, v219
	s_nop 1
	v_cndmask_b32_e32 v213, v214, v213, vcc
	v_div_scale_f32 v214, s[22:23], v213, v213, 1.0
	v_rcp_f32_e32 v215, v214
	s_nop 0
	v_fma_f32 v216, -v214, v215, 1.0
	v_fmac_f32_e32 v215, v216, v215
	v_div_scale_f32 v216, vcc, 1.0, v213, 1.0
	v_mul_f32_e32 v217, v216, v215
	v_fma_f32 v194, -v214, v217, v216
	v_fmac_f32_e32 v217, v194, v215
	v_fma_f32 v214, -v214, v217, v216
	s_nop 0
	v_div_fmas_f32 v214, v214, v215, v217
	v_div_fixup_f32 v194, v214, v213, 1.0
	v_fmamk_f32 v213, v196, 0x3a800000, v218
	v_mul_f32_e32 v214, 0x4f800000, v213
	v_cmp_gt_f32_e32 vcc, 0xf800000, v213
	s_nop 1
	v_cndmask_b32_e32 v213, v213, v214, vcc
	v_sqrt_f32_e32 v214, v213
	s_nop 0
	v_add_u32_e32 v215, -1, v214
	v_fma_f32 v217, -v215, v214, v213
	v_add_u32_e32 v216, 1, v214
	v_cmp_ge_f32_e64 s[22:23], 0, v217
	s_nop 1
	v_cndmask_b32_e64 v215, v214, v215, s[22:23]
	v_fma_f32 v214, -v216, v214, v213
	v_cmp_lt_f32_e64 s[22:23], 0, v214
	s_nop 1
	v_cndmask_b32_e64 v214, v215, v216, s[22:23]
	v_mul_f32_e32 v215, 0x37800000, v214
	v_cndmask_b32_e32 v214, v214, v215, vcc
	v_cmp_class_f32_e32 vcc, v213, v219
	s_nop 1
	v_cndmask_b32_e32 v213, v214, v213, vcc
	v_div_scale_f32 v214, s[22:23], v213, v213, 1.0
	v_rcp_f32_e32 v215, v214
	s_nop 0
	v_fma_f32 v216, -v214, v215, 1.0
	v_fmac_f32_e32 v215, v216, v215
	v_div_scale_f32 v216, vcc, 1.0, v213, 1.0
	v_mul_f32_e32 v217, v216, v215
	v_fma_f32 v196, -v214, v217, v216
	v_fmac_f32_e32 v217, v196, v215
	v_fma_f32 v214, -v214, v217, v216
	s_nop 0
	v_div_fmas_f32 v214, v214, v215, v217
	v_div_fixup_f32 v196, v214, v213, 1.0
	v_fmamk_f32 v213, v198, 0x3a800000, v218
	v_mul_f32_e32 v214, 0x4f800000, v213
	v_cmp_gt_f32_e32 vcc, 0xf800000, v213
	s_nop 1
	v_cndmask_b32_e32 v213, v213, v214, vcc
	v_sqrt_f32_e32 v214, v213
	s_nop 0
	v_add_u32_e32 v215, -1, v214
	v_fma_f32 v217, -v215, v214, v213
	v_add_u32_e32 v216, 1, v214
	v_cmp_ge_f32_e64 s[22:23], 0, v217
	s_nop 1
	v_cndmask_b32_e64 v215, v214, v215, s[22:23]
	v_fma_f32 v214, -v216, v214, v213
	v_cmp_lt_f32_e64 s[22:23], 0, v214
	s_nop 1
	v_cndmask_b32_e64 v214, v215, v216, s[22:23]
	v_mul_f32_e32 v215, 0x37800000, v214
	v_cndmask_b32_e32 v214, v214, v215, vcc
; __global__ void __launch_bounds__(512, 2) hymba_mega(Params p) {
;     ...
;             const float rstd = 1.0f / sqrtf(rs * (1.0f / 1024.0f) + EPS);
; #pragma unroll
;             for (int i = 0; i < 4; ++i) *(f32x4*)(yd + i * 256 + lane * 4) = v[i] * rstd * gq[i];
	v_cmp_class_f32_e32 vcc, v213, v219
	s_nop 1
	v_cndmask_b32_e32 v213, v214, v213, vcc
	v_div_scale_f32 v214, s[22:23], v213, v213, 1.0
	v_rcp_f32_e32 v215, v214
	s_nop 0
	v_fma_f32 v216, -v214, v215, 1.0
	v_fmac_f32_e32 v215, v216, v215
	v_div_scale_f32 v216, vcc, 1.0, v213, 1.0
	v_mul_f32_e32 v217, v216, v215
	v_fma_f32 v198, -v214, v217, v216
	v_fmac_f32_e32 v217, v198, v215
	v_fma_f32 v214, -v214, v217, v216
	s_nop 0
	v_div_fmas_f32 v214, v214, v215, v217
	v_div_fixup_f32 v198, v214, v213, 1.0
	v_fmamk_f32 v213, v200, 0x3a800000, v218
	v_mul_f32_e32 v214, 0x4f800000, v213
	v_cmp_gt_f32_e32 vcc, 0xf800000, v213
	s_nop 1
	v_cndmask_b32_e32 v213, v213, v214, vcc
	v_sqrt_f32_e32 v214, v213
	s_nop 0
	v_add_u32_e32 v215, -1, v214
	v_fma_f32 v217, -v215, v214, v213
	v_add_u32_e32 v216, 1, v214
	v_cmp_ge_f32_e64 s[22:23], 0, v217
	s_nop 1
	v_cndmask_b32_e64 v215, v214, v215, s[22:23]
	v_fma_f32 v214, -v216, v214, v213
	v_cmp_lt_f32_e64 s[22:23], 0, v214
	s_nop 1
	v_cndmask_b32_e64 v214, v215, v216, s[22:23]
	v_mul_f32_e32 v215, 0x37800000, v214
	v_cndmask_b32_e32 v214, v214, v215, vcc
	v_cmp_class_f32_e32 vcc, v213, v219
	s_nop 1
	v_cndmask_b32_e32 v213, v214, v213, vcc
	v_div_scale_f32 v214, s[22:23], v213, v213, 1.0
	v_rcp_f32_e32 v215, v214
	s_nop 0
	v_fma_f32 v216, -v214, v215, 1.0
	v_fmac_f32_e32 v215, v216, v215
	v_div_scale_f32 v216, vcc, 1.0, v213, 1.0
	v_mul_f32_e32 v217, v216, v215
	v_fma_f32 v200, -v214, v217, v216
	v_fmac_f32_e32 v217, v200, v215
	v_fma_f32 v214, -v214, v217, v216
	s_nop 0
	v_div_fmas_f32 v214, v214, v215, v217
	v_div_fixup_f32 v200, v214, v213, 1.0
	v_fmamk_f32 v213, v202, 0x3a800000, v218
	v_mul_f32_e32 v214, 0x4f800000, v213
	v_cmp_gt_f32_e32 vcc, 0xf800000, v213
	s_nop 1
	v_cndmask_b32_e32 v213, v213, v214, vcc
	v_sqrt_f32_e32 v214, v213
	s_nop 0
	v_add_u32_e32 v215, -1, v214
	v_fma_f32 v217, -v215, v214, v213
	v_add_u32_e32 v216, 1, v214
	v_cmp_ge_f32_e64 s[22:23], 0, v217
	s_nop 1
	v_cndmask_b32_e64 v215, v214, v215, s[22:23]
	v_fma_f32 v214, -v216, v214, v213
	v_cmp_lt_f32_e64 s[22:23], 0, v214
	s_nop 1
	v_cndmask_b32_e64 v214, v215, v216, s[22:23]
	v_mul_f32_e32 v215, 0x37800000, v214
	v_cndmask_b32_e32 v214, v214, v215, vcc
	v_cmp_class_f32_e32 vcc, v213, v219
	s_nop 1
	v_cndmask_b32_e32 v213, v214, v213, vcc
	v_div_scale_f32 v214, s[22:23], v213, v213, 1.0
	v_rcp_f32_e32 v215, v214
	s_nop 0
	v_fma_f32 v216, -v214, v215, 1.0
	v_fmac_f32_e32 v215, v216, v215
	v_div_scale_f32 v216, vcc, 1.0, v213, 1.0
	v_mul_f32_e32 v217, v216, v215
	v_fma_f32 v202, -v214, v217, v216
	v_fmac_f32_e32 v217, v202, v215
	v_fma_f32 v214, -v214, v217, v216
	s_nop 0
	v_div_fmas_f32 v214, v214, v215, v217
	v_div_fixup_f32 v202, v214, v213, 1.0
	v_fmamk_f32 v213, v204, 0x3a800000, v218
	v_mul_f32_e32 v214, 0x4f800000, v213
	v_cmp_gt_f32_e32 vcc, 0xf800000, v213
	s_nop 1
	v_cndmask_b32_e32 v213, v213, v214, vcc
	v_sqrt_f32_e32 v214, v213
	s_nop 0
	v_add_u32_e32 v215, -1, v214
	v_fma_f32 v217, -v215, v214, v213
	v_add_u32_e32 v216, 1, v214
	v_cmp_ge_f32_e64 s[22:23], 0, v217
	s_nop 1
	v_cndmask_b32_e64 v215, v214, v215, s[22:23]
	v_fma_f32 v214, -v216, v214, v213
	v_cmp_lt_f32_e64 s[22:23], 0, v214
	s_nop 1
	v_cndmask_b32_e64 v214, v215, v216, s[22:23]
	v_mul_f32_e32 v215, 0x37800000, v214
	v_cndmask_b32_e32 v214, v214, v215, vcc
	v_cmp_class_f32_e32 vcc, v213, v219
	s_nop 1
	v_cndmask_b32_e32 v213, v214, v213, vcc
	v_div_scale_f32 v214, s[22:23], v213, v213, 1.0
	v_rcp_f32_e32 v215, v214
	s_nop 0
	v_fma_f32 v216, -v214, v215, 1.0
	v_fmac_f32_e32 v215, v216, v215
	v_div_scale_f32 v216, vcc, 1.0, v213, 1.0
	v_mul_f32_e32 v217, v216, v215
	v_fma_f32 v204, -v214, v217, v216
	v_fmac_f32_e32 v217, v204, v215
	v_fma_f32 v214, -v214, v217, v216
	s_nop 0
	v_div_fmas_f32 v214, v214, v215, v217
	v_div_fixup_f32 v204, v214, v213, 1.0
	v_fmamk_f32 v213, v206, 0x3a800000, v218
	v_mul_f32_e32 v214, 0x4f800000, v213
	v_cmp_gt_f32_e32 vcc, 0xf800000, v213
	s_nop 1
	v_cndmask_b32_e32 v213, v213, v214, vcc
	v_sqrt_f32_e32 v214, v213
	s_nop 0
	v_add_u32_e32 v215, -1, v214
	v_fma_f32 v217, -v215, v214, v213
	v_add_u32_e32 v216, 1, v214
	v_cmp_ge_f32_e64 s[22:23], 0, v217
	s_nop 1
	v_cndmask_b32_e64 v215, v214, v215, s[22:23]
	v_fma_f32 v214, -v216, v214, v213
	v_cmp_lt_f32_e64 s[22:23], 0, v214
	s_nop 1
	v_cndmask_b32_e64 v214, v215, v216, s[22:23]
	v_mul_f32_e32 v215, 0x37800000, v214
	v_cndmask_b32_e32 v214, v214, v215, vcc
	v_cmp_class_f32_e32 vcc, v213, v219
	s_nop 1
	v_cndmask_b32_e32 v213, v214, v213, vcc
	v_div_scale_f32 v214, s[22:23], v213, v213, 1.0
	v_rcp_f32_e32 v215, v214
	s_nop 0
	v_fma_f32 v216, -v214, v215, 1.0
	v_fmac_f32_e32 v215, v216, v215
	v_div_scale_f32 v216, vcc, 1.0, v213, 1.0
	v_mul_f32_e32 v217, v216, v215
	v_fma_f32 v206, -v214, v217, v216
	v_fmac_f32_e32 v217, v206, v215
	v_fma_f32 v214, -v214, v217, v216
	s_nop 0
	v_div_fmas_f32 v214, v214, v215, v217
	v_div_fixup_f32 v206, v214, v213, 1.0
	s_bitcmp1_b32 s19, 0
	s_cbranch_scc0 .Lf3f_st_0
	s_add_i32 s87, s21, 0
	s_mul_hi_u32 s89, s87, 0x7e07e07f
	s_lshr_b32 s89, s89, 11
	s_mul_i32 vcc_lo, s89, 0x1040
	s_sub_i32 vcc_lo, s87, vcc_lo
	s_add_i32 vcc_lo, vcc_lo, -16
	s_lshl_b32 s89, s89, 12
	s_add_i32 s89, s89, vcc_lo
	s_cmp_lt_u32 vcc_lo, 0x1000
	s_cselect_b32 vcc_hi, 1, 0
	s_sub_i32 vcc_lo, s87, 0x4100
	s_cmp_ge_u32 s94, 65
	s_cselect_b32 s89, vcc_lo, s89
	s_cselect_b32 vcc_hi, 1, vcc_hi
	s_cmp_lg_u32 vcc_hi, 0
	s_cselect_b32 s89, s89, 0
	s_lshl_b32 s20, s89, 12
	v_pk_mul_f32 v[112:113], v[192:193], v[112:113] op_sel_hi:[0,1]
	v_pk_mul_f32 v[114:115], v[192:193], v[114:115] op_sel_hi:[0,1]
	v_pk_mul_f32 v[116:117], v[192:193], v[116:117] op_sel_hi:[0,1]
	v_pk_mul_f32 v[118:119], v[192:193], v[118:119] op_sel_hi:[0,1]
	v_pk_mul_f32 v[120:121], v[192:193], v[120:121] op_sel_hi:[0,1]
	v_pk_mul_f32 v[122:123], v[192:193], v[122:123] op_sel_hi:[0,1]
	v_pk_mul_f32 v[124:125], v[192:193], v[124:125] op_sel_hi:[0,1]
	v_pk_mul_f32 v[126:127], v[192:193], v[126:127] op_sel_hi:[0,1]
	v_pk_mul_f32 v[124:125], v[176:177], v[124:125]
	v_pk_mul_f32 v[126:127], v[178:179], v[126:127]
	v_pk_mul_f32 v[120:121], v[180:181], v[120:121]
	v_pk_mul_f32 v[122:123], v[182:183], v[122:123]
	v_pk_mul_f32 v[116:117], v[184:185], v[116:117]
	v_pk_mul_f32 v[118:119], v[186:187], v[118:119]
	v_pk_mul_f32 v[112:113], v[188:189], v[112:113]
	v_pk_mul_f32 v[114:115], v[190:191], v[114:115]
	s_add_u32 s22, s98, s20
	s_addc_u32 s23, s99, 0
	global_store_dwordx4 v151, v[124:127], s[22:23]
	global_store_dwordx4 v151, v[120:123], s[22:23] offset:16
	global_store_dwordx4 v151, v[116:119], s[22:23] offset:512
	global_store_dwordx4 v151, v[112:115], s[22:23] offset:528
; __global__ void __launch_bounds__(512, 2) hymba_mega(Params p) {
;     ...
;             const float rstd = 1.0f / sqrtf(rs * (1.0f / 1024.0f) + EPS);
; #pragma unroll
;             for (int i = 0; i < 4; ++i) *(f32x4*)(yd + i * 256 + lane * 4) = v[i] * rstd * gq[i];
.Lf3f_st_0:
	s_bitcmp1_b32 s19, 1
	s_cbranch_scc0 .Lf3f_st_1
	s_add_i32 s87, s21, 16
	s_mul_hi_u32 s89, s87, 0x7e07e07f
	s_lshr_b32 s89, s89, 11
	s_mul_i32 vcc_lo, s89, 0x1040
	s_sub_i32 vcc_lo, s87, vcc_lo
	s_add_i32 vcc_lo, vcc_lo, -16
	s_lshl_b32 s89, s89, 12
	s_add_i32 s89, s89, vcc_lo
	s_cmp_lt_u32 vcc_lo, 0x1000
	s_cselect_b32 vcc_hi, 1, 0
	s_sub_i32 vcc_lo, s87, 0x4100
	s_cmp_ge_u32 s94, 65
	s_cselect_b32 s89, vcc_lo, s89
	s_cselect_b32 vcc_hi, 1, vcc_hi
	s_cmp_lg_u32 vcc_hi, 0
	s_cselect_b32 s89, s89, 0
	s_lshl_b32 s20, s89, 12
	v_pk_mul_f32 v[96:97], v[194:195], v[96:97] op_sel_hi:[0,1]
	v_pk_mul_f32 v[98:99], v[194:195], v[98:99] op_sel_hi:[0,1]
	v_pk_mul_f32 v[100:101], v[194:195], v[100:101] op_sel_hi:[0,1]
	v_pk_mul_f32 v[102:103], v[194:195], v[102:103] op_sel_hi:[0,1]
	v_pk_mul_f32 v[104:105], v[194:195], v[104:105] op_sel_hi:[0,1]
	v_pk_mul_f32 v[106:107], v[194:195], v[106:107] op_sel_hi:[0,1]
	v_pk_mul_f32 v[108:109], v[194:195], v[108:109] op_sel_hi:[0,1]
	v_pk_mul_f32 v[110:111], v[194:195], v[110:111] op_sel_hi:[0,1]
	v_pk_mul_f32 v[108:109], v[176:177], v[108:109]
	v_pk_mul_f32 v[110:111], v[178:179], v[110:111]
	v_pk_mul_f32 v[104:105], v[180:181], v[104:105]
	v_pk_mul_f32 v[106:107], v[182:183], v[106:107]
	v_pk_mul_f32 v[100:101], v[184:185], v[100:101]
	v_pk_mul_f32 v[102:103], v[186:187], v[102:103]
	v_pk_mul_f32 v[96:97], v[188:189], v[96:97]
	v_pk_mul_f32 v[98:99], v[190:191], v[98:99]
	s_add_u32 s22, s98, s20
	s_addc_u32 s23, s99, 0
	global_store_dwordx4 v151, v[108:111], s[22:23]
	global_store_dwordx4 v151, v[104:107], s[22:23] offset:16
	global_store_dwordx4 v151, v[100:103], s[22:23] offset:512
	global_store_dwordx4 v151, v[96:99], s[22:23] offset:528
.Lf3f_st_1:
	s_bitcmp1_b32 s19, 2
	s_cbranch_scc0 .Lf3f_st_2
	s_add_i32 s87, s21, 32
	s_mul_hi_u32 s89, s87, 0x7e07e07f
	s_lshr_b32 s89, s89, 11
	s_mul_i32 vcc_lo, s89, 0x1040
	s_sub_i32 vcc_lo, s87, vcc_lo
	s_add_i32 vcc_lo, vcc_lo, -16
	s_lshl_b32 s89, s89, 12
	s_add_i32 s89, s89, vcc_lo
	s_cmp_lt_u32 vcc_lo, 0x1000
	s_cselect_b32 vcc_hi, 1, 0
	s_sub_i32 vcc_lo, s87, 0x4100
	s_cmp_ge_u32 s94, 65
	s_cselect_b32 s89, vcc_lo, s89
	s_cselect_b32 vcc_hi, 1, vcc_hi
	s_cmp_lg_u32 vcc_hi, 0
	s_cselect_b32 s89, s89, 0
	s_lshl_b32 s20, s89, 12
	v_pk_mul_f32 v[80:81], v[196:197], v[80:81] op_sel_hi:[0,1]
	v_pk_mul_f32 v[82:83], v[196:197], v[82:83] op_sel_hi:[0,1]
	v_pk_mul_f32 v[84:85], v[196:197], v[84:85] op_sel_hi:[0,1]
	v_pk_mul_f32 v[86:87], v[196:197], v[86:87] op_sel_hi:[0,1]
	v_pk_mul_f32 v[88:89], v[196:197], v[88:89] op_sel_hi:[0,1]
	v_pk_mul_f32 v[90:91], v[196:197], v[90:91] op_sel_hi:[0,1]
	v_pk_mul_f32 v[92:93], v[196:197], v[92:93] op_sel_hi:[0,1]
	v_pk_mul_f32 v[94:95], v[196:197], v[94:95] op_sel_hi:[0,1]
	v_pk_mul_f32 v[92:93], v[176:177], v[92:93]
	v_pk_mul_f32 v[94:95], v[178:179], v[94:95]
	v_pk_mul_f32 v[88:89], v[180:181], v[88:89]
	v_pk_mul_f32 v[90:91], v[182:183], v[90:91]
	v_pk_mul_f32 v[84:85], v[184:185], v[84:85]
	v_pk_mul_f32 v[86:87], v[186:187], v[86:87]
	v_pk_mul_f32 v[80:81], v[188:189], v[80:81]
	v_pk_mul_f32 v[82:83], v[190:191], v[82:83]
	s_add_u32 s22, s98, s20
	s_addc_u32 s23, s99, 0
	global_store_dwordx4 v151, v[92:95], s[22:23]
	global_store_dwordx4 v151, v[88:91], s[22:23] offset:16
	global_store_dwordx4 v151, v[84:87], s[22:23] offset:512
	global_store_dwordx4 v151, v[80:83], s[22:23] offset:528
.Lf3f_st_2:
	s_bitcmp1_b32 s19, 3
	s_cbranch_scc0 .Lf3f_st_3
	s_add_i32 s87, s21, 48
	s_mul_hi_u32 s89, s87, 0x7e07e07f
	s_lshr_b32 s89, s89, 11
	s_mul_i32 vcc_lo, s89, 0x1040
	s_sub_i32 vcc_lo, s87, vcc_lo
	s_add_i32 vcc_lo, vcc_lo, -16
	s_lshl_b32 s89, s89, 12
	s_add_i32 s89, s89, vcc_lo
	s_cmp_lt_u32 vcc_lo, 0x1000
	s_cselect_b32 vcc_hi, 1, 0
	s_sub_i32 vcc_lo, s87, 0x4100
	s_cmp_ge_u32 s94, 65
	s_cselect_b32 s89, vcc_lo, s89
	s_cselect_b32 vcc_hi, 1, vcc_hi
	s_cmp_lg_u32 vcc_hi, 0
	s_cselect_b32 s89, s89, 0
	s_lshl_b32 s20, s89, 12
	v_pk_mul_f32 v[64:65], v[198:199], v[64:65] op_sel_hi:[0,1]
	v_pk_mul_f32 v[66:67], v[198:199], v[66:67] op_sel_hi:[0,1]
	v_pk_mul_f32 v[68:69], v[198:199], v[68:69] op_sel_hi:[0,1]
	v_pk_mul_f32 v[70:71], v[198:199], v[70:71] op_sel_hi:[0,1]
	v_pk_mul_f32 v[72:73], v[198:199], v[72:73] op_sel_hi:[0,1]
	v_pk_mul_f32 v[74:75], v[198:199], v[74:75] op_sel_hi:[0,1]
	v_pk_mul_f32 v[76:77], v[198:199], v[76:77] op_sel_hi:[0,1]
	v_pk_mul_f32 v[78:79], v[198:199], v[78:79] op_sel_hi:[0,1]
	v_pk_mul_f32 v[76:77], v[176:177], v[76:77]
	v_pk_mul_f32 v[78:79], v[178:179], v[78:79]
	v_pk_mul_f32 v[72:73], v[180:181], v[72:73]
	v_pk_mul_f32 v[74:75], v[182:183], v[74:75]
	v_pk_mul_f32 v[68:69], v[184:185], v[68:69]
	v_pk_mul_f32 v[70:71], v[186:187], v[70:71]
	v_pk_mul_f32 v[64:65], v[188:189], v[64:65]
	v_pk_mul_f32 v[66:67], v[190:191], v[66:67]
	s_add_u32 s22, s98, s20
	s_addc_u32 s23, s99, 0
	global_store_dwordx4 v151, v[76:79], s[22:23]
	global_store_dwordx4 v151, v[72:75], s[22:23] offset:16
	global_store_dwordx4 v151, v[68:71], s[22:23] offset:512
	global_store_dwordx4 v151, v[64:67], s[22:23] offset:528
; __global__ void __launch_bounds__(512, 2) hymba_mega(Params p) {
;     ...
;             const float rstd = 1.0f / sqrtf(rs * (1.0f / 1024.0f) + EPS);
; #pragma unroll
;             for (int i = 0; i < 4; ++i) *(f32x4*)(yd + i * 256 + lane * 4) = v[i] * rstd * gq[i];
.Lf3f_st_3:
	s_bitcmp1_b32 s19, 4
	s_cbranch_scc0 .Lf3f_st_4
	s_add_i32 s87, s21, 128
	s_mul_hi_u32 s89, s87, 0x7e07e07f
	s_lshr_b32 s89, s89, 11
	s_mul_i32 vcc_lo, s89, 0x1040
	s_sub_i32 vcc_lo, s87, vcc_lo
	s_add_i32 vcc_lo, vcc_lo, -16
	s_lshl_b32 s89, s89, 12
	s_add_i32 s89, s89, vcc_lo
	s_cmp_lt_u32 vcc_lo, 0x1000
	s_cselect_b32 vcc_hi, 1, 0
	s_sub_i32 vcc_lo, s87, 0x4100
	s_cmp_ge_u32 s94, 65
	s_cselect_b32 s89, vcc_lo, s89
	s_cselect_b32 vcc_hi, 1, vcc_hi
	s_cmp_lg_u32 vcc_hi, 0
	s_cselect_b32 s89, s89, 0
	s_lshl_b32 s20, s89, 12
	v_pk_mul_f32 v[48:49], v[200:201], v[48:49] op_sel_hi:[0,1]
	v_pk_mul_f32 v[50:51], v[200:201], v[50:51] op_sel_hi:[0,1]
	v_pk_mul_f32 v[52:53], v[200:201], v[52:53] op_sel_hi:[0,1]
	v_pk_mul_f32 v[54:55], v[200:201], v[54:55] op_sel_hi:[0,1]
	v_pk_mul_f32 v[56:57], v[200:201], v[56:57] op_sel_hi:[0,1]
	v_pk_mul_f32 v[58:59], v[200:201], v[58:59] op_sel_hi:[0,1]
	v_pk_mul_f32 v[60:61], v[200:201], v[60:61] op_sel_hi:[0,1]
	v_pk_mul_f32 v[62:63], v[200:201], v[62:63] op_sel_hi:[0,1]
	v_pk_mul_f32 v[60:61], v[176:177], v[60:61]
	v_pk_mul_f32 v[62:63], v[178:179], v[62:63]
	v_pk_mul_f32 v[56:57], v[180:181], v[56:57]
	v_pk_mul_f32 v[58:59], v[182:183], v[58:59]
	v_pk_mul_f32 v[52:53], v[184:185], v[52:53]
	v_pk_mul_f32 v[54:55], v[186:187], v[54:55]
	v_pk_mul_f32 v[48:49], v[188:189], v[48:49]
	v_pk_mul_f32 v[50:51], v[190:191], v[50:51]
	s_add_u32 s22, s98, s20
	s_addc_u32 s23, s99, 0
	global_store_dwordx4 v151, v[60:63], s[22:23]
	global_store_dwordx4 v151, v[56:59], s[22:23] offset:16
	global_store_dwordx4 v151, v[52:55], s[22:23] offset:512
	global_store_dwordx4 v151, v[48:51], s[22:23] offset:528
.Lf3f_st_4:
	s_bitcmp1_b32 s19, 5
	s_cbranch_scc0 .Lf3f_st_5
	s_add_i32 s87, s21, 144
	s_mul_hi_u32 s89, s87, 0x7e07e07f
	s_lshr_b32 s89, s89, 11
	s_mul_i32 vcc_lo, s89, 0x1040
	s_sub_i32 vcc_lo, s87, vcc_lo
	s_add_i32 vcc_lo, vcc_lo, -16
	s_lshl_b32 s89, s89, 12
	s_add_i32 s89, s89, vcc_lo
	s_cmp_lt_u32 vcc_lo, 0x1000
	s_cselect_b32 vcc_hi, 1, 0
	s_sub_i32 vcc_lo, s87, 0x4100
	s_cmp_ge_u32 s94, 65
	s_cselect_b32 s89, vcc_lo, s89
	s_cselect_b32 vcc_hi, 1, vcc_hi
	s_cmp_lg_u32 vcc_hi, 0
	s_cselect_b32 s89, s89, 0
	s_lshl_b32 s20, s89, 12
	v_pk_mul_f32 v[32:33], v[202:203], v[32:33] op_sel_hi:[0,1]
	v_pk_mul_f32 v[34:35], v[202:203], v[34:35] op_sel_hi:[0,1]
	v_pk_mul_f32 v[36:37], v[202:203], v[36:37] op_sel_hi:[0,1]
	v_pk_mul_f32 v[38:39], v[202:203], v[38:39] op_sel_hi:[0,1]
	v_pk_mul_f32 v[40:41], v[202:203], v[40:41] op_sel_hi:[0,1]
	v_pk_mul_f32 v[42:43], v[202:203], v[42:43] op_sel_hi:[0,1]
	v_pk_mul_f32 v[44:45], v[202:203], v[44:45] op_sel_hi:[0,1]
	v_pk_mul_f32 v[46:47], v[202:203], v[46:47] op_sel_hi:[0,1]
	v_pk_mul_f32 v[44:45], v[176:177], v[44:45]
	v_pk_mul_f32 v[46:47], v[178:179], v[46:47]
	v_pk_mul_f32 v[40:41], v[180:181], v[40:41]
	v_pk_mul_f32 v[42:43], v[182:183], v[42:43]
	v_pk_mul_f32 v[36:37], v[184:185], v[36:37]
	v_pk_mul_f32 v[38:39], v[186:187], v[38:39]
	v_pk_mul_f32 v[32:33], v[188:189], v[32:33]
	v_pk_mul_f32 v[34:35], v[190:191], v[34:35]
	s_add_u32 s22, s98, s20
	s_addc_u32 s23, s99, 0
	global_store_dwordx4 v151, v[44:47], s[22:23]
	global_store_dwordx4 v151, v[40:43], s[22:23] offset:16
	global_store_dwordx4 v151, v[36:39], s[22:23] offset:512
	global_store_dwordx4 v151, v[32:35], s[22:23] offset:528
.Lf3f_st_5:
	s_bitcmp1_b32 s19, 6
	s_cbranch_scc0 .Lf3f_st_6
	s_add_i32 s87, s21, 160
	s_mul_hi_u32 s89, s87, 0x7e07e07f
	s_lshr_b32 s89, s89, 11
	s_mul_i32 vcc_lo, s89, 0x1040
	s_sub_i32 vcc_lo, s87, vcc_lo
	s_add_i32 vcc_lo, vcc_lo, -16
	s_lshl_b32 s89, s89, 12
	s_add_i32 s89, s89, vcc_lo
	s_cmp_lt_u32 vcc_lo, 0x1000
	s_cselect_b32 vcc_hi, 1, 0
	s_sub_i32 vcc_lo, s87, 0x4100
	s_cmp_ge_u32 s94, 65
	s_cselect_b32 s89, vcc_lo, s89
	s_cselect_b32 vcc_hi, 1, vcc_hi
	s_cmp_lg_u32 vcc_hi, 0
	s_cselect_b32 s89, s89, 0
	s_lshl_b32 s20, s89, 12
	v_pk_mul_f32 v[16:17], v[204:205], v[16:17] op_sel_hi:[0,1]
	v_pk_mul_f32 v[18:19], v[204:205], v[18:19] op_sel_hi:[0,1]
	v_pk_mul_f32 v[20:21], v[204:205], v[20:21] op_sel_hi:[0,1]
	v_pk_mul_f32 v[22:23], v[204:205], v[22:23] op_sel_hi:[0,1]
	v_pk_mul_f32 v[24:25], v[204:205], v[24:25] op_sel_hi:[0,1]
	v_pk_mul_f32 v[26:27], v[204:205], v[26:27] op_sel_hi:[0,1]
	v_pk_mul_f32 v[28:29], v[204:205], v[28:29] op_sel_hi:[0,1]
	v_pk_mul_f32 v[30:31], v[204:205], v[30:31] op_sel_hi:[0,1]
	v_pk_mul_f32 v[28:29], v[176:177], v[28:29]
	v_pk_mul_f32 v[30:31], v[178:179], v[30:31]
	v_pk_mul_f32 v[24:25], v[180:181], v[24:25]
	v_pk_mul_f32 v[26:27], v[182:183], v[26:27]
	v_pk_mul_f32 v[20:21], v[184:185], v[20:21]
	v_pk_mul_f32 v[22:23], v[186:187], v[22:23]
	v_pk_mul_f32 v[16:17], v[188:189], v[16:17]
	v_pk_mul_f32 v[18:19], v[190:191], v[18:19]
	s_add_u32 s22, s98, s20
	s_addc_u32 s23, s99, 0
	global_store_dwordx4 v151, v[28:31], s[22:23]
	global_store_dwordx4 v151, v[24:27], s[22:23] offset:16
	global_store_dwordx4 v151, v[20:23], s[22:23] offset:512
	global_store_dwordx4 v151, v[16:19], s[22:23] offset:528
; #define PG8_BAR __builtin_amdgcn_s_barrier()
; template <class Epi, class Sched, bool ALIGN_EPI = false, bool SP2 = false>
; __device__ __forceinline__ void gemm_phase(PG8_LAS unsigned char* lds, const Gemm g, const Sched& S, const Epi& E) {
;     ...
;         if constexpr (ALIGN_EPI) { if (wr == 0) PG8_BAR; }
;         if constexpr (!Epi::AFTER_DRAIN) { E(acc, cur, wr, wc, fr, fq); S.done(cur); }
;         if (!has_next) break;
; #pragma unroll
;         for (int a = 0; a < 2; ++a)
; #pragma unroll
;             for (int b = 0; b < 2; ++b)
; #pragma unroll
;                 for (int m = 0; m < 4; ++m)
; #pragma unroll
;                     for (int n = 0; n < 2; ++n) acc[a][b][m][n] = (f32x4){0.f, 0.f, 0.f, 0.f};
;         cur = nxt; cA = nA; cB = nB; ++ui;
;         if constexpr (ALIGN_EPI) { if (wr == 1) PG8_BAR; }
;     }
; __global__ void __launch_bounds__(512, 2) hymba_mega(Params p) {
;     ...
;             const float rstd = 1.0f / sqrtf(rs * (1.0f / 1024.0f) + EPS);
; #pragma unroll
;             for (int i = 0; i < 4; ++i) *(f32x4*)(yd + i * 256 + lane * 4) = v[i] * rstd * gq[i];
.Lf3f_st_6:
	s_bitcmp1_b32 s19, 7
	s_cbranch_scc0 .Lf3f_st_7
	s_add_i32 s87, s21, 176
	s_mul_hi_u32 s89, s87, 0x7e07e07f
	s_lshr_b32 s89, s89, 11
	s_mul_i32 vcc_lo, s89, 0x1040
	s_sub_i32 vcc_lo, s87, vcc_lo
	s_add_i32 vcc_lo, vcc_lo, -16
	s_lshl_b32 s89, s89, 12
	s_add_i32 s89, s89, vcc_lo
	s_cmp_lt_u32 vcc_lo, 0x1000
	s_cselect_b32 vcc_hi, 1, 0
	s_sub_i32 vcc_lo, s87, 0x4100
	s_cmp_ge_u32 s94, 65
	s_cselect_b32 s89, vcc_lo, s89
	s_cselect_b32 vcc_hi, 1, vcc_hi
	s_cmp_lg_u32 vcc_hi, 0
	s_cselect_b32 s89, s89, 0
	s_lshl_b32 s20, s89, 12
	v_pk_mul_f32 v[0:1], v[206:207], v[0:1] op_sel_hi:[0,1]
	v_pk_mul_f32 v[2:3], v[206:207], v[2:3] op_sel_hi:[0,1]
	v_pk_mul_f32 v[4:5], v[206:207], v[4:5] op_sel_hi:[0,1]
	v_pk_mul_f32 v[6:7], v[206:207], v[6:7] op_sel_hi:[0,1]
	v_pk_mul_f32 v[8:9], v[206:207], v[8:9] op_sel_hi:[0,1]
	v_pk_mul_f32 v[10:11], v[206:207], v[10:11] op_sel_hi:[0,1]
	v_pk_mul_f32 v[12:13], v[206:207], v[12:13] op_sel_hi:[0,1]
	v_pk_mul_f32 v[14:15], v[206:207], v[14:15] op_sel_hi:[0,1]
	v_pk_mul_f32 v[12:13], v[176:177], v[12:13]
	v_pk_mul_f32 v[14:15], v[178:179], v[14:15]
	v_pk_mul_f32 v[8:9], v[180:181], v[8:9]
	v_pk_mul_f32 v[10:11], v[182:183], v[10:11]
	v_pk_mul_f32 v[4:5], v[184:185], v[4:5]
	v_pk_mul_f32 v[6:7], v[186:187], v[6:7]
	v_pk_mul_f32 v[0:1], v[188:189], v[0:1]
	v_pk_mul_f32 v[2:3], v[190:191], v[2:3]
	s_add_u32 s22, s98, s20
	s_addc_u32 s23, s99, 0
	global_store_dwordx4 v151, v[12:15], s[22:23]
	global_store_dwordx4 v151, v[8:11], s[22:23] offset:16
	global_store_dwordx4 v151, v[4:7], s[22:23] offset:512
	global_store_dwordx4 v151, v[0:3], s[22:23] offset:528
.Lf3f_st_7:
.Lp3q_epi_done:
	s_andn2_b64 vcc, exec, s[38:39]
	s_mov_b64 s[38:39], -1
	s_cbranch_vccnz .LBB0_609
	s_andn2_b64 vcc, exec, s[72:73]
	s_cbranch_vccnz .LBB0_608
	s_barrier
	s_branch .LBB0_608
.Lp3q_epi:
	v_lshl_add_u32 v150, s94, 8, v158
	v_lshl_or_b32 v155, s42, 8, v159
	v_and_b32_e32 v151, 15, v158
	v_lshlrev_b32_e32 v155, 2, v155
	v_lshl_or_b32 v151, v151, 12, v155
	v_lshlrev_b32_e32 v152, 2, v150
	v_mov_b32_e32 v150, v155
	v_xor_b32_e32 v153, 16, v174
	v_xor_b32_e32 v154, 32, v174
	v_lshlrev_b32_e32 v153, 2, v153
	v_lshlrev_b32_e32 v154, 2, v154
	s_and_b64 s[20:21], s[72:73], exec
	s_cselect_b32 s20, 64, 0
	s_lshl_b32 s21, s94, 8
	s_add_i32 s21, s21, s20
	s_cmp_ge_u32 s94, 65
	s_cselect_b32 s96, s78, s76
	s_cselect_b32 s97, s79, s77
	s_cselect_b32 s98, s82, s54
	s_cselect_b32 s99, s83, s55
	s_mov_b32 s19, 0
	s_bitcmp1_b32 s100, 0
	s_cbranch_scc1 .Lp3q_v0
	s_bitcmp1_b32 s100, 1
	s_cbranch_scc1 .Lp3q_v1
	s_bitcmp1_b32 s100, 2
	s_cbranch_scc1 .Lp3q_v2
	s_branch .Lp3q_v3
;     DI void operator()(const f32x4 (&acc)[2][2][4][2], const pg8::Unit& u, int wr, int wc, int fr, int fq) const {
;     ...
;                 const int R = u.pm * 256 + ai * 128 + wr * 64 + m * 16 + fr;
;                 const float* xs = nullptr; float* yd = nullptr;
;                 if (R < ROWS_P) { const int b = R / LPAD, t = R - b * LPAD; if (t >= NMETA && t < LP) { const size_t idx = ((size_t)b * SEQ + t - NMETA) * DM; xs = p.x_prompt + idx; yd = p.out + O_YP + idx; } }
;                 else { const size_t idx = (size_t)(R - ROWS_P) * DM; xs = p.x_sample + idx; yd = p.out + O_YS + idx; }
;                 float ss = 0.f;
;                 if (xs) {
; #pragma unroll
;                     for (int bj = 0; bj < 2; ++bj) {
;                         const int n = colt + bj * 128 + wc * 32 + 8 * fq;
;                         const f32x4 x0 = *(const f32x4*)(xs + n), x1 = *(const f32x4*)(xs + n + 4);
;                         const f32x4 h0 = x0 + acc[ai][bj][m][0], h1 = x1 + acc[ai][bj][m][1];
;                         *(f32x4*)(yd + n) = h0; *(f32x4*)(yd + n + 4) = h1;
;                         ss += h0[0] * h0[0] + h0[1] * h0[1] + h0[2] * h0[2] + h0[3] * h0[3] + h1[0] * h1[0] + h1[1] * h1[1] + h1[2] * h1[2] + h1[3] * h1[3];
;                     }
;                 }
;                 ss += __shfl_xor(ss, 16); ss += __shfl_xor(ss, 32);
;                 if (xs && fq == 0) atomicAdd(p.rowss + R, ss);
.Lp3q_v0:
	s_add_i32 s87, s21, 0
	s_mul_hi_u32 s89, s87, 0x7e07e07f
	s_lshr_b32 s89, s89, 11
	s_mul_i32 vcc_lo, s89, 0x1040
	s_sub_i32 vcc_lo, s87, vcc_lo
	s_add_i32 vcc_lo, vcc_lo, -16
	s_lshl_b32 s89, s89, 12
	s_add_i32 s89, s89, vcc_lo
	s_cmp_lt_u32 vcc_lo, 0x1000
	s_cselect_b32 vcc_hi, 1, 0
	s_sub_i32 vcc_lo, s87, 0x4100
	s_cmp_ge_u32 s94, 65
	s_cselect_b32 s89, vcc_lo, s89
	s_cselect_b32 vcc_hi, 1, vcc_hi
	s_cmp_lg_u32 vcc_hi, 0
	s_cselect_b32 s89, s89, 0
	s_lshl_b32 s20, s89, 12
	s_lshl_b32 vcc_hi, vcc_hi, 0
	s_or_b32 s19, s19, vcc_hi
	s_add_u32 s22, s96, s20
	s_addc_u32 s23, s97, 0
	global_load_dwordx4 v[176:179], v151, s[22:23]
	global_load_dwordx4 v[180:183], v151, s[22:23] offset:16
	s_add_i32 s87, s21, 16
	s_mul_hi_u32 s89, s87, 0x7e07e07f
	s_lshr_b32 s89, s89, 11
	s_mul_i32 vcc_lo, s89, 0x1040
	s_sub_i32 vcc_lo, s87, vcc_lo
	s_add_i32 vcc_lo, vcc_lo, -16
	s_lshl_b32 s89, s89, 12
	s_add_i32 s89, s89, vcc_lo
	s_cmp_lt_u32 vcc_lo, 0x1000
	s_cselect_b32 vcc_hi, 1, 0
	s_sub_i32 vcc_lo, s87, 0x4100
	s_cmp_ge_u32 s94, 65
	s_cselect_b32 s89, vcc_lo, s89
	s_cselect_b32 vcc_hi, 1, vcc_hi
	s_cmp_lg_u32 vcc_hi, 0
	s_cselect_b32 s89, s89, 0
	s_lshl_b32 s42, s89, 12
	s_lshl_b32 vcc_hi, vcc_hi, 1
	s_or_b32 s19, s19, vcc_hi
	s_add_u32 s22, s96, s42
	s_addc_u32 s23, s97, 0
	global_load_dwordx4 v[184:187], v151, s[22:23]
	global_load_dwordx4 v[188:191], v151, s[22:23] offset:16
	s_add_i32 s87, s21, 32
	s_mul_hi_u32 s89, s87, 0x7e07e07f
	s_lshr_b32 s89, s89, 11
	s_mul_i32 vcc_lo, s89, 0x1040
	s_sub_i32 vcc_lo, s87, vcc_lo
	s_add_i32 vcc_lo, vcc_lo, -16
	s_lshl_b32 s89, s89, 12
	s_add_i32 s89, s89, vcc_lo
	s_cmp_lt_u32 vcc_lo, 0x1000
	s_cselect_b32 vcc_hi, 1, 0
	s_sub_i32 vcc_lo, s87, 0x4100
	s_cmp_ge_u32 s94, 65
	s_cselect_b32 s89, vcc_lo, s89
	s_cselect_b32 vcc_hi, 1, vcc_hi
	s_cmp_lg_u32 vcc_hi, 0
	s_cselect_b32 s89, s89, 0
	s_lshl_b32 s43, s89, 12
	s_lshl_b32 vcc_hi, vcc_hi, 2
	s_or_b32 s19, s19, vcc_hi
	s_add_u32 s22, s96, s43
	s_addc_u32 s23, s97, 0
	global_load_dwordx4 v[192:195], v151, s[22:23]
	global_load_dwordx4 v[196:199], v151, s[22:23] offset:16
	s_add_i32 s87, s21, 48
	s_mul_hi_u32 s89, s87, 0x7e07e07f
	s_lshr_b32 s89, s89, 11
	s_mul_i32 vcc_lo, s89, 0x1040
	s_sub_i32 vcc_lo, s87, vcc_lo
	s_add_i32 vcc_lo, vcc_lo, -16
	s_lshl_b32 s89, s89, 12
	s_add_i32 s89, s89, vcc_lo
	s_cmp_lt_u32 vcc_lo, 0x1000
	s_cselect_b32 vcc_hi, 1, 0
	s_sub_i32 vcc_lo, s87, 0x4100
	s_cmp_ge_u32 s94, 65
	s_cselect_b32 s89, vcc_lo, s89
	s_cselect_b32 vcc_hi, 1, vcc_hi
	s_cmp_lg_u32 vcc_hi, 0
	s_cselect_b32 s89, s89, 0
	s_lshl_b32 s95, s89, 12
	s_lshl_b32 vcc_hi, vcc_hi, 3
	s_or_b32 s19, s19, vcc_hi
	s_add_u32 s22, s96, s95
	s_addc_u32 s23, s97, 0
	global_load_dwordx4 v[200:203], v151, s[22:23]
	global_load_dwordx4 v[204:207], v151, s[22:23] offset:16
	s_waitcnt vmcnt(0)
	v_pk_add_f32 v[124:125], v[124:125], v[176:177]
	v_pk_add_f32 v[126:127], v[126:127], v[178:179]
	v_pk_add_f32 v[120:121], v[120:121], v[180:181]
	v_pk_add_f32 v[122:123], v[122:123], v[182:183]
	v_pk_mul_f32 v[172:173], v[124:125], v[124:125]
	v_pk_fma_f32 v[172:173], v[126:127], v[126:127], v[172:173]
	v_pk_fma_f32 v[172:173], v[120:121], v[120:121], v[172:173]
	v_pk_fma_f32 v[172:173], v[122:123], v[122:123], v[172:173]
	s_nop 0
	v_add_f32_e32 v168, v172, v173
	v_pk_add_f32 v[108:109], v[108:109], v[184:185]
	v_pk_add_f32 v[110:111], v[110:111], v[186:187]
	v_pk_add_f32 v[104:105], v[104:105], v[188:189]
	v_pk_add_f32 v[106:107], v[106:107], v[190:191]
	v_pk_mul_f32 v[172:173], v[108:109], v[108:109]
	v_pk_fma_f32 v[172:173], v[110:111], v[110:111], v[172:173]
	v_pk_fma_f32 v[172:173], v[104:105], v[104:105], v[172:173]
	v_pk_fma_f32 v[172:173], v[106:107], v[106:107], v[172:173]
	s_nop 0
	v_add_f32_e32 v169, v172, v173
	v_pk_add_f32 v[92:93], v[92:93], v[192:193]
	v_pk_add_f32 v[94:95], v[94:95], v[194:195]
	v_pk_add_f32 v[88:89], v[88:89], v[196:197]
	v_pk_add_f32 v[90:91], v[90:91], v[198:199]
	v_pk_mul_f32 v[172:173], v[92:93], v[92:93]
	v_pk_fma_f32 v[172:173], v[94:95], v[94:95], v[172:173]
	v_pk_fma_f32 v[172:173], v[88:89], v[88:89], v[172:173]
	v_pk_fma_f32 v[172:173], v[90:91], v[90:91], v[172:173]
	s_nop 0
	v_add_f32_e32 v170, v172, v173
	v_pk_add_f32 v[76:77], v[76:77], v[200:201]
	v_pk_add_f32 v[78:79], v[78:79], v[202:203]
	v_pk_add_f32 v[72:73], v[72:73], v[204:205]
	v_pk_add_f32 v[74:75], v[74:75], v[206:207]
	v_pk_mul_f32 v[172:173], v[76:77], v[76:77]
	v_pk_fma_f32 v[172:173], v[78:79], v[78:79], v[172:173]
	v_pk_fma_f32 v[172:173], v[72:73], v[72:73], v[172:173]
	v_pk_fma_f32 v[172:173], v[74:75], v[74:75], v[172:173]
	s_nop 0
	v_add_f32_e32 v171, v172, v173
	ds_bpermute_b32 v155, v153, v168
	ds_bpermute_b32 v156, v153, v169
	ds_bpermute_b32 v157, v153, v170
	ds_bpermute_b32 v132, v153, v171
	s_waitcnt lgkmcnt(0)
	v_add_f32_e32 v168, v168, v155
	v_add_f32_e32 v169, v169, v156
	v_add_f32_e32 v170, v170, v157
	v_add_f32_e32 v171, v171, v132
	ds_bpermute_b32 v155, v154, v168
	ds_bpermute_b32 v156, v154, v169
	ds_bpermute_b32 v157, v154, v170
	ds_bpermute_b32 v132, v154, v171
	s_waitcnt lgkmcnt(0)
	v_add_f32_e32 v168, v168, v155
	v_add_f32_e32 v169, v169, v156
	v_add_f32_e32 v170, v170, v157
	v_add_f32_e32 v171, v171, v132
	s_mov_b64 exec, s[36:37]
	s_bitcmp1_b32 s19, 0
	s_cbranch_scc0 .Lf3q0_at_q_0
	global_atomic_add_f32 v152, v168, s[60:61]

;     DI void operator()(const f32x4 (&acc)[2][2][4][2], const pg8::Unit& u, int wr, int wc, int fr, int fq) const {
;     ...
;                 ss += __shfl_xor(ss, 16); ss += __shfl_xor(ss, 32);
;                 if (xs && fq == 0) atomicAdd(p.rowss + R, ss);
.Lf3q0_at_q_3:
	s_mov_b64 exec, -1
	v_mov_b32_e32 v209, 0
	v_mov_b32_e32 v210, 1
	s_lshl_b32 s22, s94, 2
	s_add_i32 s22, s22, 96
	v_mov_b32_e32 v211, s22
	s_waitcnt vmcnt(0)
	s_barrier
	global_load_dwordx4 v[176:179], v150, s[52:53]
	global_load_dwordx4 v[180:183], v150, s[52:53] offset:16
	global_load_dwordx4 v[184:187], v150, s[52:53] offset:512
	global_load_dwordx4 v[188:191], v150, s[52:53] offset:528
	v_and_b32_e32 v208, 15, v174
	v_lshlrev_b32_e32 v208, 2, v208
	v_mov_b32_e32 v218, 0x358637bd
	v_mov_b32_e32 v219, 0x260
	s_movk_i32 s23, 16
	s_and_saveexec_b64 vcc, s[40:41]
	s_cbranch_execz .Lf3q0_go_q
	global_atomic_add v211, v210, s[56:57]

; __global__ void __launch_bounds__(512, 2) hymba_mega(Params p) {
;     ...
;             const float rstd = 1.0f / sqrtf(rs * (1.0f / 1024.0f) + EPS);
; #pragma unroll
;             for (int i = 0; i < 4; ++i) *(f32x4*)(yd + i * 256 + lane * 4) = v[i] * rstd * gq[i];
.Lf3q0_go_q:
	s_or_b64 exec, exec, vcc
	s_barrier
	s_mov_b64 exec, s[36:37]
	global_atomic_add_f32 v192, v152, v209, s[60:61] sc0
	global_atomic_add_f32 v194, v152, v209, s[60:61] offset:64 sc0
	global_atomic_add_f32 v196, v152, v209, s[60:61] offset:128 sc0
	global_atomic_add_f32 v198, v152, v209, s[60:61] offset:192 sc0
	s_mov_b64 exec, -1
	s_waitcnt vmcnt(0)
	ds_bpermute_b32 v192, v208, v192
	ds_bpermute_b32 v194, v208, v194
	ds_bpermute_b32 v196, v208, v196
	ds_bpermute_b32 v198, v208, v198
	s_waitcnt lgkmcnt(0)
	v_fmamk_f32 v213, v192, 0x3a800000, v218
	v_mul_f32_e32 v214, 0x4f800000, v213
	v_cmp_gt_f32_e32 vcc, 0xf800000, v213
	s_nop 1
	v_cndmask_b32_e32 v213, v213, v214, vcc
	v_sqrt_f32_e32 v214, v213
	s_nop 0
	v_add_u32_e32 v215, -1, v214
	v_fma_f32 v217, -v215, v214, v213
	v_add_u32_e32 v216, 1, v214
	v_cmp_ge_f32_e64 s[22:23], 0, v217
	s_nop 1
	v_cndmask_b32_e64 v215, v214, v215, s[22:23]
	v_fma_f32 v214, -v216, v214, v213
	v_cmp_lt_f32_e64 s[22:23], 0, v214
	s_nop 1
	v_cndmask_b32_e64 v214, v215, v216, s[22:23]
	v_mul_f32_e32 v215, 0x37800000, v214
	v_cndmask_b32_e32 v214, v214, v215, vcc
	v_cmp_class_f32_e32 vcc, v213, v219
	s_nop 1
	v_cndmask_b32_e32 v213, v214, v213, vcc
	v_div_scale_f32 v214, s[22:23], v213, v213, 1.0
	v_rcp_f32_e32 v215, v214
	s_nop 0
	v_fma_f32 v216, -v214, v215, 1.0
	v_fmac_f32_e32 v215, v216, v215
	v_div_scale_f32 v216, vcc, 1.0, v213, 1.0
	v_mul_f32_e32 v217, v216, v215
	v_fma_f32 v192, -v214, v217, v216
	v_fmac_f32_e32 v217, v192, v215
	v_fma_f32 v214, -v214, v217, v216
	s_nop 0
	v_div_fmas_f32 v214, v214, v215, v217
	v_div_fixup_f32 v192, v214, v213, 1.0
	v_fmamk_f32 v213, v194, 0x3a800000, v218
	v_mul_f32_e32 v214, 0x4f800000, v213
	v_cmp_gt_f32_e32 vcc, 0xf800000, v213
	s_nop 1
	v_cndmask_b32_e32 v213, v213, v214, vcc
	v_sqrt_f32_e32 v214, v213
	s_nop 0
	v_add_u32_e32 v215, -1, v214
	v_fma_f32 v217, -v215, v214, v213
	v_add_u32_e32 v216, 1, v214
	v_cmp_ge_f32_e64 s[22:23], 0, v217
	s_nop 1
	v_cndmask_b32_e64 v215, v214, v215, s[22:23]
	v_fma_f32 v214, -v216, v214, v213
	v_cmp_lt_f32_e64 s[22:23], 0, v214
	s_nop 1
	v_cndmask_b32_e64 v214, v215, v216, s[22:23]
	v_mul_f32_e32 v215, 0x37800000, v214
	v_cndmask_b32_e32 v214, v214, v215, vcc
	v_cmp_class_f32_e32 vcc, v213, v219
	s_nop 1
	v_cndmask_b32_e32 v213, v214, v213, vcc
	v_div_scale_f32 v214, s[22:23], v213, v213, 1.0
	v_rcp_f32_e32 v215, v214
	s_nop 0
	v_fma_f32 v216, -v214, v215, 1.0
	v_fmac_f32_e32 v215, v216, v215
	v_div_scale_f32 v216, vcc, 1.0, v213, 1.0
	v_mul_f32_e32 v217, v216, v215
	v_fma_f32 v194, -v214, v217, v216
	v_fmac_f32_e32 v217, v194, v215
	v_fma_f32 v214, -v214, v217, v216
	s_nop 0
	v_div_fmas_f32 v214, v214, v215, v217
	v_div_fixup_f32 v194, v214, v213, 1.0
	v_fmamk_f32 v213, v196, 0x3a800000, v218
	v_mul_f32_e32 v214, 0x4f800000, v213
	v_cmp_gt_f32_e32 vcc, 0xf800000, v213
	s_nop 1
	v_cndmask_b32_e32 v213, v213, v214, vcc
	v_sqrt_f32_e32 v214, v213
	s_nop 0
	v_add_u32_e32 v215, -1, v214
	v_fma_f32 v217, -v215, v214, v213
	v_add_u32_e32 v216, 1, v214
	v_cmp_ge_f32_e64 s[22:23], 0, v217
	s_nop 1
	v_cndmask_b32_e64 v215, v214, v215, s[22:23]
	v_fma_f32 v214, -v216, v214, v213
	v_cmp_lt_f32_e64 s[22:23], 0, v214
	s_nop 1
	v_cndmask_b32_e64 v214, v215, v216, s[22:23]
	v_mul_f32_e32 v215, 0x37800000, v214
	v_cndmask_b32_e32 v214, v214, v215, vcc
	v_cmp_class_f32_e32 vcc, v213, v219
	s_nop 1
	v_cndmask_b32_e32 v213, v214, v213, vcc
	v_div_scale_f32 v214, s[22:23], v213, v213, 1.0
	v_rcp_f32_e32 v215, v214
	s_nop 0
	v_fma_f32 v216, -v214, v215, 1.0
	v_fmac_f32_e32 v215, v216, v215
	v_div_scale_f32 v216, vcc, 1.0, v213, 1.0
	v_mul_f32_e32 v217, v216, v215
	v_fma_f32 v196, -v214, v217, v216
	v_fmac_f32_e32 v217, v196, v215
	v_fma_f32 v214, -v214, v217, v216
	s_nop 0
	v_div_fmas_f32 v214, v214, v215, v217
	v_div_fixup_f32 v196, v214, v213, 1.0
	v_fmamk_f32 v213, v198, 0x3a800000, v218
	v_mul_f32_e32 v214, 0x4f800000, v213
	v_cmp_gt_f32_e32 vcc, 0xf800000, v213
	s_nop 1
	v_cndmask_b32_e32 v213, v213, v214, vcc
	v_sqrt_f32_e32 v214, v213
	s_nop 0
	v_add_u32_e32 v215, -1, v214
	v_fma_f32 v217, -v215, v214, v213
	v_add_u32_e32 v216, 1, v214
	v_cmp_ge_f32_e64 s[22:23], 0, v217
	s_nop 1
	v_cndmask_b32_e64 v215, v214, v215, s[22:23]
	v_fma_f32 v214, -v216, v214, v213
	v_cmp_lt_f32_e64 s[22:23], 0, v214
	s_nop 1
	v_cndmask_b32_e64 v214, v215, v216, s[22:23]
	v_mul_f32_e32 v215, 0x37800000, v214
	v_cndmask_b32_e32 v214, v214, v215, vcc
	v_cmp_class_f32_e32 vcc, v213, v219
	s_nop 1
	v_cndmask_b32_e32 v213, v214, v213, vcc
	v_div_scale_f32 v214, s[22:23], v213, v213, 1.0
	v_rcp_f32_e32 v215, v214
	s_nop 0
	v_fma_f32 v216, -v214, v215, 1.0
	v_fmac_f32_e32 v215, v216, v215
	v_div_scale_f32 v216, vcc, 1.0, v213, 1.0
	v_mul_f32_e32 v217, v216, v215
	v_fma_f32 v198, -v214, v217, v216
	v_fmac_f32_e32 v217, v198, v215
	v_fma_f32 v214, -v214, v217, v216
	s_nop 0
	v_div_fmas_f32 v214, v214, v215, v217
	v_div_fixup_f32 v198, v214, v213, 1.0
	s_bitcmp1_b32 s19, 0
	s_cbranch_scc0 .Lf3q0_st_0
	s_add_i32 s87, s21, 0
	s_mul_hi_u32 s89, s87, 0x7e07e07f
	s_lshr_b32 s89, s89, 11
	s_mul_i32 vcc_lo, s89, 0x1040
	s_sub_i32 vcc_lo, s87, vcc_lo
	s_add_i32 vcc_lo, vcc_lo, -16
	s_lshl_b32 s89, s89, 12
	s_add_i32 s89, s89, vcc_lo
	s_cmp_lt_u32 vcc_lo, 0x1000
	s_cselect_b32 vcc_hi, 1, 0
	s_sub_i32 vcc_lo, s87, 0x4100
	s_cmp_ge_u32 s94, 65
	s_cselect_b32 s89, vcc_lo, s89
	s_cselect_b32 vcc_hi, 1, vcc_hi
	s_cmp_lg_u32 vcc_hi, 0
	s_cselect_b32 s89, s89, 0
	s_lshl_b32 s20, s89, 12
	v_pk_mul_f32 v[124:125], v[192:193], v[124:125] op_sel_hi:[0,1]
	v_pk_mul_f32 v[126:127], v[192:193], v[126:127] op_sel_hi:[0,1]
	v_pk_mul_f32 v[120:121], v[192:193], v[120:121] op_sel_hi:[0,1]
	v_pk_mul_f32 v[122:123], v[192:193], v[122:123] op_sel_hi:[0,1]
	v_pk_mul_f32 v[124:125], v[176:177], v[124:125]
	v_pk_mul_f32 v[126:127], v[178:179], v[126:127]
	v_pk_mul_f32 v[120:121], v[180:181], v[120:121]
	v_pk_mul_f32 v[122:123], v[182:183], v[122:123]
	s_add_u32 s22, s98, s20
	s_addc_u32 s23, s99, 0
	global_store_dwordx4 v151, v[124:127], s[22:23]
	global_store_dwordx4 v151, v[120:123], s[22:23] offset:16
; __global__ void __launch_bounds__(512, 2) hymba_mega(Params p) {
;     ...
;             const float rstd = 1.0f / sqrtf(rs * (1.0f / 1024.0f) + EPS);
; #pragma unroll
;             for (int i = 0; i < 4; ++i) *(f32x4*)(yd + i * 256 + lane * 4) = v[i] * rstd * gq[i];
.Lf3q0_st_0:
	s_bitcmp1_b32 s19, 1
	s_cbranch_scc0 .Lf3q0_st_1
	s_add_i32 s87, s21, 16
	s_mul_hi_u32 s89, s87, 0x7e07e07f
	s_lshr_b32 s89, s89, 11
	s_mul_i32 vcc_lo, s89, 0x1040
	s_sub_i32 vcc_lo, s87, vcc_lo
	s_add_i32 vcc_lo, vcc_lo, -16
	s_lshl_b32 s89, s89, 12
	s_add_i32 s89, s89, vcc_lo
	s_cmp_lt_u32 vcc_lo, 0x1000
	s_cselect_b32 vcc_hi, 1, 0
	s_sub_i32 vcc_lo, s87, 0x4100
	s_cmp_ge_u32 s94, 65
	s_cselect_b32 s89, vcc_lo, s89
	s_cselect_b32 vcc_hi, 1, vcc_hi
	s_cmp_lg_u32 vcc_hi, 0
	s_cselect_b32 s89, s89, 0
	s_lshl_b32 s20, s89, 12
	v_pk_mul_f32 v[108:109], v[194:195], v[108:109] op_sel_hi:[0,1]
	v_pk_mul_f32 v[110:111], v[194:195], v[110:111] op_sel_hi:[0,1]
	v_pk_mul_f32 v[104:105], v[194:195], v[104:105] op_sel_hi:[0,1]
	v_pk_mul_f32 v[106:107], v[194:195], v[106:107] op_sel_hi:[0,1]
	v_pk_mul_f32 v[108:109], v[176:177], v[108:109]
	v_pk_mul_f32 v[110:111], v[178:179], v[110:111]
	v_pk_mul_f32 v[104:105], v[180:181], v[104:105]
	v_pk_mul_f32 v[106:107], v[182:183], v[106:107]
	s_add_u32 s22, s98, s20
	s_addc_u32 s23, s99, 0
	global_store_dwordx4 v151, v[108:111], s[22:23]
	global_store_dwordx4 v151, v[104:107], s[22:23] offset:16
.Lf3q0_st_1:
	s_bitcmp1_b32 s19, 2
	s_cbranch_scc0 .Lf3q0_st_2
	s_add_i32 s87, s21, 32
	s_mul_hi_u32 s89, s87, 0x7e07e07f
	s_lshr_b32 s89, s89, 11
	s_mul_i32 vcc_lo, s89, 0x1040
	s_sub_i32 vcc_lo, s87, vcc_lo
	s_add_i32 vcc_lo, vcc_lo, -16
	s_lshl_b32 s89, s89, 12
	s_add_i32 s89, s89, vcc_lo
	s_cmp_lt_u32 vcc_lo, 0x1000
	s_cselect_b32 vcc_hi, 1, 0
	s_sub_i32 vcc_lo, s87, 0x4100
	s_cmp_ge_u32 s94, 65
	s_cselect_b32 s89, vcc_lo, s89
	s_cselect_b32 vcc_hi, 1, vcc_hi
	s_cmp_lg_u32 vcc_hi, 0
	s_cselect_b32 s89, s89, 0
	s_lshl_b32 s20, s89, 12
	v_pk_mul_f32 v[92:93], v[196:197], v[92:93] op_sel_hi:[0,1]
	v_pk_mul_f32 v[94:95], v[196:197], v[94:95] op_sel_hi:[0,1]
	v_pk_mul_f32 v[88:89], v[196:197], v[88:89] op_sel_hi:[0,1]
	v_pk_mul_f32 v[90:91], v[196:197], v[90:91] op_sel_hi:[0,1]
	v_pk_mul_f32 v[92:93], v[176:177], v[92:93]
	v_pk_mul_f32 v[94:95], v[178:179], v[94:95]
	v_pk_mul_f32 v[88:89], v[180:181], v[88:89]
	v_pk_mul_f32 v[90:91], v[182:183], v[90:91]
	s_add_u32 s22, s98, s20
	s_addc_u32 s23, s99, 0
	global_store_dwordx4 v151, v[92:95], s[22:23]
	global_store_dwordx4 v151, v[88:91], s[22:23] offset:16
.Lf3q0_st_2:
	s_bitcmp1_b32 s19, 3
	s_cbranch_scc0 .Lf3q0_st_3
	s_add_i32 s87, s21, 48
	s_mul_hi_u32 s89, s87, 0x7e07e07f
	s_lshr_b32 s89, s89, 11
	s_mul_i32 vcc_lo, s89, 0x1040
	s_sub_i32 vcc_lo, s87, vcc_lo
	s_add_i32 vcc_lo, vcc_lo, -16
	s_lshl_b32 s89, s89, 12
	s_add_i32 s89, s89, vcc_lo
	s_cmp_lt_u32 vcc_lo, 0x1000
	s_cselect_b32 vcc_hi, 1, 0
	s_sub_i32 vcc_lo, s87, 0x4100
	s_cmp_ge_u32 s94, 65
	s_cselect_b32 s89, vcc_lo, s89
	s_cselect_b32 vcc_hi, 1, vcc_hi
	s_cmp_lg_u32 vcc_hi, 0
	s_cselect_b32 s89, s89, 0
	s_lshl_b32 s20, s89, 12
	v_pk_mul_f32 v[76:77], v[198:199], v[76:77] op_sel_hi:[0,1]
	v_pk_mul_f32 v[78:79], v[198:199], v[78:79] op_sel_hi:[0,1]
	v_pk_mul_f32 v[72:73], v[198:199], v[72:73] op_sel_hi:[0,1]
	v_pk_mul_f32 v[74:75], v[198:199], v[74:75] op_sel_hi:[0,1]
	v_pk_mul_f32 v[76:77], v[176:177], v[76:77]
	v_pk_mul_f32 v[78:79], v[178:179], v[78:79]
	v_pk_mul_f32 v[72:73], v[180:181], v[72:73]
	v_pk_mul_f32 v[74:75], v[182:183], v[74:75]
	s_add_u32 s22, s98, s20
	s_addc_u32 s23, s99, 0
	global_store_dwordx4 v151, v[76:79], s[22:23]
	global_store_dwordx4 v151, v[72:75], s[22:23] offset:16

;     DI void operator()(const f32x4 (&acc)[2][2][4][2], const pg8::Unit& u, int wr, int wc, int fr, int fq) const {
;     ...
;                 const int R = u.pm * 256 + ai * 128 + wr * 64 + m * 16 + fr;
;                 const float* xs = nullptr; float* yd = nullptr;
;                 if (R < ROWS_P) { const int b = R / LPAD, t = R - b * LPAD; if (t >= NMETA && t < LP) { const size_t idx = ((size_t)b * SEQ + t - NMETA) * DM; xs = p.x_prompt + idx; yd = p.out + O_YP + idx; } }
;                 else { const size_t idx = (size_t)(R - ROWS_P) * DM; xs = p.x_sample + idx; yd = p.out + O_YS + idx; }
;                 float ss = 0.f;
;                 if (xs) {
; #pragma unroll
;                     for (int bj = 0; bj < 2; ++bj) {
;                         const int n = colt + bj * 128 + wc * 32 + 8 * fq;
;                         const f32x4 x0 = *(const f32x4*)(xs + n), x1 = *(const f32x4*)(xs + n + 4);
;                         const f32x4 h0 = x0 + acc[ai][bj][m][0], h1 = x1 + acc[ai][bj][m][1];
;                         *(f32x4*)(yd + n) = h0; *(f32x4*)(yd + n + 4) = h1;
;                         ss += h0[0] * h0[0] + h0[1] * h0[1] + h0[2] * h0[2] + h0[3] * h0[3] + h1[0] * h1[0] + h1[1] * h1[1] + h1[2] * h1[2] + h1[3] * h1[3];
;                     }
;                 }
;                 ss += __shfl_xor(ss, 16); ss += __shfl_xor(ss, 32);
;                 if (xs && fq == 0) atomicAdd(p.rowss + R, ss);
.Lp3q_v1:
	s_add_i32 s87, s21, 0
	s_mul_hi_u32 s89, s87, 0x7e07e07f
	s_lshr_b32 s89, s89, 11
	s_mul_i32 vcc_lo, s89, 0x1040
	s_sub_i32 vcc_lo, s87, vcc_lo
	s_add_i32 vcc_lo, vcc_lo, -16
	s_lshl_b32 s89, s89, 12
	s_add_i32 s89, s89, vcc_lo
	s_cmp_lt_u32 vcc_lo, 0x1000
	s_cselect_b32 vcc_hi, 1, 0
	s_sub_i32 vcc_lo, s87, 0x4100
	s_cmp_ge_u32 s94, 65
	s_cselect_b32 s89, vcc_lo, s89
	s_cselect_b32 vcc_hi, 1, vcc_hi
	s_cmp_lg_u32 vcc_hi, 0
	s_cselect_b32 s89, s89, 0
	s_lshl_b32 s20, s89, 12
	s_lshl_b32 vcc_hi, vcc_hi, 0
	s_or_b32 s19, s19, vcc_hi
	s_add_u32 s22, s96, s20
	s_addc_u32 s23, s97, 0
	global_load_dwordx4 v[176:179], v151, s[22:23] offset:512
	global_load_dwordx4 v[180:183], v151, s[22:23] offset:528
	s_add_i32 s87, s21, 16
	s_mul_hi_u32 s89, s87, 0x7e07e07f
	s_lshr_b32 s89, s89, 11
	s_mul_i32 vcc_lo, s89, 0x1040
	s_sub_i32 vcc_lo, s87, vcc_lo
	s_add_i32 vcc_lo, vcc_lo, -16
	s_lshl_b32 s89, s89, 12
	s_add_i32 s89, s89, vcc_lo
	s_cmp_lt_u32 vcc_lo, 0x1000
	s_cselect_b32 vcc_hi, 1, 0
	s_sub_i32 vcc_lo, s87, 0x4100
	s_cmp_ge_u32 s94, 65
	s_cselect_b32 s89, vcc_lo, s89
	s_cselect_b32 vcc_hi, 1, vcc_hi
	s_cmp_lg_u32 vcc_hi, 0
	s_cselect_b32 s89, s89, 0
	s_lshl_b32 s42, s89, 12
	s_lshl_b32 vcc_hi, vcc_hi, 1
	s_or_b32 s19, s19, vcc_hi
	s_add_u32 s22, s96, s42
	s_addc_u32 s23, s97, 0
	global_load_dwordx4 v[184:187], v151, s[22:23] offset:512
	global_load_dwordx4 v[188:191], v151, s[22:23] offset:528
	s_add_i32 s87, s21, 32
	s_mul_hi_u32 s89, s87, 0x7e07e07f
	s_lshr_b32 s89, s89, 11
	s_mul_i32 vcc_lo, s89, 0x1040
	s_sub_i32 vcc_lo, s87, vcc_lo
	s_add_i32 vcc_lo, vcc_lo, -16
	s_lshl_b32 s89, s89, 12
	s_add_i32 s89, s89, vcc_lo
	s_cmp_lt_u32 vcc_lo, 0x1000
	s_cselect_b32 vcc_hi, 1, 0
	s_sub_i32 vcc_lo, s87, 0x4100
	s_cmp_ge_u32 s94, 65
	s_cselect_b32 s89, vcc_lo, s89
	s_cselect_b32 vcc_hi, 1, vcc_hi
	s_cmp_lg_u32 vcc_hi, 0
	s_cselect_b32 s89, s89, 0
	s_lshl_b32 s43, s89, 12
	s_lshl_b32 vcc_hi, vcc_hi, 2
	s_or_b32 s19, s19, vcc_hi
	s_add_u32 s22, s96, s43
	s_addc_u32 s23, s97, 0
	global_load_dwordx4 v[192:195], v151, s[22:23] offset:512
	global_load_dwordx4 v[196:199], v151, s[22:23] offset:528
	s_add_i32 s87, s21, 48
	s_mul_hi_u32 s89, s87, 0x7e07e07f
	s_lshr_b32 s89, s89, 11
	s_mul_i32 vcc_lo, s89, 0x1040
	s_sub_i32 vcc_lo, s87, vcc_lo
	s_add_i32 vcc_lo, vcc_lo, -16
	s_lshl_b32 s89, s89, 12
	s_add_i32 s89, s89, vcc_lo
	s_cmp_lt_u32 vcc_lo, 0x1000
	s_cselect_b32 vcc_hi, 1, 0
	s_sub_i32 vcc_lo, s87, 0x4100
	s_cmp_ge_u32 s94, 65
	s_cselect_b32 s89, vcc_lo, s89
	s_cselect_b32 vcc_hi, 1, vcc_hi
	s_cmp_lg_u32 vcc_hi, 0
	s_cselect_b32 s89, s89, 0
	s_lshl_b32 s95, s89, 12
	s_lshl_b32 vcc_hi, vcc_hi, 3
	s_or_b32 s19, s19, vcc_hi
	s_add_u32 s22, s96, s95
	s_addc_u32 s23, s97, 0
	global_load_dwordx4 v[200:203], v151, s[22:23] offset:512
	global_load_dwordx4 v[204:207], v151, s[22:23] offset:528
	s_waitcnt vmcnt(0)
	v_pk_add_f32 v[116:117], v[116:117], v[176:177]
	v_pk_add_f32 v[118:119], v[118:119], v[178:179]
	v_pk_add_f32 v[112:113], v[112:113], v[180:181]
	v_pk_add_f32 v[114:115], v[114:115], v[182:183]
	v_pk_mul_f32 v[172:173], v[116:117], v[116:117]
	v_pk_fma_f32 v[172:173], v[118:119], v[118:119], v[172:173]
	v_pk_fma_f32 v[172:173], v[112:113], v[112:113], v[172:173]
	v_pk_fma_f32 v[172:173], v[114:115], v[114:115], v[172:173]
	s_nop 0
	v_add_f32_e32 v168, v172, v173
	v_pk_add_f32 v[100:101], v[100:101], v[184:185]
	v_pk_add_f32 v[102:103], v[102:103], v[186:187]
	v_pk_add_f32 v[96:97], v[96:97], v[188:189]
	v_pk_add_f32 v[98:99], v[98:99], v[190:191]
	v_pk_mul_f32 v[172:173], v[100:101], v[100:101]
	v_pk_fma_f32 v[172:173], v[102:103], v[102:103], v[172:173]
	v_pk_fma_f32 v[172:173], v[96:97], v[96:97], v[172:173]
	v_pk_fma_f32 v[172:173], v[98:99], v[98:99], v[172:173]
	s_nop 0
	v_add_f32_e32 v169, v172, v173
	v_pk_add_f32 v[84:85], v[84:85], v[192:193]
	v_pk_add_f32 v[86:87], v[86:87], v[194:195]
	v_pk_add_f32 v[80:81], v[80:81], v[196:197]
	v_pk_add_f32 v[82:83], v[82:83], v[198:199]
	v_pk_mul_f32 v[172:173], v[84:85], v[84:85]
	v_pk_fma_f32 v[172:173], v[86:87], v[86:87], v[172:173]
	v_pk_fma_f32 v[172:173], v[80:81], v[80:81], v[172:173]
	v_pk_fma_f32 v[172:173], v[82:83], v[82:83], v[172:173]
	s_nop 0
	v_add_f32_e32 v170, v172, v173
	v_pk_add_f32 v[68:69], v[68:69], v[200:201]
	v_pk_add_f32 v[70:71], v[70:71], v[202:203]
	v_pk_add_f32 v[64:65], v[64:65], v[204:205]
	v_pk_add_f32 v[66:67], v[66:67], v[206:207]
	v_pk_mul_f32 v[172:173], v[68:69], v[68:69]
	v_pk_fma_f32 v[172:173], v[70:71], v[70:71], v[172:173]
	v_pk_fma_f32 v[172:173], v[64:65], v[64:65], v[172:173]
	v_pk_fma_f32 v[172:173], v[66:67], v[66:67], v[172:173]
	s_nop 0
	v_add_f32_e32 v171, v172, v173
	ds_bpermute_b32 v155, v153, v168
	ds_bpermute_b32 v156, v153, v169
	ds_bpermute_b32 v157, v153, v170
	ds_bpermute_b32 v132, v153, v171
	s_waitcnt lgkmcnt(0)
	v_add_f32_e32 v168, v168, v155
	v_add_f32_e32 v169, v169, v156
	v_add_f32_e32 v170, v170, v157
	v_add_f32_e32 v171, v171, v132
	ds_bpermute_b32 v155, v154, v168
	ds_bpermute_b32 v156, v154, v169
	ds_bpermute_b32 v157, v154, v170
	ds_bpermute_b32 v132, v154, v171
	s_waitcnt lgkmcnt(0)
	v_add_f32_e32 v168, v168, v155
	v_add_f32_e32 v169, v169, v156
	v_add_f32_e32 v170, v170, v157
	v_add_f32_e32 v171, v171, v132
	s_mov_b64 exec, s[36:37]
	s_bitcmp1_b32 s19, 0
	s_cbranch_scc0 .Lf3q1_at_q_0
	global_atomic_add_f32 v152, v168, s[60:61]

; __global__ void __launch_bounds__(512, 2) hymba_mega(Params p) {
;     ...
;             const float rstd = 1.0f / sqrtf(rs * (1.0f / 1024.0f) + EPS);
; #pragma unroll
;             for (int i = 0; i < 4; ++i) *(f32x4*)(yd + i * 256 + lane * 4) = v[i] * rstd * gq[i];
.Lf3q1_go_q:
	s_or_b64 exec, exec, vcc
	s_barrier
	s_mov_b64 exec, s[36:37]
	global_atomic_add_f32 v192, v152, v209, s[60:61] sc0
	global_atomic_add_f32 v194, v152, v209, s[60:61] offset:64 sc0
	global_atomic_add_f32 v196, v152, v209, s[60:61] offset:128 sc0
	global_atomic_add_f32 v198, v152, v209, s[60:61] offset:192 sc0
	s_mov_b64 exec, -1
	s_waitcnt vmcnt(0)
	ds_bpermute_b32 v192, v208, v192
	ds_bpermute_b32 v194, v208, v194
	ds_bpermute_b32 v196, v208, v196
	ds_bpermute_b32 v198, v208, v198
	s_waitcnt lgkmcnt(0)
	v_fmamk_f32 v213, v192, 0x3a800000, v218
	v_mul_f32_e32 v214, 0x4f800000, v213
	v_cmp_gt_f32_e32 vcc, 0xf800000, v213
	s_nop 1
	v_cndmask_b32_e32 v213, v213, v214, vcc
	v_sqrt_f32_e32 v214, v213
	s_nop 0
	v_add_u32_e32 v215, -1, v214
	v_fma_f32 v217, -v215, v214, v213
	v_add_u32_e32 v216, 1, v214
	v_cmp_ge_f32_e64 s[22:23], 0, v217
	s_nop 1
	v_cndmask_b32_e64 v215, v214, v215, s[22:23]
	v_fma_f32 v214, -v216, v214, v213
	v_cmp_lt_f32_e64 s[22:23], 0, v214
	s_nop 1
	v_cndmask_b32_e64 v214, v215, v216, s[22:23]
	v_mul_f32_e32 v215, 0x37800000, v214
	v_cndmask_b32_e32 v214, v214, v215, vcc
	v_cmp_class_f32_e32 vcc, v213, v219
	s_nop 1
	v_cndmask_b32_e32 v213, v214, v213, vcc
	v_div_scale_f32 v214, s[22:23], v213, v213, 1.0
	v_rcp_f32_e32 v215, v214
	s_nop 0
	v_fma_f32 v216, -v214, v215, 1.0
	v_fmac_f32_e32 v215, v216, v215
	v_div_scale_f32 v216, vcc, 1.0, v213, 1.0
	v_mul_f32_e32 v217, v216, v215
	v_fma_f32 v192, -v214, v217, v216
	v_fmac_f32_e32 v217, v192, v215
	v_fma_f32 v214, -v214, v217, v216
	s_nop 0
	v_div_fmas_f32 v214, v214, v215, v217
	v_div_fixup_f32 v192, v214, v213, 1.0
	v_fmamk_f32 v213, v194, 0x3a800000, v218
	v_mul_f32_e32 v214, 0x4f800000, v213
	v_cmp_gt_f32_e32 vcc, 0xf800000, v213
	s_nop 1
	v_cndmask_b32_e32 v213, v213, v214, vcc
	v_sqrt_f32_e32 v214, v213
	s_nop 0
	v_add_u32_e32 v215, -1, v214
	v_fma_f32 v217, -v215, v214, v213
	v_add_u32_e32 v216, 1, v214
	v_cmp_ge_f32_e64 s[22:23], 0, v217
	s_nop 1
	v_cndmask_b32_e64 v215, v214, v215, s[22:23]
	v_fma_f32 v214, -v216, v214, v213
	v_cmp_lt_f32_e64 s[22:23], 0, v214
	s_nop 1
	v_cndmask_b32_e64 v214, v215, v216, s[22:23]
	v_mul_f32_e32 v215, 0x37800000, v214
	v_cndmask_b32_e32 v214, v214, v215, vcc
	v_cmp_class_f32_e32 vcc, v213, v219
	s_nop 1
	v_cndmask_b32_e32 v213, v214, v213, vcc
	v_div_scale_f32 v214, s[22:23], v213, v213, 1.0
	v_rcp_f32_e32 v215, v214
	s_nop 0
	v_fma_f32 v216, -v214, v215, 1.0
	v_fmac_f32_e32 v215, v216, v215
	v_div_scale_f32 v216, vcc, 1.0, v213, 1.0
	v_mul_f32_e32 v217, v216, v215
	v_fma_f32 v194, -v214, v217, v216
	v_fmac_f32_e32 v217, v194, v215
	v_fma_f32 v214, -v214, v217, v216
	s_nop 0
	v_div_fmas_f32 v214, v214, v215, v217
	v_div_fixup_f32 v194, v214, v213, 1.0
	v_fmamk_f32 v213, v196, 0x3a800000, v218
	v_mul_f32_e32 v214, 0x4f800000, v213
	v_cmp_gt_f32_e32 vcc, 0xf800000, v213
	s_nop 1
	v_cndmask_b32_e32 v213, v213, v214, vcc
	v_sqrt_f32_e32 v214, v213
	s_nop 0
	v_add_u32_e32 v215, -1, v214
	v_fma_f32 v217, -v215, v214, v213
	v_add_u32_e32 v216, 1, v214
	v_cmp_ge_f32_e64 s[22:23], 0, v217
	s_nop 1
	v_cndmask_b32_e64 v215, v214, v215, s[22:23]
	v_fma_f32 v214, -v216, v214, v213
	v_cmp_lt_f32_e64 s[22:23], 0, v214
	s_nop 1
	v_cndmask_b32_e64 v214, v215, v216, s[22:23]
	v_mul_f32_e32 v215, 0x37800000, v214
	v_cndmask_b32_e32 v214, v214, v215, vcc
	v_cmp_class_f32_e32 vcc, v213, v219
	s_nop 1
	v_cndmask_b32_e32 v213, v214, v213, vcc
	v_div_scale_f32 v214, s[22:23], v213, v213, 1.0
	v_rcp_f32_e32 v215, v214
	s_nop 0
	v_fma_f32 v216, -v214, v215, 1.0
	v_fmac_f32_e32 v215, v216, v215
	v_div_scale_f32 v216, vcc, 1.0, v213, 1.0
	v_mul_f32_e32 v217, v216, v215
	v_fma_f32 v196, -v214, v217, v216
	v_fmac_f32_e32 v217, v196, v215
	v_fma_f32 v214, -v214, v217, v216
	s_nop 0
	v_div_fmas_f32 v214, v214, v215, v217
	v_div_fixup_f32 v196, v214, v213, 1.0
	v_fmamk_f32 v213, v198, 0x3a800000, v218
	v_mul_f32_e32 v214, 0x4f800000, v213
	v_cmp_gt_f32_e32 vcc, 0xf800000, v213
	s_nop 1
	v_cndmask_b32_e32 v213, v213, v214, vcc
	v_sqrt_f32_e32 v214, v213
	s_nop 0
	v_add_u32_e32 v215, -1, v214
	v_fma_f32 v217, -v215, v214, v213
	v_add_u32_e32 v216, 1, v214
	v_cmp_ge_f32_e64 s[22:23], 0, v217
	s_nop 1
	v_cndmask_b32_e64 v215, v214, v215, s[22:23]
	v_fma_f32 v214, -v216, v214, v213
	v_cmp_lt_f32_e64 s[22:23], 0, v214
	s_nop 1
	v_cndmask_b32_e64 v214, v215, v216, s[22:23]
	v_mul_f32_e32 v215, 0x37800000, v214
	v_cndmask_b32_e32 v214, v214, v215, vcc
	v_cmp_class_f32_e32 vcc, v213, v219
	s_nop 1
	v_cndmask_b32_e32 v213, v214, v213, vcc
	v_div_scale_f32 v214, s[22:23], v213, v213, 1.0
	v_rcp_f32_e32 v215, v214
	s_nop 0
	v_fma_f32 v216, -v214, v215, 1.0
	v_fmac_f32_e32 v215, v216, v215
	v_div_scale_f32 v216, vcc, 1.0, v213, 1.0
	v_mul_f32_e32 v217, v216, v215
	v_fma_f32 v198, -v214, v217, v216
	v_fmac_f32_e32 v217, v198, v215
	v_fma_f32 v214, -v214, v217, v216
	s_nop 0
	v_div_fmas_f32 v214, v214, v215, v217
	v_div_fixup_f32 v198, v214, v213, 1.0
	s_bitcmp1_b32 s19, 0
	s_cbranch_scc0 .Lf3q1_st_0
	s_add_i32 s87, s21, 0
	s_mul_hi_u32 s89, s87, 0x7e07e07f
	s_lshr_b32 s89, s89, 11
	s_mul_i32 vcc_lo, s89, 0x1040
	s_sub_i32 vcc_lo, s87, vcc_lo
	s_add_i32 vcc_lo, vcc_lo, -16
	s_lshl_b32 s89, s89, 12
	s_add_i32 s89, s89, vcc_lo
	s_cmp_lt_u32 vcc_lo, 0x1000
	s_cselect_b32 vcc_hi, 1, 0
	s_sub_i32 vcc_lo, s87, 0x4100
	s_cmp_ge_u32 s94, 65
	s_cselect_b32 s89, vcc_lo, s89
	s_cselect_b32 vcc_hi, 1, vcc_hi
	s_cmp_lg_u32 vcc_hi, 0
	s_cselect_b32 s89, s89, 0
	s_lshl_b32 s20, s89, 12
	v_pk_mul_f32 v[116:117], v[192:193], v[116:117] op_sel_hi:[0,1]
	v_pk_mul_f32 v[118:119], v[192:193], v[118:119] op_sel_hi:[0,1]
	v_pk_mul_f32 v[112:113], v[192:193], v[112:113] op_sel_hi:[0,1]
	v_pk_mul_f32 v[114:115], v[192:193], v[114:115] op_sel_hi:[0,1]
	v_pk_mul_f32 v[116:117], v[184:185], v[116:117]
	v_pk_mul_f32 v[118:119], v[186:187], v[118:119]
	v_pk_mul_f32 v[112:113], v[188:189], v[112:113]
	v_pk_mul_f32 v[114:115], v[190:191], v[114:115]
	s_add_u32 s22, s98, s20
	s_addc_u32 s23, s99, 0
	global_store_dwordx4 v151, v[116:119], s[22:23] offset:512
	global_store_dwordx4 v151, v[112:115], s[22:23] offset:528
; __global__ void __launch_bounds__(512, 2) hymba_mega(Params p) {
;     ...
;             const float rstd = 1.0f / sqrtf(rs * (1.0f / 1024.0f) + EPS);
; #pragma unroll
;             for (int i = 0; i < 4; ++i) *(f32x4*)(yd + i * 256 + lane * 4) = v[i] * rstd * gq[i];
.Lf3q1_st_0:
	s_bitcmp1_b32 s19, 1
	s_cbranch_scc0 .Lf3q1_st_1
	s_add_i32 s87, s21, 16
	s_mul_hi_u32 s89, s87, 0x7e07e07f
	s_lshr_b32 s89, s89, 11
	s_mul_i32 vcc_lo, s89, 0x1040
	s_sub_i32 vcc_lo, s87, vcc_lo
	s_add_i32 vcc_lo, vcc_lo, -16
	s_lshl_b32 s89, s89, 12
	s_add_i32 s89, s89, vcc_lo
	s_cmp_lt_u32 vcc_lo, 0x1000
	s_cselect_b32 vcc_hi, 1, 0
	s_sub_i32 vcc_lo, s87, 0x4100
	s_cmp_ge_u32 s94, 65
	s_cselect_b32 s89, vcc_lo, s89
	s_cselect_b32 vcc_hi, 1, vcc_hi
	s_cmp_lg_u32 vcc_hi, 0
	s_cselect_b32 s89, s89, 0
	s_lshl_b32 s20, s89, 12
	v_pk_mul_f32 v[100:101], v[194:195], v[100:101] op_sel_hi:[0,1]
	v_pk_mul_f32 v[102:103], v[194:195], v[102:103] op_sel_hi:[0,1]
	v_pk_mul_f32 v[96:97], v[194:195], v[96:97] op_sel_hi:[0,1]
	v_pk_mul_f32 v[98:99], v[194:195], v[98:99] op_sel_hi:[0,1]
	v_pk_mul_f32 v[100:101], v[184:185], v[100:101]
	v_pk_mul_f32 v[102:103], v[186:187], v[102:103]
	v_pk_mul_f32 v[96:97], v[188:189], v[96:97]
	v_pk_mul_f32 v[98:99], v[190:191], v[98:99]
	s_add_u32 s22, s98, s20
	s_addc_u32 s23, s99, 0
	global_store_dwordx4 v151, v[100:103], s[22:23] offset:512
	global_store_dwordx4 v151, v[96:99], s[22:23] offset:528
.Lf3q1_st_1:
	s_bitcmp1_b32 s19, 2
	s_cbranch_scc0 .Lf3q1_st_2
	s_add_i32 s87, s21, 32
	s_mul_hi_u32 s89, s87, 0x7e07e07f
	s_lshr_b32 s89, s89, 11
	s_mul_i32 vcc_lo, s89, 0x1040
	s_sub_i32 vcc_lo, s87, vcc_lo
	s_add_i32 vcc_lo, vcc_lo, -16
	s_lshl_b32 s89, s89, 12
	s_add_i32 s89, s89, vcc_lo
	s_cmp_lt_u32 vcc_lo, 0x1000
	s_cselect_b32 vcc_hi, 1, 0
	s_sub_i32 vcc_lo, s87, 0x4100
	s_cmp_ge_u32 s94, 65
	s_cselect_b32 s89, vcc_lo, s89
	s_cselect_b32 vcc_hi, 1, vcc_hi
	s_cmp_lg_u32 vcc_hi, 0
	s_cselect_b32 s89, s89, 0
	s_lshl_b32 s20, s89, 12
	v_pk_mul_f32 v[84:85], v[196:197], v[84:85] op_sel_hi:[0,1]
	v_pk_mul_f32 v[86:87], v[196:197], v[86:87] op_sel_hi:[0,1]
	v_pk_mul_f32 v[80:81], v[196:197], v[80:81] op_sel_hi:[0,1]
	v_pk_mul_f32 v[82:83], v[196:197], v[82:83] op_sel_hi:[0,1]
	v_pk_mul_f32 v[84:85], v[184:185], v[84:85]
	v_pk_mul_f32 v[86:87], v[186:187], v[86:87]
	v_pk_mul_f32 v[80:81], v[188:189], v[80:81]
	v_pk_mul_f32 v[82:83], v[190:191], v[82:83]
	s_add_u32 s22, s98, s20
	s_addc_u32 s23, s99, 0
	global_store_dwordx4 v151, v[84:87], s[22:23] offset:512
	global_store_dwordx4 v151, v[80:83], s[22:23] offset:528
.Lf3q1_st_2:
	s_bitcmp1_b32 s19, 3
	s_cbranch_scc0 .Lf3q1_st_3
	s_add_i32 s87, s21, 48
	s_mul_hi_u32 s89, s87, 0x7e07e07f
	s_lshr_b32 s89, s89, 11
	s_mul_i32 vcc_lo, s89, 0x1040
	s_sub_i32 vcc_lo, s87, vcc_lo
	s_add_i32 vcc_lo, vcc_lo, -16
	s_lshl_b32 s89, s89, 12
	s_add_i32 s89, s89, vcc_lo
	s_cmp_lt_u32 vcc_lo, 0x1000
	s_cselect_b32 vcc_hi, 1, 0
	s_sub_i32 vcc_lo, s87, 0x4100
	s_cmp_ge_u32 s94, 65
	s_cselect_b32 s89, vcc_lo, s89
	s_cselect_b32 vcc_hi, 1, vcc_hi
	s_cmp_lg_u32 vcc_hi, 0
	s_cselect_b32 s89, s89, 0
	s_lshl_b32 s20, s89, 12
	v_pk_mul_f32 v[68:69], v[198:199], v[68:69] op_sel_hi:[0,1]
	v_pk_mul_f32 v[70:71], v[198:199], v[70:71] op_sel_hi:[0,1]
	v_pk_mul_f32 v[64:65], v[198:199], v[64:65] op_sel_hi:[0,1]
	v_pk_mul_f32 v[66:67], v[198:199], v[66:67] op_sel_hi:[0,1]
	v_pk_mul_f32 v[68:69], v[184:185], v[68:69]
	v_pk_mul_f32 v[70:71], v[186:187], v[70:71]
	v_pk_mul_f32 v[64:65], v[188:189], v[64:65]
	v_pk_mul_f32 v[66:67], v[190:191], v[66:67]
	s_add_u32 s22, s98, s20
	s_addc_u32 s23, s99, 0
	global_store_dwordx4 v151, v[68:71], s[22:23] offset:512
	global_store_dwordx4 v151, v[64:67], s[22:23] offset:528

;     DI void operator()(const f32x4 (&acc)[2][2][4][2], const pg8::Unit& u, int wr, int wc, int fr, int fq) const {
;     ...
;                 const int R = u.pm * 256 + ai * 128 + wr * 64 + m * 16 + fr;
;                 const float* xs = nullptr; float* yd = nullptr;
;                 if (R < ROWS_P) { const int b = R / LPAD, t = R - b * LPAD; if (t >= NMETA && t < LP) { const size_t idx = ((size_t)b * SEQ + t - NMETA) * DM; xs = p.x_prompt + idx; yd = p.out + O_YP + idx; } }
;                 else { const size_t idx = (size_t)(R - ROWS_P) * DM; xs = p.x_sample + idx; yd = p.out + O_YS + idx; }
;                 float ss = 0.f;
;                 if (xs) {
; #pragma unroll
;                     for (int bj = 0; bj < 2; ++bj) {
;                         const int n = colt + bj * 128 + wc * 32 + 8 * fq;
;                         const f32x4 x0 = *(const f32x4*)(xs + n), x1 = *(const f32x4*)(xs + n + 4);
;                         const f32x4 h0 = x0 + acc[ai][bj][m][0], h1 = x1 + acc[ai][bj][m][1];
;                         *(f32x4*)(yd + n) = h0; *(f32x4*)(yd + n + 4) = h1;
;                         ss += h0[0] * h0[0] + h0[1] * h0[1] + h0[2] * h0[2] + h0[3] * h0[3] + h1[0] * h1[0] + h1[1] * h1[1] + h1[2] * h1[2] + h1[3] * h1[3];
;                     }
;                 }
;                 ss += __shfl_xor(ss, 16); ss += __shfl_xor(ss, 32);
;                 if (xs && fq == 0) atomicAdd(p.rowss + R, ss);
.Lp3q_v2:
	s_add_i32 s87, s21, 128
	s_mul_hi_u32 s89, s87, 0x7e07e07f
	s_lshr_b32 s89, s89, 11
	s_mul_i32 vcc_lo, s89, 0x1040
	s_sub_i32 vcc_lo, s87, vcc_lo
	s_add_i32 vcc_lo, vcc_lo, -16
	s_lshl_b32 s89, s89, 12
	s_add_i32 s89, s89, vcc_lo
	s_cmp_lt_u32 vcc_lo, 0x1000
	s_cselect_b32 vcc_hi, 1, 0
	s_sub_i32 vcc_lo, s87, 0x4100
	s_cmp_ge_u32 s94, 65
	s_cselect_b32 s89, vcc_lo, s89
	s_cselect_b32 vcc_hi, 1, vcc_hi
	s_cmp_lg_u32 vcc_hi, 0
	s_cselect_b32 s89, s89, 0
	s_lshl_b32 s20, s89, 12
	s_lshl_b32 vcc_hi, vcc_hi, 0
	s_or_b32 s19, s19, vcc_hi
	s_add_u32 s22, s96, s20
	s_addc_u32 s23, s97, 0
	global_load_dwordx4 v[176:179], v151, s[22:23]
	global_load_dwordx4 v[180:183], v151, s[22:23] offset:16
	s_add_i32 s87, s21, 144
	s_mul_hi_u32 s89, s87, 0x7e07e07f
	s_lshr_b32 s89, s89, 11
	s_mul_i32 vcc_lo, s89, 0x1040
	s_sub_i32 vcc_lo, s87, vcc_lo
	s_add_i32 vcc_lo, vcc_lo, -16
	s_lshl_b32 s89, s89, 12
	s_add_i32 s89, s89, vcc_lo
	s_cmp_lt_u32 vcc_lo, 0x1000
	s_cselect_b32 vcc_hi, 1, 0
	s_sub_i32 vcc_lo, s87, 0x4100
	s_cmp_ge_u32 s94, 65
	s_cselect_b32 s89, vcc_lo, s89
	s_cselect_b32 vcc_hi, 1, vcc_hi
	s_cmp_lg_u32 vcc_hi, 0
	s_cselect_b32 s89, s89, 0
	s_lshl_b32 s42, s89, 12
	s_lshl_b32 vcc_hi, vcc_hi, 1
	s_or_b32 s19, s19, vcc_hi
	s_add_u32 s22, s96, s42
	s_addc_u32 s23, s97, 0
	global_load_dwordx4 v[184:187], v151, s[22:23]
	global_load_dwordx4 v[188:191], v151, s[22:23] offset:16
	s_add_i32 s87, s21, 160
	s_mul_hi_u32 s89, s87, 0x7e07e07f
	s_lshr_b32 s89, s89, 11
	s_mul_i32 vcc_lo, s89, 0x1040
	s_sub_i32 vcc_lo, s87, vcc_lo
	s_add_i32 vcc_lo, vcc_lo, -16
	s_lshl_b32 s89, s89, 12
	s_add_i32 s89, s89, vcc_lo
	s_cmp_lt_u32 vcc_lo, 0x1000
	s_cselect_b32 vcc_hi, 1, 0
	s_sub_i32 vcc_lo, s87, 0x4100
	s_cmp_ge_u32 s94, 65
	s_cselect_b32 s89, vcc_lo, s89
	s_cselect_b32 vcc_hi, 1, vcc_hi
	s_cmp_lg_u32 vcc_hi, 0
	s_cselect_b32 s89, s89, 0
	s_lshl_b32 s43, s89, 12
	s_lshl_b32 vcc_hi, vcc_hi, 2
	s_or_b32 s19, s19, vcc_hi
	s_add_u32 s22, s96, s43
	s_addc_u32 s23, s97, 0
	global_load_dwordx4 v[192:195], v151, s[22:23]
	global_load_dwordx4 v[196:199], v151, s[22:23] offset:16
	s_add_i32 s87, s21, 176
	s_mul_hi_u32 s89, s87, 0x7e07e07f
	s_lshr_b32 s89, s89, 11
	s_mul_i32 vcc_lo, s89, 0x1040
	s_sub_i32 vcc_lo, s87, vcc_lo
	s_add_i32 vcc_lo, vcc_lo, -16
	s_lshl_b32 s89, s89, 12
	s_add_i32 s89, s89, vcc_lo
	s_cmp_lt_u32 vcc_lo, 0x1000
	s_cselect_b32 vcc_hi, 1, 0
	s_sub_i32 vcc_lo, s87, 0x4100
	s_cmp_ge_u32 s94, 65
	s_cselect_b32 s89, vcc_lo, s89
	s_cselect_b32 vcc_hi, 1, vcc_hi
	s_cmp_lg_u32 vcc_hi, 0
	s_cselect_b32 s89, s89, 0
	s_lshl_b32 s95, s89, 12
	s_lshl_b32 vcc_hi, vcc_hi, 3
	s_or_b32 s19, s19, vcc_hi
	s_add_u32 s22, s96, s95
	s_addc_u32 s23, s97, 0
	global_load_dwordx4 v[200:203], v151, s[22:23]
	global_load_dwordx4 v[204:207], v151, s[22:23] offset:16
	s_waitcnt vmcnt(0)
	v_pk_add_f32 v[60:61], v[60:61], v[176:177]
	v_pk_add_f32 v[62:63], v[62:63], v[178:179]
	v_pk_add_f32 v[56:57], v[56:57], v[180:181]
	v_pk_add_f32 v[58:59], v[58:59], v[182:183]
	v_pk_mul_f32 v[172:173], v[60:61], v[60:61]
	v_pk_fma_f32 v[172:173], v[62:63], v[62:63], v[172:173]
	v_pk_fma_f32 v[172:173], v[56:57], v[56:57], v[172:173]
	v_pk_fma_f32 v[172:173], v[58:59], v[58:59], v[172:173]
	s_nop 0
	v_add_f32_e32 v168, v172, v173
	v_pk_add_f32 v[44:45], v[44:45], v[184:185]
	v_pk_add_f32 v[46:47], v[46:47], v[186:187]
	v_pk_add_f32 v[40:41], v[40:41], v[188:189]
	v_pk_add_f32 v[42:43], v[42:43], v[190:191]
	v_pk_mul_f32 v[172:173], v[44:45], v[44:45]
	v_pk_fma_f32 v[172:173], v[46:47], v[46:47], v[172:173]
	v_pk_fma_f32 v[172:173], v[40:41], v[40:41], v[172:173]
	v_pk_fma_f32 v[172:173], v[42:43], v[42:43], v[172:173]
	s_nop 0
	v_add_f32_e32 v169, v172, v173
	v_pk_add_f32 v[28:29], v[28:29], v[192:193]
	v_pk_add_f32 v[30:31], v[30:31], v[194:195]
	v_pk_add_f32 v[24:25], v[24:25], v[196:197]
	v_pk_add_f32 v[26:27], v[26:27], v[198:199]
	v_pk_mul_f32 v[172:173], v[28:29], v[28:29]
	v_pk_fma_f32 v[172:173], v[30:31], v[30:31], v[172:173]
	v_pk_fma_f32 v[172:173], v[24:25], v[24:25], v[172:173]
	v_pk_fma_f32 v[172:173], v[26:27], v[26:27], v[172:173]
	s_nop 0
	v_add_f32_e32 v170, v172, v173
	v_pk_add_f32 v[12:13], v[12:13], v[200:201]
	v_pk_add_f32 v[14:15], v[14:15], v[202:203]
	v_pk_add_f32 v[8:9], v[8:9], v[204:205]
	v_pk_add_f32 v[10:11], v[10:11], v[206:207]
	v_pk_mul_f32 v[172:173], v[12:13], v[12:13]
	v_pk_fma_f32 v[172:173], v[14:15], v[14:15], v[172:173]
	v_pk_fma_f32 v[172:173], v[8:9], v[8:9], v[172:173]
	v_pk_fma_f32 v[172:173], v[10:11], v[10:11], v[172:173]
	s_nop 0
	v_add_f32_e32 v171, v172, v173
	ds_bpermute_b32 v155, v153, v168
	ds_bpermute_b32 v156, v153, v169
	ds_bpermute_b32 v157, v153, v170
	ds_bpermute_b32 v132, v153, v171
	s_waitcnt lgkmcnt(0)
	v_add_f32_e32 v168, v168, v155
	v_add_f32_e32 v169, v169, v156
	v_add_f32_e32 v170, v170, v157
	v_add_f32_e32 v171, v171, v132
	ds_bpermute_b32 v155, v154, v168
	ds_bpermute_b32 v156, v154, v169
	ds_bpermute_b32 v157, v154, v170
	ds_bpermute_b32 v132, v154, v171
	s_waitcnt lgkmcnt(0)
	v_add_f32_e32 v168, v168, v155
	v_add_f32_e32 v169, v169, v156
	v_add_f32_e32 v170, v170, v157
	v_add_f32_e32 v171, v171, v132
	s_mov_b64 exec, s[36:37]
	s_bitcmp1_b32 s19, 0
	s_cbranch_scc0 .Lf3q2_at_q_0
	global_atomic_add_f32 v152, v168, s[60:61] offset:512

;     DI void operator()(const f32x4 (&acc)[2][2][4][2], const pg8::Unit& u, int wr, int wc, int fr, int fq) const {
;     ...
;                 const int R = u.pm * 256 + ai * 128 + wr * 64 + m * 16 + fr;
;                 const float* xs = nullptr; float* yd = nullptr;
;                 if (R < ROWS_P) { const int b = R / LPAD, t = R - b * LPAD; if (t >= NMETA && t < LP) { const size_t idx = ((size_t)b * SEQ + t - NMETA) * DM; xs = p.x_prompt + idx; yd = p.out + O_YP + idx; } }
;                 else { const size_t idx = (size_t)(R - ROWS_P) * DM; xs = p.x_sample + idx; yd = p.out + O_YS + idx; }
;                 float ss = 0.f;
;                 if (xs) {
; #pragma unroll
;                     for (int bj = 0; bj < 2; ++bj) {
;                         const int n = colt + bj * 128 + wc * 32 + 8 * fq;
;                         const f32x4 x0 = *(const f32x4*)(xs + n), x1 = *(const f32x4*)(xs + n + 4);
;                         const f32x4 h0 = x0 + acc[ai][bj][m][0], h1 = x1 + acc[ai][bj][m][1];
;                         *(f32x4*)(yd + n) = h0; *(f32x4*)(yd + n + 4) = h1;
;                         ss += h0[0] * h0[0] + h0[1] * h0[1] + h0[2] * h0[2] + h0[3] * h0[3] + h1[0] * h1[0] + h1[1] * h1[1] + h1[2] * h1[2] + h1[3] * h1[3];
;                     }
;                 }
;                 ss += __shfl_xor(ss, 16); ss += __shfl_xor(ss, 32);
;                 if (xs && fq == 0) atomicAdd(p.rowss + R, ss);
; __global__ void __launch_bounds__(512, 2) hymba_mega(Params p) {
;     ...
;             const float rstd = 1.0f / sqrtf(rs * (1.0f / 1024.0f) + EPS);
; #pragma unroll
;             for (int i = 0; i < 4; ++i) *(f32x4*)(yd + i * 256 + lane * 4) = v[i] * rstd * gq[i];
.Lf3q2_go_q:
	s_or_b64 exec, exec, vcc
	s_barrier
	s_mov_b64 exec, s[36:37]
	global_atomic_add_f32 v200, v152, v209, s[60:61] offset:512 sc0
	global_atomic_add_f32 v202, v152, v209, s[60:61] offset:576 sc0
	global_atomic_add_f32 v204, v152, v209, s[60:61] offset:640 sc0
	global_atomic_add_f32 v206, v152, v209, s[60:61] offset:704 sc0
	s_mov_b64 exec, -1
	s_waitcnt vmcnt(0)
	ds_bpermute_b32 v200, v208, v200
	ds_bpermute_b32 v202, v208, v202
	ds_bpermute_b32 v204, v208, v204
	ds_bpermute_b32 v206, v208, v206
	s_waitcnt lgkmcnt(0)
	v_fmamk_f32 v213, v200, 0x3a800000, v218
	v_mul_f32_e32 v214, 0x4f800000, v213
	v_cmp_gt_f32_e32 vcc, 0xf800000, v213
	s_nop 1
	v_cndmask_b32_e32 v213, v213, v214, vcc
	v_sqrt_f32_e32 v214, v213
	s_nop 0
	v_add_u32_e32 v215, -1, v214
	v_fma_f32 v217, -v215, v214, v213
	v_add_u32_e32 v216, 1, v214
	v_cmp_ge_f32_e64 s[22:23], 0, v217
	s_nop 1
	v_cndmask_b32_e64 v215, v214, v215, s[22:23]
	v_fma_f32 v214, -v216, v214, v213
	v_cmp_lt_f32_e64 s[22:23], 0, v214
	s_nop 1
	v_cndmask_b32_e64 v214, v215, v216, s[22:23]
	v_mul_f32_e32 v215, 0x37800000, v214
	v_cndmask_b32_e32 v214, v214, v215, vcc
	v_cmp_class_f32_e32 vcc, v213, v219
	s_nop 1
	v_cndmask_b32_e32 v213, v214, v213, vcc
	v_div_scale_f32 v214, s[22:23], v213, v213, 1.0
	v_rcp_f32_e32 v215, v214
	s_nop 0
	v_fma_f32 v216, -v214, v215, 1.0
	v_fmac_f32_e32 v215, v216, v215
	v_div_scale_f32 v216, vcc, 1.0, v213, 1.0
	v_mul_f32_e32 v217, v216, v215
	v_fma_f32 v200, -v214, v217, v216
	v_fmac_f32_e32 v217, v200, v215
	v_fma_f32 v214, -v214, v217, v216
	s_nop 0
	v_div_fmas_f32 v214, v214, v215, v217
	v_div_fixup_f32 v200, v214, v213, 1.0
	v_fmamk_f32 v213, v202, 0x3a800000, v218
	v_mul_f32_e32 v214, 0x4f800000, v213
	v_cmp_gt_f32_e32 vcc, 0xf800000, v213
	s_nop 1
	v_cndmask_b32_e32 v213, v213, v214, vcc
	v_sqrt_f32_e32 v214, v213
	s_nop 0
	v_add_u32_e32 v215, -1, v214
	v_fma_f32 v217, -v215, v214, v213
	v_add_u32_e32 v216, 1, v214
	v_cmp_ge_f32_e64 s[22:23], 0, v217
	s_nop 1
	v_cndmask_b32_e64 v215, v214, v215, s[22:23]
	v_fma_f32 v214, -v216, v214, v213
	v_cmp_lt_f32_e64 s[22:23], 0, v214
	s_nop 1
	v_cndmask_b32_e64 v214, v215, v216, s[22:23]
	v_mul_f32_e32 v215, 0x37800000, v214
	v_cndmask_b32_e32 v214, v214, v215, vcc
	v_cmp_class_f32_e32 vcc, v213, v219
	s_nop 1
	v_cndmask_b32_e32 v213, v214, v213, vcc
	v_div_scale_f32 v214, s[22:23], v213, v213, 1.0
	v_rcp_f32_e32 v215, v214
	s_nop 0
	v_fma_f32 v216, -v214, v215, 1.0
	v_fmac_f32_e32 v215, v216, v215
	v_div_scale_f32 v216, vcc, 1.0, v213, 1.0
	v_mul_f32_e32 v217, v216, v215
	v_fma_f32 v202, -v214, v217, v216
	v_fmac_f32_e32 v217, v202, v215
	v_fma_f32 v214, -v214, v217, v216
	s_nop 0
	v_div_fmas_f32 v214, v214, v215, v217
	v_div_fixup_f32 v202, v214, v213, 1.0
	v_fmamk_f32 v213, v204, 0x3a800000, v218
	v_mul_f32_e32 v214, 0x4f800000, v213
	v_cmp_gt_f32_e32 vcc, 0xf800000, v213
	s_nop 1
	v_cndmask_b32_e32 v213, v213, v214, vcc
	v_sqrt_f32_e32 v214, v213
	s_nop 0
	v_add_u32_e32 v215, -1, v214
	v_fma_f32 v217, -v215, v214, v213
	v_add_u32_e32 v216, 1, v214
	v_cmp_ge_f32_e64 s[22:23], 0, v217
	s_nop 1
	v_cndmask_b32_e64 v215, v214, v215, s[22:23]
	v_fma_f32 v214, -v216, v214, v213
	v_cmp_lt_f32_e64 s[22:23], 0, v214
	s_nop 1
	v_cndmask_b32_e64 v214, v215, v216, s[22:23]
	v_mul_f32_e32 v215, 0x37800000, v214
	v_cndmask_b32_e32 v214, v214, v215, vcc
	v_cmp_class_f32_e32 vcc, v213, v219
	s_nop 1
	v_cndmask_b32_e32 v213, v214, v213, vcc
	v_div_scale_f32 v214, s[22:23], v213, v213, 1.0
	v_rcp_f32_e32 v215, v214
	s_nop 0
	v_fma_f32 v216, -v214, v215, 1.0
	v_fmac_f32_e32 v215, v216, v215
	v_div_scale_f32 v216, vcc, 1.0, v213, 1.0
	v_mul_f32_e32 v217, v216, v215
	v_fma_f32 v204, -v214, v217, v216
	v_fmac_f32_e32 v217, v204, v215
	v_fma_f32 v214, -v214, v217, v216
	s_nop 0
	v_div_fmas_f32 v214, v214, v215, v217
	v_div_fixup_f32 v204, v214, v213, 1.0
	v_fmamk_f32 v213, v206, 0x3a800000, v218
	v_mul_f32_e32 v214, 0x4f800000, v213
	v_cmp_gt_f32_e32 vcc, 0xf800000, v213
	s_nop 1
	v_cndmask_b32_e32 v213, v213, v214, vcc
	v_sqrt_f32_e32 v214, v213
	s_nop 0
	v_add_u32_e32 v215, -1, v214
	v_fma_f32 v217, -v215, v214, v213
	v_add_u32_e32 v216, 1, v214
	v_cmp_ge_f32_e64 s[22:23], 0, v217
	s_nop 1
	v_cndmask_b32_e64 v215, v214, v215, s[22:23]
	v_fma_f32 v214, -v216, v214, v213
	v_cmp_lt_f32_e64 s[22:23], 0, v214
	s_nop 1
	v_cndmask_b32_e64 v214, v215, v216, s[22:23]
	v_mul_f32_e32 v215, 0x37800000, v214
	v_cndmask_b32_e32 v214, v214, v215, vcc
	v_cmp_class_f32_e32 vcc, v213, v219
	s_nop 1
	v_cndmask_b32_e32 v213, v214, v213, vcc
	v_div_scale_f32 v214, s[22:23], v213, v213, 1.0
	v_rcp_f32_e32 v215, v214
	s_nop 0
	v_fma_f32 v216, -v214, v215, 1.0
	v_fmac_f32_e32 v215, v216, v215
	v_div_scale_f32 v216, vcc, 1.0, v213, 1.0
	v_mul_f32_e32 v217, v216, v215
	v_fma_f32 v206, -v214, v217, v216
	v_fmac_f32_e32 v217, v206, v215
	v_fma_f32 v214, -v214, v217, v216
	s_nop 0
	v_div_fmas_f32 v214, v214, v215, v217
	v_div_fixup_f32 v206, v214, v213, 1.0
	s_bitcmp1_b32 s19, 0
	s_cbranch_scc0 .Lf3q2_st_0
	s_add_i32 s87, s21, 128
	s_mul_hi_u32 s89, s87, 0x7e07e07f
	s_lshr_b32 s89, s89, 11
	s_mul_i32 vcc_lo, s89, 0x1040
	s_sub_i32 vcc_lo, s87, vcc_lo
	s_add_i32 vcc_lo, vcc_lo, -16
	s_lshl_b32 s89, s89, 12
	s_add_i32 s89, s89, vcc_lo
	s_cmp_lt_u32 vcc_lo, 0x1000
	s_cselect_b32 vcc_hi, 1, 0
	s_sub_i32 vcc_lo, s87, 0x4100
	s_cmp_ge_u32 s94, 65
	s_cselect_b32 s89, vcc_lo, s89
	s_cselect_b32 vcc_hi, 1, vcc_hi
	s_cmp_lg_u32 vcc_hi, 0
	s_cselect_b32 s89, s89, 0
	s_lshl_b32 s20, s89, 12
	v_pk_mul_f32 v[60:61], v[200:201], v[60:61] op_sel_hi:[0,1]
	v_pk_mul_f32 v[62:63], v[200:201], v[62:63] op_sel_hi:[0,1]
	v_pk_mul_f32 v[56:57], v[200:201], v[56:57] op_sel_hi:[0,1]
	v_pk_mul_f32 v[58:59], v[200:201], v[58:59] op_sel_hi:[0,1]
	v_pk_mul_f32 v[60:61], v[176:177], v[60:61]
	v_pk_mul_f32 v[62:63], v[178:179], v[62:63]
	v_pk_mul_f32 v[56:57], v[180:181], v[56:57]
	v_pk_mul_f32 v[58:59], v[182:183], v[58:59]
	s_add_u32 s22, s98, s20
	s_addc_u32 s23, s99, 0
	global_store_dwordx4 v151, v[60:63], s[22:23]
	global_store_dwordx4 v151, v[56:59], s[22:23] offset:16
;     DI void operator()(const f32x4 (&acc)[2][2][4][2], const pg8::Unit& u, int wr, int wc, int fr, int fq) const {
;     ...
;                 const int R = u.pm * 256 + ai * 128 + wr * 64 + m * 16 + fr;
;                 const float* xs = nullptr; float* yd = nullptr;
;                 if (R < ROWS_P) { const int b = R / LPAD, t = R - b * LPAD; if (t >= NMETA && t < LP) { const size_t idx = ((size_t)b * SEQ + t - NMETA) * DM; xs = p.x_prompt + idx; yd = p.out + O_YP + idx; } }
;                 else { const size_t idx = (size_t)(R - ROWS_P) * DM; xs = p.x_sample + idx; yd = p.out + O_YS + idx; }
; __global__ void __launch_bounds__(512, 2) hymba_mega(Params p) {
;     ...
;             const float rstd = 1.0f / sqrtf(rs * (1.0f / 1024.0f) + EPS);
; #pragma unroll
;             for (int i = 0; i < 4; ++i) *(f32x4*)(yd + i * 256 + lane * 4) = v[i] * rstd * gq[i];
.Lf3q2_st_0:
	s_bitcmp1_b32 s19, 1
	s_cbranch_scc0 .Lf3q2_st_1
	s_add_i32 s87, s21, 144
	s_mul_hi_u32 s89, s87, 0x7e07e07f
	s_lshr_b32 s89, s89, 11
	s_mul_i32 vcc_lo, s89, 0x1040
	s_sub_i32 vcc_lo, s87, vcc_lo
	s_add_i32 vcc_lo, vcc_lo, -16
	s_lshl_b32 s89, s89, 12
	s_add_i32 s89, s89, vcc_lo
	s_cmp_lt_u32 vcc_lo, 0x1000
	s_cselect_b32 vcc_hi, 1, 0
	s_sub_i32 vcc_lo, s87, 0x4100
	s_cmp_ge_u32 s94, 65
	s_cselect_b32 s89, vcc_lo, s89
	s_cselect_b32 vcc_hi, 1, vcc_hi
	s_cmp_lg_u32 vcc_hi, 0
	s_cselect_b32 s89, s89, 0
	s_lshl_b32 s20, s89, 12
	v_pk_mul_f32 v[44:45], v[202:203], v[44:45] op_sel_hi:[0,1]
	v_pk_mul_f32 v[46:47], v[202:203], v[46:47] op_sel_hi:[0,1]
	v_pk_mul_f32 v[40:41], v[202:203], v[40:41] op_sel_hi:[0,1]
	v_pk_mul_f32 v[42:43], v[202:203], v[42:43] op_sel_hi:[0,1]
	v_pk_mul_f32 v[44:45], v[176:177], v[44:45]
	v_pk_mul_f32 v[46:47], v[178:179], v[46:47]
	v_pk_mul_f32 v[40:41], v[180:181], v[40:41]
	v_pk_mul_f32 v[42:43], v[182:183], v[42:43]
	s_add_u32 s22, s98, s20
	s_addc_u32 s23, s99, 0
	global_store_dwordx4 v151, v[44:47], s[22:23]
	global_store_dwordx4 v151, v[40:43], s[22:23] offset:16
.Lf3q2_st_1:
	s_bitcmp1_b32 s19, 2
	s_cbranch_scc0 .Lf3q2_st_2
	s_add_i32 s87, s21, 160
	s_mul_hi_u32 s89, s87, 0x7e07e07f
	s_lshr_b32 s89, s89, 11
	s_mul_i32 vcc_lo, s89, 0x1040
	s_sub_i32 vcc_lo, s87, vcc_lo
	s_add_i32 vcc_lo, vcc_lo, -16
	s_lshl_b32 s89, s89, 12
	s_add_i32 s89, s89, vcc_lo
	s_cmp_lt_u32 vcc_lo, 0x1000
	s_cselect_b32 vcc_hi, 1, 0
	s_sub_i32 vcc_lo, s87, 0x4100
	s_cmp_ge_u32 s94, 65
	s_cselect_b32 s89, vcc_lo, s89
	s_cselect_b32 vcc_hi, 1, vcc_hi
	s_cmp_lg_u32 vcc_hi, 0
	s_cselect_b32 s89, s89, 0
	s_lshl_b32 s20, s89, 12
	v_pk_mul_f32 v[28:29], v[204:205], v[28:29] op_sel_hi:[0,1]
	v_pk_mul_f32 v[30:31], v[204:205], v[30:31] op_sel_hi:[0,1]
	v_pk_mul_f32 v[24:25], v[204:205], v[24:25] op_sel_hi:[0,1]
	v_pk_mul_f32 v[26:27], v[204:205], v[26:27] op_sel_hi:[0,1]
	v_pk_mul_f32 v[28:29], v[176:177], v[28:29]
	v_pk_mul_f32 v[30:31], v[178:179], v[30:31]
	v_pk_mul_f32 v[24:25], v[180:181], v[24:25]
	v_pk_mul_f32 v[26:27], v[182:183], v[26:27]
	s_add_u32 s22, s98, s20
	s_addc_u32 s23, s99, 0
	global_store_dwordx4 v151, v[28:31], s[22:23]
	global_store_dwordx4 v151, v[24:27], s[22:23] offset:16
.Lf3q2_st_2:
	s_bitcmp1_b32 s19, 3
	s_cbranch_scc0 .Lf3q2_st_3
	s_add_i32 s87, s21, 176
	s_mul_hi_u32 s89, s87, 0x7e07e07f
	s_lshr_b32 s89, s89, 11
	s_mul_i32 vcc_lo, s89, 0x1040
	s_sub_i32 vcc_lo, s87, vcc_lo
	s_add_i32 vcc_lo, vcc_lo, -16
	s_lshl_b32 s89, s89, 12
	s_add_i32 s89, s89, vcc_lo
	s_cmp_lt_u32 vcc_lo, 0x1000
	s_cselect_b32 vcc_hi, 1, 0
	s_sub_i32 vcc_lo, s87, 0x4100
	s_cmp_ge_u32 s94, 65
	s_cselect_b32 s89, vcc_lo, s89
	s_cselect_b32 vcc_hi, 1, vcc_hi
	s_cmp_lg_u32 vcc_hi, 0
	s_cselect_b32 s89, s89, 0
	s_lshl_b32 s20, s89, 12
	v_pk_mul_f32 v[12:13], v[206:207], v[12:13] op_sel_hi:[0,1]
	v_pk_mul_f32 v[14:15], v[206:207], v[14:15] op_sel_hi:[0,1]
	v_pk_mul_f32 v[8:9], v[206:207], v[8:9] op_sel_hi:[0,1]
	v_pk_mul_f32 v[10:11], v[206:207], v[10:11] op_sel_hi:[0,1]
	v_pk_mul_f32 v[12:13], v[176:177], v[12:13]
	v_pk_mul_f32 v[14:15], v[178:179], v[14:15]
	v_pk_mul_f32 v[8:9], v[180:181], v[8:9]
	v_pk_mul_f32 v[10:11], v[182:183], v[10:11]
	s_add_u32 s22, s98, s20
	s_addc_u32 s23, s99, 0
	global_store_dwordx4 v151, v[12:15], s[22:23]
	global_store_dwordx4 v151, v[8:11], s[22:23] offset:16

;     DI void operator()(const f32x4 (&acc)[2][2][4][2], const pg8::Unit& u, int wr, int wc, int fr, int fq) const {
;     ...
;                 const int R = u.pm * 256 + ai * 128 + wr * 64 + m * 16 + fr;
;                 const float* xs = nullptr; float* yd = nullptr;
;                 if (R < ROWS_P) { const int b = R / LPAD, t = R - b * LPAD; if (t >= NMETA && t < LP) { const size_t idx = ((size_t)b * SEQ + t - NMETA) * DM; xs = p.x_prompt + idx; yd = p.out + O_YP + idx; } }
;                 else { const size_t idx = (size_t)(R - ROWS_P) * DM; xs = p.x_sample + idx; yd = p.out + O_YS + idx; }
;                 float ss = 0.f;
;                 if (xs) {
; #pragma unroll
;                     for (int bj = 0; bj < 2; ++bj) {
;                         const int n = colt + bj * 128 + wc * 32 + 8 * fq;
;                         const f32x4 x0 = *(const f32x4*)(xs + n), x1 = *(const f32x4*)(xs + n + 4);
;                         const f32x4 h0 = x0 + acc[ai][bj][m][0], h1 = x1 + acc[ai][bj][m][1];
;                         *(f32x4*)(yd + n) = h0; *(f32x4*)(yd + n + 4) = h1;
;                         ss += h0[0] * h0[0] + h0[1] * h0[1] + h0[2] * h0[2] + h0[3] * h0[3] + h1[0] * h1[0] + h1[1] * h1[1] + h1[2] * h1[2] + h1[3] * h1[3];
;                     }
;                 }
;                 ss += __shfl_xor(ss, 16); ss += __shfl_xor(ss, 32);
;                 if (xs && fq == 0) atomicAdd(p.rowss + R, ss);
.Lp3q_v3:
	s_add_i32 s87, s21, 128
	s_mul_hi_u32 s89, s87, 0x7e07e07f
	s_lshr_b32 s89, s89, 11
	s_mul_i32 vcc_lo, s89, 0x1040
	s_sub_i32 vcc_lo, s87, vcc_lo
	s_add_i32 vcc_lo, vcc_lo, -16
	s_lshl_b32 s89, s89, 12
	s_add_i32 s89, s89, vcc_lo
	s_cmp_lt_u32 vcc_lo, 0x1000
	s_cselect_b32 vcc_hi, 1, 0
	s_sub_i32 vcc_lo, s87, 0x4100
	s_cmp_ge_u32 s94, 65
	s_cselect_b32 s89, vcc_lo, s89
	s_cselect_b32 vcc_hi, 1, vcc_hi
	s_cmp_lg_u32 vcc_hi, 0
	s_cselect_b32 s89, s89, 0
	s_lshl_b32 s20, s89, 12
	s_lshl_b32 vcc_hi, vcc_hi, 0
	s_or_b32 s19, s19, vcc_hi
	s_add_u32 s22, s96, s20
	s_addc_u32 s23, s97, 0
	global_load_dwordx4 v[176:179], v151, s[22:23] offset:512
	global_load_dwordx4 v[180:183], v151, s[22:23] offset:528
	s_add_i32 s87, s21, 144
	s_mul_hi_u32 s89, s87, 0x7e07e07f
	s_lshr_b32 s89, s89, 11
	s_mul_i32 vcc_lo, s89, 0x1040
	s_sub_i32 vcc_lo, s87, vcc_lo
	s_add_i32 vcc_lo, vcc_lo, -16
	s_lshl_b32 s89, s89, 12
	s_add_i32 s89, s89, vcc_lo
	s_cmp_lt_u32 vcc_lo, 0x1000
	s_cselect_b32 vcc_hi, 1, 0
	s_sub_i32 vcc_lo, s87, 0x4100
	s_cmp_ge_u32 s94, 65
	s_cselect_b32 s89, vcc_lo, s89
	s_cselect_b32 vcc_hi, 1, vcc_hi
	s_cmp_lg_u32 vcc_hi, 0
	s_cselect_b32 s89, s89, 0
	s_lshl_b32 s42, s89, 12
	s_lshl_b32 vcc_hi, vcc_hi, 1
	s_or_b32 s19, s19, vcc_hi
	s_add_u32 s22, s96, s42
	s_addc_u32 s23, s97, 0
	global_load_dwordx4 v[184:187], v151, s[22:23] offset:512
	global_load_dwordx4 v[188:191], v151, s[22:23] offset:528
	s_add_i32 s87, s21, 160
	s_mul_hi_u32 s89, s87, 0x7e07e07f
	s_lshr_b32 s89, s89, 11
	s_mul_i32 vcc_lo, s89, 0x1040
	s_sub_i32 vcc_lo, s87, vcc_lo
	s_add_i32 vcc_lo, vcc_lo, -16
	s_lshl_b32 s89, s89, 12
	s_add_i32 s89, s89, vcc_lo
	s_cmp_lt_u32 vcc_lo, 0x1000
	s_cselect_b32 vcc_hi, 1, 0
	s_sub_i32 vcc_lo, s87, 0x4100
	s_cmp_ge_u32 s94, 65
	s_cselect_b32 s89, vcc_lo, s89
	s_cselect_b32 vcc_hi, 1, vcc_hi
	s_cmp_lg_u32 vcc_hi, 0
	s_cselect_b32 s89, s89, 0
	s_lshl_b32 s43, s89, 12
	s_lshl_b32 vcc_hi, vcc_hi, 2
	s_or_b32 s19, s19, vcc_hi
	s_add_u32 s22, s96, s43
	s_addc_u32 s23, s97, 0
	global_load_dwordx4 v[192:195], v151, s[22:23] offset:512
	global_load_dwordx4 v[196:199], v151, s[22:23] offset:528
	s_add_i32 s87, s21, 176
	s_mul_hi_u32 s89, s87, 0x7e07e07f
	s_lshr_b32 s89, s89, 11
	s_mul_i32 vcc_lo, s89, 0x1040
	s_sub_i32 vcc_lo, s87, vcc_lo
	s_add_i32 vcc_lo, vcc_lo, -16
	s_lshl_b32 s89, s89, 12
	s_add_i32 s89, s89, vcc_lo
	s_cmp_lt_u32 vcc_lo, 0x1000
	s_cselect_b32 vcc_hi, 1, 0
	s_sub_i32 vcc_lo, s87, 0x4100
	s_cmp_ge_u32 s94, 65
	s_cselect_b32 s89, vcc_lo, s89
	s_cselect_b32 vcc_hi, 1, vcc_hi
	s_cmp_lg_u32 vcc_hi, 0
	s_cselect_b32 s89, s89, 0
	s_lshl_b32 s95, s89, 12
	s_lshl_b32 vcc_hi, vcc_hi, 3
	s_or_b32 s19, s19, vcc_hi
	s_add_u32 s22, s96, s95
	s_addc_u32 s23, s97, 0
	global_load_dwordx4 v[200:203], v151, s[22:23] offset:512
	global_load_dwordx4 v[204:207], v151, s[22:23] offset:528
	s_waitcnt vmcnt(0)
	v_pk_add_f32 v[52:53], v[52:53], v[176:177]
	v_pk_add_f32 v[54:55], v[54:55], v[178:179]
	v_pk_add_f32 v[48:49], v[48:49], v[180:181]
	v_pk_add_f32 v[50:51], v[50:51], v[182:183]
	v_pk_mul_f32 v[172:173], v[52:53], v[52:53]
	v_pk_fma_f32 v[172:173], v[54:55], v[54:55], v[172:173]
	v_pk_fma_f32 v[172:173], v[48:49], v[48:49], v[172:173]
	v_pk_fma_f32 v[172:173], v[50:51], v[50:51], v[172:173]
	s_nop 0
	v_add_f32_e32 v168, v172, v173
	v_pk_add_f32 v[36:37], v[36:37], v[184:185]
	v_pk_add_f32 v[38:39], v[38:39], v[186:187]
	v_pk_add_f32 v[32:33], v[32:33], v[188:189]
	v_pk_add_f32 v[34:35], v[34:35], v[190:191]
	v_pk_mul_f32 v[172:173], v[36:37], v[36:37]
	v_pk_fma_f32 v[172:173], v[38:39], v[38:39], v[172:173]
	v_pk_fma_f32 v[172:173], v[32:33], v[32:33], v[172:173]
	v_pk_fma_f32 v[172:173], v[34:35], v[34:35], v[172:173]
	s_nop 0
	v_add_f32_e32 v169, v172, v173
	v_pk_add_f32 v[20:21], v[20:21], v[192:193]
	v_pk_add_f32 v[22:23], v[22:23], v[194:195]
	v_pk_add_f32 v[16:17], v[16:17], v[196:197]
	v_pk_add_f32 v[18:19], v[18:19], v[198:199]
	v_pk_mul_f32 v[172:173], v[20:21], v[20:21]
	v_pk_fma_f32 v[172:173], v[22:23], v[22:23], v[172:173]
	v_pk_fma_f32 v[172:173], v[16:17], v[16:17], v[172:173]
	v_pk_fma_f32 v[172:173], v[18:19], v[18:19], v[172:173]
	s_nop 0
	v_add_f32_e32 v170, v172, v173
	v_pk_add_f32 v[4:5], v[4:5], v[200:201]
	v_pk_add_f32 v[6:7], v[6:7], v[202:203]
	v_pk_add_f32 v[0:1], v[0:1], v[204:205]
	v_pk_add_f32 v[2:3], v[2:3], v[206:207]
	v_pk_mul_f32 v[172:173], v[4:5], v[4:5]
	v_pk_fma_f32 v[172:173], v[6:7], v[6:7], v[172:173]
	v_pk_fma_f32 v[172:173], v[0:1], v[0:1], v[172:173]
	v_pk_fma_f32 v[172:173], v[2:3], v[2:3], v[172:173]
	s_nop 0
	v_add_f32_e32 v171, v172, v173
	ds_bpermute_b32 v155, v153, v168
	ds_bpermute_b32 v156, v153, v169
	ds_bpermute_b32 v157, v153, v170
	ds_bpermute_b32 v132, v153, v171
	s_waitcnt lgkmcnt(0)
	v_add_f32_e32 v168, v168, v155
	v_add_f32_e32 v169, v169, v156
	v_add_f32_e32 v170, v170, v157
	v_add_f32_e32 v171, v171, v132
	ds_bpermute_b32 v155, v154, v168
	ds_bpermute_b32 v156, v154, v169
	ds_bpermute_b32 v157, v154, v170
	ds_bpermute_b32 v132, v154, v171
	s_waitcnt lgkmcnt(0)
	v_add_f32_e32 v168, v168, v155
	v_add_f32_e32 v169, v169, v156
	v_add_f32_e32 v170, v170, v157
	v_add_f32_e32 v171, v171, v132
	s_mov_b64 exec, s[36:37]
	s_bitcmp1_b32 s19, 0
	s_cbranch_scc0 .Lf3q3_at_q_0
	global_atomic_add_f32 v152, v168, s[60:61] offset:512

;     DI void operator()(const f32x4 (&acc)[2][2][4][2], const pg8::Unit& u, int wr, int wc, int fr, int fq) const {
;     ...
;                 ss += __shfl_xor(ss, 16); ss += __shfl_xor(ss, 32);
;                 if (xs && fq == 0) atomicAdd(p.rowss + R, ss);
; __global__ void __launch_bounds__(512, 2) hymba_mega(Params p) {
;     ...
;             const float rstd = 1.0f / sqrtf(rs * (1.0f / 1024.0f) + EPS);
; #pragma unroll
;             for (int i = 0; i < 4; ++i) *(f32x4*)(yd + i * 256 + lane * 4) = v[i] * rstd * gq[i];
.Lf3q3_go_q:
	s_or_b64 exec, exec, vcc
	s_barrier
	s_mov_b64 exec, s[36:37]
	global_atomic_add_f32 v200, v152, v209, s[60:61] offset:512 sc0
	global_atomic_add_f32 v202, v152, v209, s[60:61] offset:576 sc0
	global_atomic_add_f32 v204, v152, v209, s[60:61] offset:640 sc0
	global_atomic_add_f32 v206, v152, v209, s[60:61] offset:704 sc0
	s_mov_b64 exec, -1
	s_waitcnt vmcnt(0)
	ds_bpermute_b32 v200, v208, v200
	ds_bpermute_b32 v202, v208, v202
	ds_bpermute_b32 v204, v208, v204
	ds_bpermute_b32 v206, v208, v206
	s_waitcnt lgkmcnt(0)
	v_fmamk_f32 v213, v200, 0x3a800000, v218
	v_mul_f32_e32 v214, 0x4f800000, v213
	v_cmp_gt_f32_e32 vcc, 0xf800000, v213
	s_nop 1
	v_cndmask_b32_e32 v213, v213, v214, vcc
	v_sqrt_f32_e32 v214, v213
	s_nop 0
	v_add_u32_e32 v215, -1, v214
	v_fma_f32 v217, -v215, v214, v213
	v_add_u32_e32 v216, 1, v214
	v_cmp_ge_f32_e64 s[22:23], 0, v217
	s_nop 1
	v_cndmask_b32_e64 v215, v214, v215, s[22:23]
	v_fma_f32 v214, -v216, v214, v213
	v_cmp_lt_f32_e64 s[22:23], 0, v214
	s_nop 1
	v_cndmask_b32_e64 v214, v215, v216, s[22:23]
	v_mul_f32_e32 v215, 0x37800000, v214
	v_cndmask_b32_e32 v214, v214, v215, vcc
	v_cmp_class_f32_e32 vcc, v213, v219
	s_nop 1
	v_cndmask_b32_e32 v213, v214, v213, vcc
	v_div_scale_f32 v214, s[22:23], v213, v213, 1.0
	v_rcp_f32_e32 v215, v214
	s_nop 0
	v_fma_f32 v216, -v214, v215, 1.0
	v_fmac_f32_e32 v215, v216, v215
	v_div_scale_f32 v216, vcc, 1.0, v213, 1.0
	v_mul_f32_e32 v217, v216, v215
	v_fma_f32 v200, -v214, v217, v216
	v_fmac_f32_e32 v217, v200, v215
	v_fma_f32 v214, -v214, v217, v216
	s_nop 0
	v_div_fmas_f32 v214, v214, v215, v217
	v_div_fixup_f32 v200, v214, v213, 1.0
	v_fmamk_f32 v213, v202, 0x3a800000, v218
	v_mul_f32_e32 v214, 0x4f800000, v213
	v_cmp_gt_f32_e32 vcc, 0xf800000, v213
	s_nop 1
	v_cndmask_b32_e32 v213, v213, v214, vcc
	v_sqrt_f32_e32 v214, v213
	s_nop 0
	v_add_u32_e32 v215, -1, v214
	v_fma_f32 v217, -v215, v214, v213
	v_add_u32_e32 v216, 1, v214
	v_cmp_ge_f32_e64 s[22:23], 0, v217
	s_nop 1
	v_cndmask_b32_e64 v215, v214, v215, s[22:23]
	v_fma_f32 v214, -v216, v214, v213
	v_cmp_lt_f32_e64 s[22:23], 0, v214
	s_nop 1
	v_cndmask_b32_e64 v214, v215, v216, s[22:23]
	v_mul_f32_e32 v215, 0x37800000, v214
	v_cndmask_b32_e32 v214, v214, v215, vcc
	v_cmp_class_f32_e32 vcc, v213, v219
	s_nop 1
	v_cndmask_b32_e32 v213, v214, v213, vcc
	v_div_scale_f32 v214, s[22:23], v213, v213, 1.0
	v_rcp_f32_e32 v215, v214
	s_nop 0
	v_fma_f32 v216, -v214, v215, 1.0
	v_fmac_f32_e32 v215, v216, v215
	v_div_scale_f32 v216, vcc, 1.0, v213, 1.0
	v_mul_f32_e32 v217, v216, v215
	v_fma_f32 v202, -v214, v217, v216
	v_fmac_f32_e32 v217, v202, v215
	v_fma_f32 v214, -v214, v217, v216
	s_nop 0
	v_div_fmas_f32 v214, v214, v215, v217
	v_div_fixup_f32 v202, v214, v213, 1.0
	v_fmamk_f32 v213, v204, 0x3a800000, v218
	v_mul_f32_e32 v214, 0x4f800000, v213
	v_cmp_gt_f32_e32 vcc, 0xf800000, v213
	s_nop 1
	v_cndmask_b32_e32 v213, v213, v214, vcc
	v_sqrt_f32_e32 v214, v213
	s_nop 0
	v_add_u32_e32 v215, -1, v214
	v_fma_f32 v217, -v215, v214, v213
	v_add_u32_e32 v216, 1, v214
	v_cmp_ge_f32_e64 s[22:23], 0, v217
	s_nop 1
	v_cndmask_b32_e64 v215, v214, v215, s[22:23]
	v_fma_f32 v214, -v216, v214, v213
	v_cmp_lt_f32_e64 s[22:23], 0, v214
	s_nop 1
	v_cndmask_b32_e64 v214, v215, v216, s[22:23]
	v_mul_f32_e32 v215, 0x37800000, v214
	v_cndmask_b32_e32 v214, v214, v215, vcc
	v_cmp_class_f32_e32 vcc, v213, v219
	s_nop 1
	v_cndmask_b32_e32 v213, v214, v213, vcc
	v_div_scale_f32 v214, s[22:23], v213, v213, 1.0
	v_rcp_f32_e32 v215, v214
	s_nop 0
	v_fma_f32 v216, -v214, v215, 1.0
	v_fmac_f32_e32 v215, v216, v215
	v_div_scale_f32 v216, vcc, 1.0, v213, 1.0
	v_mul_f32_e32 v217, v216, v215
	v_fma_f32 v204, -v214, v217, v216
	v_fmac_f32_e32 v217, v204, v215
	v_fma_f32 v214, -v214, v217, v216
	s_nop 0
	v_div_fmas_f32 v214, v214, v215, v217
	v_div_fixup_f32 v204, v214, v213, 1.0
	v_fmamk_f32 v213, v206, 0x3a800000, v218
	v_mul_f32_e32 v214, 0x4f800000, v213
	v_cmp_gt_f32_e32 vcc, 0xf800000, v213
	s_nop 1
	v_cndmask_b32_e32 v213, v213, v214, vcc
	v_sqrt_f32_e32 v214, v213
	s_nop 0
	v_add_u32_e32 v215, -1, v214
	v_fma_f32 v217, -v215, v214, v213
	v_add_u32_e32 v216, 1, v214
	v_cmp_ge_f32_e64 s[22:23], 0, v217
	s_nop 1
	v_cndmask_b32_e64 v215, v214, v215, s[22:23]
	v_fma_f32 v214, -v216, v214, v213
	v_cmp_lt_f32_e64 s[22:23], 0, v214
	s_nop 1
	v_cndmask_b32_e64 v214, v215, v216, s[22:23]
	v_mul_f32_e32 v215, 0x37800000, v214
	v_cndmask_b32_e32 v214, v214, v215, vcc
	v_cmp_class_f32_e32 vcc, v213, v219
	s_nop 1
	v_cndmask_b32_e32 v213, v214, v213, vcc
	v_div_scale_f32 v214, s[22:23], v213, v213, 1.0
	v_rcp_f32_e32 v215, v214
	s_nop 0
	v_fma_f32 v216, -v214, v215, 1.0
	v_fmac_f32_e32 v215, v216, v215
	v_div_scale_f32 v216, vcc, 1.0, v213, 1.0
	v_mul_f32_e32 v217, v216, v215
	v_fma_f32 v206, -v214, v217, v216
	v_fmac_f32_e32 v217, v206, v215
	v_fma_f32 v214, -v214, v217, v216
	s_nop 0
	v_div_fmas_f32 v214, v214, v215, v217
	v_div_fixup_f32 v206, v214, v213, 1.0
	s_bitcmp1_b32 s19, 0
	s_cbranch_scc0 .Lf3q3_st_0
	s_add_i32 s87, s21, 128
	s_mul_hi_u32 s89, s87, 0x7e07e07f
	s_lshr_b32 s89, s89, 11
	s_mul_i32 vcc_lo, s89, 0x1040
	s_sub_i32 vcc_lo, s87, vcc_lo
	s_add_i32 vcc_lo, vcc_lo, -16
	s_lshl_b32 s89, s89, 12
	s_add_i32 s89, s89, vcc_lo
	s_cmp_lt_u32 vcc_lo, 0x1000
	s_cselect_b32 vcc_hi, 1, 0
	s_sub_i32 vcc_lo, s87, 0x4100
	s_cmp_ge_u32 s94, 65
	s_cselect_b32 s89, vcc_lo, s89
	s_cselect_b32 vcc_hi, 1, vcc_hi
	s_cmp_lg_u32 vcc_hi, 0
	s_cselect_b32 s89, s89, 0
	s_lshl_b32 s20, s89, 12
	v_pk_mul_f32 v[52:53], v[200:201], v[52:53] op_sel_hi:[0,1]
	v_pk_mul_f32 v[54:55], v[200:201], v[54:55] op_sel_hi:[0,1]
	v_pk_mul_f32 v[48:49], v[200:201], v[48:49] op_sel_hi:[0,1]
	v_pk_mul_f32 v[50:51], v[200:201], v[50:51] op_sel_hi:[0,1]
	v_pk_mul_f32 v[52:53], v[184:185], v[52:53]
	v_pk_mul_f32 v[54:55], v[186:187], v[54:55]
	v_pk_mul_f32 v[48:49], v[188:189], v[48:49]
	v_pk_mul_f32 v[50:51], v[190:191], v[50:51]
	s_add_u32 s22, s98, s20
	s_addc_u32 s23, s99, 0
	global_store_dwordx4 v151, v[52:55], s[22:23] offset:512
	global_store_dwordx4 v151, v[48:51], s[22:23] offset:528
;     DI void operator()(const f32x4 (&acc)[2][2][4][2], const pg8::Unit& u, int wr, int wc, int fr, int fq) const {
;     ...
;                 const int R = u.pm * 256 + ai * 128 + wr * 64 + m * 16 + fr;
;                 const float* xs = nullptr; float* yd = nullptr;
;                 if (R < ROWS_P) { const int b = R / LPAD, t = R - b * LPAD; if (t >= NMETA && t < LP) { const size_t idx = ((size_t)b * SEQ + t - NMETA) * DM; xs = p.x_prompt + idx; yd = p.out + O_YP + idx; } }
;                 else { const size_t idx = (size_t)(R - ROWS_P) * DM; xs = p.x_sample + idx; yd = p.out + O_YS + idx; }
; __global__ void __launch_bounds__(512, 2) hymba_mega(Params p) {
;     ...
;             const float rstd = 1.0f / sqrtf(rs * (1.0f / 1024.0f) + EPS);
; #pragma unroll
;             for (int i = 0; i < 4; ++i) *(f32x4*)(yd + i * 256 + lane * 4) = v[i] * rstd * gq[i];
.Lf3q3_st_0:
	s_bitcmp1_b32 s19, 1
	s_cbranch_scc0 .Lf3q3_st_1
	s_add_i32 s87, s21, 144
	s_mul_hi_u32 s89, s87, 0x7e07e07f
	s_lshr_b32 s89, s89, 11
	s_mul_i32 vcc_lo, s89, 0x1040
	s_sub_i32 vcc_lo, s87, vcc_lo
	s_add_i32 vcc_lo, vcc_lo, -16
	s_lshl_b32 s89, s89, 12
	s_add_i32 s89, s89, vcc_lo
	s_cmp_lt_u32 vcc_lo, 0x1000
	s_cselect_b32 vcc_hi, 1, 0
	s_sub_i32 vcc_lo, s87, 0x4100
	s_cmp_ge_u32 s94, 65
	s_cselect_b32 s89, vcc_lo, s89
	s_cselect_b32 vcc_hi, 1, vcc_hi
	s_cmp_lg_u32 vcc_hi, 0
	s_cselect_b32 s89, s89, 0
	s_lshl_b32 s20, s89, 12
	v_pk_mul_f32 v[36:37], v[202:203], v[36:37] op_sel_hi:[0,1]
	v_pk_mul_f32 v[38:39], v[202:203], v[38:39] op_sel_hi:[0,1]
	v_pk_mul_f32 v[32:33], v[202:203], v[32:33] op_sel_hi:[0,1]
	v_pk_mul_f32 v[34:35], v[202:203], v[34:35] op_sel_hi:[0,1]
	v_pk_mul_f32 v[36:37], v[184:185], v[36:37]
	v_pk_mul_f32 v[38:39], v[186:187], v[38:39]
	v_pk_mul_f32 v[32:33], v[188:189], v[32:33]
	v_pk_mul_f32 v[34:35], v[190:191], v[34:35]
	s_add_u32 s22, s98, s20
	s_addc_u32 s23, s99, 0
	global_store_dwordx4 v151, v[36:39], s[22:23] offset:512
	global_store_dwordx4 v151, v[32:35], s[22:23] offset:528
.Lf3q3_st_1:
	s_bitcmp1_b32 s19, 2
	s_cbranch_scc0 .Lf3q3_st_2
	s_add_i32 s87, s21, 160
	s_mul_hi_u32 s89, s87, 0x7e07e07f
	s_lshr_b32 s89, s89, 11
	s_mul_i32 vcc_lo, s89, 0x1040
	s_sub_i32 vcc_lo, s87, vcc_lo
	s_add_i32 vcc_lo, vcc_lo, -16
	s_lshl_b32 s89, s89, 12
	s_add_i32 s89, s89, vcc_lo
	s_cmp_lt_u32 vcc_lo, 0x1000
	s_cselect_b32 vcc_hi, 1, 0
	s_sub_i32 vcc_lo, s87, 0x4100
	s_cmp_ge_u32 s94, 65
	s_cselect_b32 s89, vcc_lo, s89
	s_cselect_b32 vcc_hi, 1, vcc_hi
	s_cmp_lg_u32 vcc_hi, 0
	s_cselect_b32 s89, s89, 0
	s_lshl_b32 s20, s89, 12
	v_pk_mul_f32 v[20:21], v[204:205], v[20:21] op_sel_hi:[0,1]
	v_pk_mul_f32 v[22:23], v[204:205], v[22:23] op_sel_hi:[0,1]
	v_pk_mul_f32 v[16:17], v[204:205], v[16:17] op_sel_hi:[0,1]
	v_pk_mul_f32 v[18:19], v[204:205], v[18:19] op_sel_hi:[0,1]
	v_pk_mul_f32 v[20:21], v[184:185], v[20:21]
	v_pk_mul_f32 v[22:23], v[186:187], v[22:23]
	v_pk_mul_f32 v[16:17], v[188:189], v[16:17]
	v_pk_mul_f32 v[18:19], v[190:191], v[18:19]
	s_add_u32 s22, s98, s20
	s_addc_u32 s23, s99, 0
	global_store_dwordx4 v151, v[20:23], s[22:23] offset:512
	global_store_dwordx4 v151, v[16:19], s[22:23] offset:528
.Lf3q3_st_2:
	s_bitcmp1_b32 s19, 3
	s_cbranch_scc0 .Lf3q3_st_3
	s_add_i32 s87, s21, 176
	s_mul_hi_u32 s89, s87, 0x7e07e07f
	s_lshr_b32 s89, s89, 11
	s_mul_i32 vcc_lo, s89, 0x1040
	s_sub_i32 vcc_lo, s87, vcc_lo
	s_add_i32 vcc_lo, vcc_lo, -16
	s_lshl_b32 s89, s89, 12
	s_add_i32 s89, s89, vcc_lo
	s_cmp_lt_u32 vcc_lo, 0x1000
	s_cselect_b32 vcc_hi, 1, 0
	s_sub_i32 vcc_lo, s87, 0x4100
	s_cmp_ge_u32 s94, 65
	s_cselect_b32 s89, vcc_lo, s89
	s_cselect_b32 vcc_hi, 1, vcc_hi
	s_cmp_lg_u32 vcc_hi, 0
	s_cselect_b32 s89, s89, 0
	s_lshl_b32 s20, s89, 12
	v_pk_mul_f32 v[4:5], v[206:207], v[4:5] op_sel_hi:[0,1]
	v_pk_mul_f32 v[6:7], v[206:207], v[6:7] op_sel_hi:[0,1]
	v_pk_mul_f32 v[0:1], v[206:207], v[0:1] op_sel_hi:[0,1]
	v_pk_mul_f32 v[2:3], v[206:207], v[2:3] op_sel_hi:[0,1]
	v_pk_mul_f32 v[4:5], v[184:185], v[4:5]
	v_pk_mul_f32 v[6:7], v[186:187], v[6:7]
	v_pk_mul_f32 v[0:1], v[188:189], v[0:1]
	v_pk_mul_f32 v[2:3], v[190:191], v[2:3]
	s_add_u32 s22, s98, s20
	s_addc_u32 s23, s99, 0
	global_store_dwordx4 v151, v[4:7], s[22:23] offset:512
	global_store_dwordx4 v151, v[0:3], s[22:23] offset:528
.Lf3q3_st_3:
	s_branch .Lp3q_epi_done
.LBB0_703:
	s_waitcnt vmcnt(0)
	v_readlane_b32 s10, v246, 23
	v_readlane_b32 s12, v246, 21
	v_readlane_b32 s14, v246, 19
	v_readlane_b32 s16, v246, 17
	v_readlane_b32 s18, v246, 15
	v_readlane_b32 s20, v246, 13
	v_readlane_b32 s22, v246, 11
	v_readlane_b32 s24, v246, 9
	v_readlane_b32 s86, v246, 7
	v_readlane_b32 s88, v246, 5
	v_readlane_b32 s90, v246, 3
	v_readlane_b32 s11, v246, 24
	v_readlane_b32 s13, v246, 22
	v_readlane_b32 s15, v246, 20
	v_readlane_b32 s17, v246, 18
	v_readlane_b32 s19, v246, 16
	v_readlane_b32 s21, v246, 14
	v_readlane_b32 s23, v246, 12
	v_readlane_b32 s25, v246, 10
	v_readlane_b32 s87, v246, 8
	v_readlane_b32 s89, v246, 6
	v_readlane_b32 s91, v246, 4
	s_barrier
.LBB0_704:
	s_endpgm
	s_waitcnt vmcnt(0)
	s_waitcnt vmcnt(0) lgkmcnt(0)
	s_barrier
	s_and_saveexec_b64 s[2:3], s[40:41]
	s_cbranch_execz .LBB0_752
	s_mov_b32 s0, 0x20000
	s_addk_i32 s0, 0x100
	v_mov_b32_e32 v0, s0
	s_mov_b32 s0, 0x20004
	s_waitcnt vmcnt(0) expcnt(0) lgkmcnt(0)
	ds_read_b32 v2, v0
	s_addk_i32 s0, 0x100
	v_mov_b32_e32 v0, s0
	ds_read_b32 v0, v0
	s_waitcnt lgkmcnt(1)
	v_cmp_ne_u32_e32 vcc, 0, v2
	s_cbranch_vccnz .LBB0_720
	s_load_dwordx2 s[4:5], s[44:45], 0x4
	s_mov_b32 s0, 1
	v_mov_b32_e32 v16, 0
	s_waitcnt lgkmcnt(0)
	s_mul_i32 s1, s4, s33
	s_mul_i32 s1, s1, s5
	s_branch .LBB0_708
